# residual-stream f32 loads/stores in GEMM+residual epilogues: default cache policy instead of nt
# baseline (speedup 1.0000x reference)
; __device__ __forceinline__ u32x4 pack8(const f32x4 a, const f32x4 b) { u32x4 w; w.x = cvt_pk_bf16(a[0], a[1]); w.y = cvt_pk_bf16(a[2], a[3]); w.z = cvt_pk_bf16(b[0], b[1]); w.w = cvt_pk_bf16(b[2], b[3]); return w; }
; __device__ __forceinline__ void ss_add(ssq_t* p, float sq) { __hip_atomic_fetch_add(p, (ssq_t)(sq * 16777216.0f), __ATOMIC_RELAXED, __HIP_MEMORY_SCOPE_AGENT); }
; __device__ __forceinline__ float dot4(const f32x4 a) { return (a[0] * a[0] + a[1] * a[1]) + (a[2] * a[2] + a[3] * a[3]); }
;     __device__ __forceinline__ void operator()(const f32x4 (&acc)[2][2][4][2], const Unit& u, int wr, int wc, int fr, int fq) const {
;         const int row0 = u.pm * BM + wr * 64 + fr, col0 = u.pn * BM + wc * 32 + 8 * fq;
; #pragma unroll
;         for (int ai = 0; ai < 2; ++ai)
; #pragma unroll
;             for (int m = 0; m < 4; ++m) { const int row = row0 + ai * HALF + m * 16; const size_t off = (size_t)row * 2048 + col0; float sq = 0.f;
; #pragma unroll
;                 for (int bj = 0; bj < 2; ++bj) {
;                     const f32x4 x0 = __builtin_nontemporal_load((const f32x4*)(xin + off + bj * HALF)), x1 = __builtin_nontemporal_load((const f32x4*)(xin + off + bj * HALF + 4));
;                     const f32x4 v0 = x0 + acc[ai][bj][m][0] * alpha, v1 = x1 + acc[ai][bj][m][1] * alpha;
;                     __builtin_nontemporal_store(v0, (f32x4*)(xout + off + bj * HALF)); __builtin_nontemporal_store(v1, (f32x4*)(xout + off + bj * HALF + 4));
;                     if (WRITE_XB) *(u32x4*)(xb + off + bj * HALF) = pack8(v0, v1); sq += dot4(v0) + dot4(v1); }
;                 sq += __shfl_xor(sq, 16); sq += __shfl_xor(sq, 32);
;                 if (fq == 0) ss_add(ssout + row, sq); }
.LBB0_586:
	v_lshl_add_u32 v146, s36, 8, v148
	v_lshl_add_u32 v144, s37, 8, v150
	v_ashrrev_i32_e32 v147, 31, v146
	v_ashrrev_i32_e32 v145, 31, v144
	v_lshlrev_b64 v[156:157], 11, v[146:147]
	v_lshl_add_u64 v[164:165], v[156:157], 0, v[144:145]
	v_lshlrev_b64 v[166:167], 2, v[164:165]
	v_lshl_add_u64 v[168:169], s[52:53], 0, v[166:167]
	global_load_dwordx4 v[156:159], v[168:169], off
	global_load_dwordx4 v[160:163], v[168:169], off offset:16
	global_load_dwordx4 v[176:179], v[168:169], off offset:512
	global_load_dwordx4 v[180:183], v[168:169], off offset:528
	v_lshl_add_u64 v[170:171], v[164:165], 1, s[46:47]
	v_lshl_add_u64 v[172:173], s[28:29], 0, v[166:167]
	s_waitcnt vmcnt(2)
	v_pk_fma_f32 v[126:127], v[126:127], 0.5, v[158:159] op_sel_hi:[1,0,1]
	v_pk_fma_f32 v[124:125], v[124:125], 0.5, v[156:157] op_sel_hi:[1,0,1]
	v_pk_fma_f32 v[158:159], v[122:123], 0.5, v[162:163] op_sel_hi:[1,0,1]
	v_pk_fma_f32 v[156:157], v[120:121], 0.5, v[160:161] op_sel_hi:[1,0,1]
	v_cvt_pk_bf16_f32 v120, v124, v125
	v_cvt_pk_bf16_f32 v121, v126, v127
	v_cvt_pk_bf16_f32 v122, v156, v157
	v_cvt_pk_bf16_f32 v123, v158, v159
	global_store_dwordx4 v[172:173], v[124:127], off
	global_store_dwordx4 v[172:173], v[156:159], off offset:16
	global_store_dwordx4 v[170:171], v[120:123], off
	s_nop 1
	v_and_b32_e32 v121, 64, v154
	v_xor_b32_e32 v120, 16, v154
	v_add_u32_e32 v121, 64, v121
	v_xor_b32_e32 v122, 32, v154
	v_cmp_lt_i32_e32 vcc, v120, v121
	v_mul_f32_e32 v123, v127, v127
	v_mul_f32_e32 v127, v159, v159
	v_cndmask_b32_e32 v120, v154, v120, vcc
	v_cmp_lt_i32_e32 vcc, v122, v121
	v_fmac_f32_e32 v123, v126, v126
	v_fmac_f32_e32 v127, v158, v158
	v_cndmask_b32_e32 v121, v154, v122, vcc
	v_mul_f32_e32 v122, v125, v125
	v_mul_f32_e32 v125, v157, v157
	v_fmac_f32_e32 v122, v124, v124
	v_fmac_f32_e32 v125, v156, v156
	v_add_f32_e32 v122, v122, v123
	v_add_f32_e32 v123, v125, v127
	v_add_f32_e32 v126, v122, v123
	v_lshlrev_b32_e32 v120, 2, v120
	s_waitcnt vmcnt(4)
	v_pk_fma_f32 v[118:119], v[118:119], 0.5, v[178:179] op_sel_hi:[1,0,1]
	v_pk_fma_f32 v[116:117], v[116:117], 0.5, v[176:177] op_sel_hi:[1,0,1]
	s_waitcnt vmcnt(3)
	v_pk_fma_f32 v[124:125], v[114:115], 0.5, v[182:183] op_sel_hi:[1,0,1]
	v_pk_fma_f32 v[122:123], v[112:113], 0.5, v[180:181] op_sel_hi:[1,0,1]
	v_mul_f32_e32 v112, v117, v117
	v_mul_f32_e32 v113, v119, v119
	v_mul_f32_e32 v114, v123, v123
	v_mul_f32_e32 v115, v125, v125
	v_fmac_f32_e32 v112, v116, v116
	v_fmac_f32_e32 v113, v118, v118
	v_fmac_f32_e32 v114, v122, v122
	v_fmac_f32_e32 v115, v124, v124
	v_add_f32_e32 v112, v112, v113
	v_add_f32_e32 v113, v114, v115
	v_add_f32_e32 v112, v112, v113
	v_add_f32_e32 v112, v126, v112
	ds_bpermute_b32 v113, v120, v112
	v_lshlrev_b32_e32 v114, 2, v121
	global_store_dwordx4 v[172:173], v[116:119], off offset:512
	global_store_dwordx4 v[172:173], v[122:125], off offset:528
	s_waitcnt lgkmcnt(0)
	v_add_f32_e32 v112, v112, v113
	ds_bpermute_b32 v113, v114, v112
	v_cvt_pk_bf16_f32 v116, v116, v117
	v_cvt_pk_bf16_f32 v117, v118, v119
	v_cvt_pk_bf16_f32 v118, v122, v123
	v_cvt_pk_bf16_f32 v119, v124, v125
	global_store_dwordx4 v[170:171], v[116:119], off offset:256
	s_and_saveexec_b64 s[36:37], s[2:3]
	s_cbranch_execz .LBB0_588
	s_waitcnt lgkmcnt(0)
	v_add_f32_e32 v112, v112, v113
	v_mul_f32_e32 v112, 0x4b800000, v112
	v_trunc_f32_e32 v112, v112
	v_mul_f32_e32 v113, 0x2f800000, v112
	v_floor_f32_e32 v113, v113
	v_fmac_f32_e32 v112, 0xcf800000, v113
	v_cvt_u32_f32_e32 v112, v112
	v_cvt_u32_f32_e32 v113, v113
	v_lshl_add_u64 v[116:117], v[146:147], 3, s[18:19]
	global_atomic_add_x2 v[116:117], v[112:113], off
.LBB0_588:
	s_or_b64 exec, exec, s[36:37]
	v_or_b32_e32 v112, 16, v146
	s_waitcnt lgkmcnt(0)
	v_ashrrev_i32_e32 v113, 31, v112
	v_lshlrev_b64 v[116:117], 11, v[112:113]
	v_lshl_add_u64 v[126:127], v[116:117], 0, v[144:145]
	v_lshlrev_b64 v[156:157], 2, v[126:127]
	v_lshl_add_u64 v[158:159], s[52:53], 0, v[156:157]
	global_load_dwordx4 v[116:119], v[158:159], off
	global_load_dwordx4 v[122:125], v[158:159], off offset:16
	global_load_dwordx4 v[176:179], v[158:159], off offset:512
	global_load_dwordx4 v[180:183], v[158:159], off offset:528
	v_lshl_add_u64 v[126:127], v[126:127], 1, s[46:47]
	v_lshl_add_u64 v[156:157], s[28:29], 0, v[156:157]
	s_waitcnt vmcnt(3)
	v_pk_fma_f32 v[110:111], v[110:111], 0.5, v[118:119] op_sel_hi:[1,0,1]
	v_pk_fma_f32 v[108:109], v[108:109], 0.5, v[116:117] op_sel_hi:[1,0,1]
	s_waitcnt vmcnt(2)
	v_pk_fma_f32 v[106:107], v[106:107], 0.5, v[124:125] op_sel_hi:[1,0,1]
	v_pk_fma_f32 v[104:105], v[104:105], 0.5, v[122:123] op_sel_hi:[1,0,1]
	v_cvt_pk_bf16_f32 v116, v108, v109
	v_cvt_pk_bf16_f32 v117, v110, v111
	v_cvt_pk_bf16_f32 v118, v104, v105
	v_cvt_pk_bf16_f32 v119, v106, v107
	global_store_dwordx4 v[156:157], v[108:111], off
	global_store_dwordx4 v[156:157], v[104:107], off offset:16
	global_store_dwordx4 v[126:127], v[116:119], off
	s_nop 1
	v_mul_f32_e32 v109, v109, v109
	v_mul_f32_e32 v111, v111, v111
	v_mul_f32_e32 v105, v105, v105
	v_mul_f32_e32 v107, v107, v107
	v_fmac_f32_e32 v109, v108, v108
	v_fmac_f32_e32 v111, v110, v110
	v_fmac_f32_e32 v105, v104, v104
	v_fmac_f32_e32 v107, v106, v106
	v_add_f32_e32 v104, v109, v111
	v_add_f32_e32 v105, v105, v107
	v_add_f32_e32 v108, v104, v105
	s_waitcnt vmcnt(4)
	v_pk_fma_f32 v[102:103], v[102:103], 0.5, v[178:179] op_sel_hi:[1,0,1]
	v_pk_fma_f32 v[100:101], v[100:101], 0.5, v[176:177] op_sel_hi:[1,0,1]
	s_waitcnt vmcnt(3)
	v_pk_fma_f32 v[106:107], v[98:99], 0.5, v[182:183] op_sel_hi:[1,0,1]
	v_pk_fma_f32 v[104:105], v[96:97], 0.5, v[180:181] op_sel_hi:[1,0,1]
	v_mul_f32_e32 v96, v101, v101
	v_mul_f32_e32 v97, v103, v103
	v_mul_f32_e32 v98, v105, v105
	v_mul_f32_e32 v99, v107, v107
	v_fmac_f32_e32 v96, v100, v100
	v_fmac_f32_e32 v97, v102, v102
	v_fmac_f32_e32 v98, v104, v104
	v_fmac_f32_e32 v99, v106, v106
	v_add_f32_e32 v96, v96, v97
	v_add_f32_e32 v97, v98, v99
	v_add_f32_e32 v96, v96, v97
	v_add_f32_e32 v96, v108, v96
	ds_bpermute_b32 v97, v120, v96
	global_store_dwordx4 v[156:157], v[100:103], off offset:512
	global_store_dwordx4 v[156:157], v[104:107], off offset:528
	v_cvt_pk_bf16_f32 v98, v100, v101
	v_cvt_pk_bf16_f32 v99, v102, v103
	v_cvt_pk_bf16_f32 v100, v104, v105
	s_waitcnt lgkmcnt(0)
	v_add_f32_e32 v96, v96, v97
	ds_bpermute_b32 v97, v114, v96
	v_cvt_pk_bf16_f32 v101, v106, v107
	global_store_dwordx4 v[126:127], v[98:101], off offset:256
	s_and_saveexec_b64 s[36:37], s[2:3]
	s_cbranch_execz .LBB0_590
	s_waitcnt lgkmcnt(0)
	v_add_f32_e32 v96, v96, v97
	v_mul_f32_e32 v96, 0x4b800000, v96
	v_trunc_f32_e32 v96, v96
	v_mul_f32_e32 v97, 0x2f800000, v96
	v_floor_f32_e32 v97, v97
	v_fmac_f32_e32 v96, 0xcf800000, v97
	v_cvt_u32_f32_e32 v96, v96
	v_cvt_u32_f32_e32 v97, v97
	v_lshl_add_u64 v[98:99], v[112:113], 3, s[18:19]
	global_atomic_add_x2 v[98:99], v[96:97], off
; __device__ __forceinline__ u32x4 pack8(const f32x4 a, const f32x4 b) { u32x4 w; w.x = cvt_pk_bf16(a[0], a[1]); w.y = cvt_pk_bf16(a[2], a[3]); w.z = cvt_pk_bf16(b[0], b[1]); w.w = cvt_pk_bf16(b[2], b[3]); return w; }
; __device__ __forceinline__ void ss_add(ssq_t* p, float sq) { __hip_atomic_fetch_add(p, (ssq_t)(sq * 16777216.0f), __ATOMIC_RELAXED, __HIP_MEMORY_SCOPE_AGENT); }
; __device__ __forceinline__ float dot4(const f32x4 a) { return (a[0] * a[0] + a[1] * a[1]) + (a[2] * a[2] + a[3] * a[3]); }
;     __device__ __forceinline__ void operator()(const f32x4 (&acc)[2][2][4][2], const Unit& u, int wr, int wc, int fr, int fq) const {
;     ...
;         for (int ai = 0; ai < 2; ++ai)
; #pragma unroll
;             for (int m = 0; m < 4; ++m) { const int row = row0 + ai * HALF + m * 16; const size_t off = (size_t)row * 2048 + col0; float sq = 0.f;
; #pragma unroll
;                 for (int bj = 0; bj < 2; ++bj) {
;                     const f32x4 x0 = __builtin_nontemporal_load((const f32x4*)(xin + off + bj * HALF)), x1 = __builtin_nontemporal_load((const f32x4*)(xin + off + bj * HALF + 4));
;                     const f32x4 v0 = x0 + acc[ai][bj][m][0] * alpha, v1 = x1 + acc[ai][bj][m][1] * alpha;
;                     __builtin_nontemporal_store(v0, (f32x4*)(xout + off + bj * HALF)); __builtin_nontemporal_store(v1, (f32x4*)(xout + off + bj * HALF + 4));
;                     if (WRITE_XB) *(u32x4*)(xb + off + bj * HALF) = pack8(v0, v1); sq += dot4(v0) + dot4(v1); }
;                 sq += __shfl_xor(sq, 16); sq += __shfl_xor(sq, 32);
;                 if (fq == 0) ss_add(ssout + row, sq); }
.LBB0_590:
	s_or_b64 exec, exec, s[36:37]
	v_or_b32_e32 v96, 32, v146
	s_waitcnt lgkmcnt(0)
	v_ashrrev_i32_e32 v97, 31, v96
	v_lshlrev_b64 v[98:99], 11, v[96:97]
	v_lshl_add_u64 v[106:107], v[98:99], 0, v[144:145]
	v_lshlrev_b64 v[108:109], 2, v[106:107]
	v_lshl_add_u64 v[110:111], s[52:53], 0, v[108:109]
	global_load_dwordx4 v[98:101], v[110:111], off
	global_load_dwordx4 v[102:105], v[110:111], off offset:16
	global_load_dwordx4 v[176:179], v[110:111], off offset:512
	global_load_dwordx4 v[180:183], v[110:111], off offset:528
	v_lshl_add_u64 v[106:107], v[106:107], 1, s[46:47]
	v_lshl_add_u64 v[108:109], s[28:29], 0, v[108:109]
	s_waitcnt vmcnt(3)
	v_pk_fma_f32 v[94:95], v[94:95], 0.5, v[100:101] op_sel_hi:[1,0,1]
	v_pk_fma_f32 v[92:93], v[92:93], 0.5, v[98:99] op_sel_hi:[1,0,1]
	s_waitcnt vmcnt(2)
	v_pk_fma_f32 v[90:91], v[90:91], 0.5, v[104:105] op_sel_hi:[1,0,1]
	v_pk_fma_f32 v[88:89], v[88:89], 0.5, v[102:103] op_sel_hi:[1,0,1]
	v_cvt_pk_bf16_f32 v98, v92, v93
	v_cvt_pk_bf16_f32 v99, v94, v95
	v_cvt_pk_bf16_f32 v100, v88, v89
	v_cvt_pk_bf16_f32 v101, v90, v91
	global_store_dwordx4 v[108:109], v[92:95], off
	global_store_dwordx4 v[108:109], v[88:91], off offset:16
	global_store_dwordx4 v[106:107], v[98:101], off
	s_nop 1
	v_mul_f32_e32 v93, v93, v93
	v_mul_f32_e32 v95, v95, v95
	v_mul_f32_e32 v89, v89, v89
	v_mul_f32_e32 v91, v91, v91
	v_fmac_f32_e32 v93, v92, v92
	v_fmac_f32_e32 v95, v94, v94
	v_fmac_f32_e32 v89, v88, v88
	v_fmac_f32_e32 v91, v90, v90
	v_add_f32_e32 v88, v93, v95
	v_add_f32_e32 v89, v89, v91
	v_add_f32_e32 v92, v88, v89
	s_waitcnt vmcnt(4)
	v_pk_fma_f32 v[86:87], v[86:87], 0.5, v[178:179] op_sel_hi:[1,0,1]
	v_pk_fma_f32 v[84:85], v[84:85], 0.5, v[176:177] op_sel_hi:[1,0,1]
	s_waitcnt vmcnt(3)
	v_pk_fma_f32 v[90:91], v[82:83], 0.5, v[182:183] op_sel_hi:[1,0,1]
	v_pk_fma_f32 v[88:89], v[80:81], 0.5, v[180:181] op_sel_hi:[1,0,1]
	v_mul_f32_e32 v80, v85, v85
	v_mul_f32_e32 v81, v87, v87
	v_mul_f32_e32 v82, v89, v89
	v_mul_f32_e32 v83, v91, v91
	v_fmac_f32_e32 v80, v84, v84
	v_fmac_f32_e32 v81, v86, v86
	v_fmac_f32_e32 v82, v88, v88
	v_fmac_f32_e32 v83, v90, v90
	v_add_f32_e32 v80, v80, v81
	v_add_f32_e32 v81, v82, v83
	v_add_f32_e32 v80, v80, v81
	v_add_f32_e32 v80, v92, v80
	ds_bpermute_b32 v81, v120, v80
	global_store_dwordx4 v[108:109], v[84:87], off offset:512
	global_store_dwordx4 v[108:109], v[88:91], off offset:528
	v_cvt_pk_bf16_f32 v82, v84, v85
	v_cvt_pk_bf16_f32 v83, v86, v87
	v_cvt_pk_bf16_f32 v84, v88, v89
	s_waitcnt lgkmcnt(0)
	v_add_f32_e32 v80, v80, v81
	ds_bpermute_b32 v81, v114, v80
	v_cvt_pk_bf16_f32 v85, v90, v91
	global_store_dwordx4 v[106:107], v[82:85], off offset:256
	s_and_saveexec_b64 s[36:37], s[2:3]
	s_cbranch_execz .LBB0_592
	s_waitcnt lgkmcnt(0)
	v_add_f32_e32 v80, v80, v81
	v_mul_f32_e32 v80, 0x4b800000, v80
	v_trunc_f32_e32 v80, v80
	v_mul_f32_e32 v81, 0x2f800000, v80
	v_floor_f32_e32 v81, v81
	v_fmac_f32_e32 v80, 0xcf800000, v81
	v_cvt_u32_f32_e32 v80, v80
	v_cvt_u32_f32_e32 v81, v81
	v_lshl_add_u64 v[82:83], v[96:97], 3, s[18:19]
	global_atomic_add_x2 v[82:83], v[80:81], off
.LBB0_592:
	s_or_b64 exec, exec, s[36:37]
	v_or_b32_e32 v80, 48, v146
	s_waitcnt lgkmcnt(0)
	v_ashrrev_i32_e32 v81, 31, v80
	v_lshlrev_b64 v[82:83], 11, v[80:81]
	v_lshl_add_u64 v[90:91], v[82:83], 0, v[144:145]
	v_lshlrev_b64 v[92:93], 2, v[90:91]
	v_lshl_add_u64 v[94:95], s[52:53], 0, v[92:93]
	global_load_dwordx4 v[82:85], v[94:95], off
	global_load_dwordx4 v[86:89], v[94:95], off offset:16
	global_load_dwordx4 v[176:179], v[94:95], off offset:512
	global_load_dwordx4 v[180:183], v[94:95], off offset:528
	v_lshl_add_u64 v[90:91], v[90:91], 1, s[46:47]
	v_lshl_add_u64 v[92:93], s[28:29], 0, v[92:93]
	s_waitcnt vmcnt(3)
	v_pk_fma_f32 v[78:79], v[78:79], 0.5, v[84:85] op_sel_hi:[1,0,1]
	v_pk_fma_f32 v[76:77], v[76:77], 0.5, v[82:83] op_sel_hi:[1,0,1]
	s_waitcnt vmcnt(2)
	v_pk_fma_f32 v[74:75], v[74:75], 0.5, v[88:89] op_sel_hi:[1,0,1]
	v_pk_fma_f32 v[72:73], v[72:73], 0.5, v[86:87] op_sel_hi:[1,0,1]
	v_cvt_pk_bf16_f32 v82, v76, v77
	v_cvt_pk_bf16_f32 v83, v78, v79
	v_cvt_pk_bf16_f32 v84, v72, v73
	v_cvt_pk_bf16_f32 v85, v74, v75
	global_store_dwordx4 v[92:93], v[76:79], off
	global_store_dwordx4 v[92:93], v[72:75], off offset:16
	global_store_dwordx4 v[90:91], v[82:85], off
	s_nop 1
	v_mul_f32_e32 v77, v77, v77
	v_mul_f32_e32 v79, v79, v79
	v_mul_f32_e32 v73, v73, v73
	v_mul_f32_e32 v75, v75, v75
	v_fmac_f32_e32 v77, v76, v76
	v_fmac_f32_e32 v79, v78, v78
	v_fmac_f32_e32 v73, v72, v72
	v_fmac_f32_e32 v75, v74, v74
	v_add_f32_e32 v72, v77, v79
	v_add_f32_e32 v73, v73, v75
	v_add_f32_e32 v76, v72, v73
	s_waitcnt vmcnt(4)
	v_pk_fma_f32 v[70:71], v[70:71], 0.5, v[178:179] op_sel_hi:[1,0,1]
	v_pk_fma_f32 v[68:69], v[68:69], 0.5, v[176:177] op_sel_hi:[1,0,1]
	s_waitcnt vmcnt(3)
	v_pk_fma_f32 v[74:75], v[66:67], 0.5, v[182:183] op_sel_hi:[1,0,1]
	v_pk_fma_f32 v[72:73], v[64:65], 0.5, v[180:181] op_sel_hi:[1,0,1]
	v_mul_f32_e32 v64, v69, v69
	v_mul_f32_e32 v65, v71, v71
	v_mul_f32_e32 v66, v73, v73
	v_mul_f32_e32 v67, v75, v75
	v_fmac_f32_e32 v64, v68, v68
	v_fmac_f32_e32 v65, v70, v70
	v_fmac_f32_e32 v66, v72, v72
	v_fmac_f32_e32 v67, v74, v74
	v_add_f32_e32 v64, v64, v65
	v_add_f32_e32 v65, v66, v67
	v_add_f32_e32 v64, v64, v65
	v_add_f32_e32 v64, v76, v64
	ds_bpermute_b32 v65, v120, v64
	global_store_dwordx4 v[92:93], v[68:71], off offset:512
	global_store_dwordx4 v[92:93], v[72:75], off offset:528
	v_cvt_pk_bf16_f32 v66, v68, v69
	v_cvt_pk_bf16_f32 v67, v70, v71
	v_cvt_pk_bf16_f32 v68, v72, v73
	s_waitcnt lgkmcnt(0)
	v_add_f32_e32 v64, v64, v65
	ds_bpermute_b32 v65, v114, v64
	v_cvt_pk_bf16_f32 v69, v74, v75
	global_store_dwordx4 v[90:91], v[66:69], off offset:256
	s_and_saveexec_b64 s[36:37], s[2:3]
	s_cbranch_execz .LBB0_594
	s_waitcnt lgkmcnt(0)
	v_add_f32_e32 v64, v64, v65
	v_mul_f32_e32 v64, 0x4b800000, v64
	v_trunc_f32_e32 v64, v64
	v_mul_f32_e32 v65, 0x2f800000, v64
	v_floor_f32_e32 v65, v65
	v_fmac_f32_e32 v64, 0xcf800000, v65
	v_cvt_u32_f32_e32 v64, v64
	v_cvt_u32_f32_e32 v65, v65
	v_lshl_add_u64 v[66:67], v[80:81], 3, s[18:19]
	global_atomic_add_x2 v[66:67], v[64:65], off
; __device__ __forceinline__ u32x4 pack8(const f32x4 a, const f32x4 b) { u32x4 w; w.x = cvt_pk_bf16(a[0], a[1]); w.y = cvt_pk_bf16(a[2], a[3]); w.z = cvt_pk_bf16(b[0], b[1]); w.w = cvt_pk_bf16(b[2], b[3]); return w; }
; __device__ __forceinline__ void ss_add(ssq_t* p, float sq) { __hip_atomic_fetch_add(p, (ssq_t)(sq * 16777216.0f), __ATOMIC_RELAXED, __HIP_MEMORY_SCOPE_AGENT); }
; __device__ __forceinline__ float dot4(const f32x4 a) { return (a[0] * a[0] + a[1] * a[1]) + (a[2] * a[2] + a[3] * a[3]); }
;     __device__ __forceinline__ void operator()(const f32x4 (&acc)[2][2][4][2], const Unit& u, int wr, int wc, int fr, int fq) const {
;     ...
;         for (int ai = 0; ai < 2; ++ai)
; #pragma unroll
;             for (int m = 0; m < 4; ++m) { const int row = row0 + ai * HALF + m * 16; const size_t off = (size_t)row * 2048 + col0; float sq = 0.f;
; #pragma unroll
;                 for (int bj = 0; bj < 2; ++bj) {
;                     const f32x4 x0 = __builtin_nontemporal_load((const f32x4*)(xin + off + bj * HALF)), x1 = __builtin_nontemporal_load((const f32x4*)(xin + off + bj * HALF + 4));
;                     const f32x4 v0 = x0 + acc[ai][bj][m][0] * alpha, v1 = x1 + acc[ai][bj][m][1] * alpha;
;                     __builtin_nontemporal_store(v0, (f32x4*)(xout + off + bj * HALF)); __builtin_nontemporal_store(v1, (f32x4*)(xout + off + bj * HALF + 4));
;                     if (WRITE_XB) *(u32x4*)(xb + off + bj * HALF) = pack8(v0, v1); sq += dot4(v0) + dot4(v1); }
;                 sq += __shfl_xor(sq, 16); sq += __shfl_xor(sq, 32);
;                 if (fq == 0) ss_add(ssout + row, sq); }
.LBB0_594:
	s_or_b64 exec, exec, s[36:37]
	v_add_u32_e32 v64, 0x80, v146
	s_waitcnt lgkmcnt(0)
	v_ashrrev_i32_e32 v65, 31, v64
	v_lshlrev_b64 v[66:67], 11, v[64:65]
	v_lshl_add_u64 v[74:75], v[66:67], 0, v[144:145]
	v_lshlrev_b64 v[76:77], 2, v[74:75]
	v_lshl_add_u64 v[78:79], s[52:53], 0, v[76:77]
	global_load_dwordx4 v[66:69], v[78:79], off
	global_load_dwordx4 v[70:73], v[78:79], off offset:16
	global_load_dwordx4 v[176:179], v[78:79], off offset:512
	global_load_dwordx4 v[180:183], v[78:79], off offset:528
	v_lshl_add_u64 v[74:75], v[74:75], 1, s[46:47]
	v_lshl_add_u64 v[76:77], s[28:29], 0, v[76:77]
	s_waitcnt vmcnt(3)
	v_pk_fma_f32 v[62:63], v[62:63], 0.5, v[68:69] op_sel_hi:[1,0,1]
	v_pk_fma_f32 v[60:61], v[60:61], 0.5, v[66:67] op_sel_hi:[1,0,1]
	s_waitcnt vmcnt(2)
	v_pk_fma_f32 v[58:59], v[58:59], 0.5, v[72:73] op_sel_hi:[1,0,1]
	v_pk_fma_f32 v[56:57], v[56:57], 0.5, v[70:71] op_sel_hi:[1,0,1]
	v_cvt_pk_bf16_f32 v66, v60, v61
	v_cvt_pk_bf16_f32 v67, v62, v63
	v_cvt_pk_bf16_f32 v68, v56, v57
	v_cvt_pk_bf16_f32 v69, v58, v59
	global_store_dwordx4 v[76:77], v[60:63], off
	global_store_dwordx4 v[76:77], v[56:59], off offset:16
	global_store_dwordx4 v[74:75], v[66:69], off
	s_nop 1
	v_mul_f32_e32 v61, v61, v61
	v_mul_f32_e32 v63, v63, v63
	v_mul_f32_e32 v57, v57, v57
	v_mul_f32_e32 v59, v59, v59
	v_fmac_f32_e32 v61, v60, v60
	v_fmac_f32_e32 v63, v62, v62
	v_fmac_f32_e32 v57, v56, v56
	v_fmac_f32_e32 v59, v58, v58
	v_add_f32_e32 v56, v61, v63
	v_add_f32_e32 v57, v57, v59
	v_add_f32_e32 v60, v56, v57
	s_waitcnt vmcnt(4)
	v_pk_fma_f32 v[54:55], v[54:55], 0.5, v[178:179] op_sel_hi:[1,0,1]
	v_pk_fma_f32 v[52:53], v[52:53], 0.5, v[176:177] op_sel_hi:[1,0,1]
	s_waitcnt vmcnt(3)
	v_pk_fma_f32 v[58:59], v[50:51], 0.5, v[182:183] op_sel_hi:[1,0,1]
	v_pk_fma_f32 v[56:57], v[48:49], 0.5, v[180:181] op_sel_hi:[1,0,1]
	v_mul_f32_e32 v48, v53, v53
	v_mul_f32_e32 v49, v55, v55
	v_mul_f32_e32 v50, v57, v57
	v_mul_f32_e32 v51, v59, v59
	v_fmac_f32_e32 v48, v52, v52
	v_fmac_f32_e32 v49, v54, v54
	v_fmac_f32_e32 v50, v56, v56
	v_fmac_f32_e32 v51, v58, v58
	v_add_f32_e32 v48, v48, v49
	v_add_f32_e32 v49, v50, v51
	v_add_f32_e32 v48, v48, v49
	v_add_f32_e32 v48, v60, v48
	ds_bpermute_b32 v49, v120, v48
	global_store_dwordx4 v[76:77], v[52:55], off offset:512
	global_store_dwordx4 v[76:77], v[56:59], off offset:528
	v_cvt_pk_bf16_f32 v50, v52, v53
	v_cvt_pk_bf16_f32 v51, v54, v55
	v_cvt_pk_bf16_f32 v52, v56, v57
	s_waitcnt lgkmcnt(0)
	v_add_f32_e32 v48, v48, v49
	ds_bpermute_b32 v49, v114, v48
	v_cvt_pk_bf16_f32 v53, v58, v59
	global_store_dwordx4 v[74:75], v[50:53], off offset:256
	s_and_saveexec_b64 s[36:37], s[2:3]
	s_cbranch_execz .LBB0_596
	s_waitcnt lgkmcnt(0)
	v_add_f32_e32 v48, v48, v49
	v_mul_f32_e32 v48, 0x4b800000, v48
	v_trunc_f32_e32 v48, v48
	v_mul_f32_e32 v49, 0x2f800000, v48
	v_floor_f32_e32 v49, v49
	v_fmac_f32_e32 v48, 0xcf800000, v49
	v_cvt_u32_f32_e32 v48, v48
	v_cvt_u32_f32_e32 v49, v49
	v_lshl_add_u64 v[50:51], v[64:65], 3, s[18:19]
	global_atomic_add_x2 v[50:51], v[48:49], off
.LBB0_596:
	s_or_b64 exec, exec, s[36:37]
	v_add_u32_e32 v48, 0x90, v146
	s_waitcnt lgkmcnt(0)
	v_ashrrev_i32_e32 v49, 31, v48
	v_lshlrev_b64 v[50:51], 11, v[48:49]
	v_lshl_add_u64 v[58:59], v[50:51], 0, v[144:145]
	v_lshlrev_b64 v[60:61], 2, v[58:59]
	v_lshl_add_u64 v[62:63], s[52:53], 0, v[60:61]
	global_load_dwordx4 v[50:53], v[62:63], off
	global_load_dwordx4 v[54:57], v[62:63], off offset:16
	global_load_dwordx4 v[176:179], v[62:63], off offset:512
	global_load_dwordx4 v[180:183], v[62:63], off offset:528
	v_lshl_add_u64 v[58:59], v[58:59], 1, s[46:47]
	v_lshl_add_u64 v[60:61], s[28:29], 0, v[60:61]
	s_waitcnt vmcnt(3)
	v_pk_fma_f32 v[46:47], v[46:47], 0.5, v[52:53] op_sel_hi:[1,0,1]
	v_pk_fma_f32 v[44:45], v[44:45], 0.5, v[50:51] op_sel_hi:[1,0,1]
	s_waitcnt vmcnt(2)
	v_pk_fma_f32 v[42:43], v[42:43], 0.5, v[56:57] op_sel_hi:[1,0,1]
	v_pk_fma_f32 v[40:41], v[40:41], 0.5, v[54:55] op_sel_hi:[1,0,1]
	v_cvt_pk_bf16_f32 v50, v44, v45
	v_cvt_pk_bf16_f32 v51, v46, v47
	v_cvt_pk_bf16_f32 v52, v40, v41
	v_cvt_pk_bf16_f32 v53, v42, v43
	global_store_dwordx4 v[60:61], v[44:47], off
	global_store_dwordx4 v[60:61], v[40:43], off offset:16
	global_store_dwordx4 v[58:59], v[50:53], off
	s_nop 1
	v_mul_f32_e32 v45, v45, v45
	v_mul_f32_e32 v47, v47, v47
	v_mul_f32_e32 v41, v41, v41
	v_mul_f32_e32 v43, v43, v43
	v_fmac_f32_e32 v45, v44, v44
	v_fmac_f32_e32 v47, v46, v46
	v_fmac_f32_e32 v41, v40, v40
	v_fmac_f32_e32 v43, v42, v42
	v_add_f32_e32 v40, v45, v47
	v_add_f32_e32 v41, v41, v43
	v_add_f32_e32 v44, v40, v41
	s_waitcnt vmcnt(4)
	v_pk_fma_f32 v[38:39], v[38:39], 0.5, v[178:179] op_sel_hi:[1,0,1]
	v_pk_fma_f32 v[36:37], v[36:37], 0.5, v[176:177] op_sel_hi:[1,0,1]
	s_waitcnt vmcnt(3)
	v_pk_fma_f32 v[42:43], v[34:35], 0.5, v[182:183] op_sel_hi:[1,0,1]
	v_pk_fma_f32 v[40:41], v[32:33], 0.5, v[180:181] op_sel_hi:[1,0,1]
	v_mul_f32_e32 v32, v37, v37
	v_mul_f32_e32 v33, v39, v39
	v_mul_f32_e32 v34, v41, v41
	v_mul_f32_e32 v35, v43, v43
	v_fmac_f32_e32 v32, v36, v36
	v_fmac_f32_e32 v33, v38, v38
	v_fmac_f32_e32 v34, v40, v40
	v_fmac_f32_e32 v35, v42, v42
	v_add_f32_e32 v32, v32, v33
	v_add_f32_e32 v33, v34, v35
	v_add_f32_e32 v32, v32, v33
	v_add_f32_e32 v32, v44, v32
	ds_bpermute_b32 v33, v120, v32
	global_store_dwordx4 v[60:61], v[36:39], off offset:512
	global_store_dwordx4 v[60:61], v[40:43], off offset:528
	v_cvt_pk_bf16_f32 v34, v36, v37
	v_cvt_pk_bf16_f32 v35, v38, v39
	v_cvt_pk_bf16_f32 v36, v40, v41
	s_waitcnt lgkmcnt(0)
	v_add_f32_e32 v32, v32, v33
	ds_bpermute_b32 v33, v114, v32
	v_cvt_pk_bf16_f32 v37, v42, v43
	global_store_dwordx4 v[58:59], v[34:37], off offset:256
	s_and_saveexec_b64 s[36:37], s[2:3]
	s_cbranch_execz .LBB0_598
	s_waitcnt lgkmcnt(0)
	v_add_f32_e32 v32, v32, v33
	v_mul_f32_e32 v32, 0x4b800000, v32
	v_trunc_f32_e32 v32, v32
	v_mul_f32_e32 v33, 0x2f800000, v32
	v_floor_f32_e32 v33, v33
	v_fmac_f32_e32 v32, 0xcf800000, v33
	v_cvt_u32_f32_e32 v32, v32
	v_cvt_u32_f32_e32 v33, v33
	v_lshl_add_u64 v[34:35], v[48:49], 3, s[18:19]
	global_atomic_add_x2 v[34:35], v[32:33], off
; __device__ __forceinline__ u32x4 pack8(const f32x4 a, const f32x4 b) { u32x4 w; w.x = cvt_pk_bf16(a[0], a[1]); w.y = cvt_pk_bf16(a[2], a[3]); w.z = cvt_pk_bf16(b[0], b[1]); w.w = cvt_pk_bf16(b[2], b[3]); return w; }
; __device__ __forceinline__ void ss_add(ssq_t* p, float sq) { __hip_atomic_fetch_add(p, (ssq_t)(sq * 16777216.0f), __ATOMIC_RELAXED, __HIP_MEMORY_SCOPE_AGENT); }
; __device__ __forceinline__ float dot4(const f32x4 a) { return (a[0] * a[0] + a[1] * a[1]) + (a[2] * a[2] + a[3] * a[3]); }
;     __device__ __forceinline__ void operator()(const f32x4 (&acc)[2][2][4][2], const Unit& u, int wr, int wc, int fr, int fq) const {
;     ...
;         for (int ai = 0; ai < 2; ++ai)
; #pragma unroll
;             for (int m = 0; m < 4; ++m) { const int row = row0 + ai * HALF + m * 16; const size_t off = (size_t)row * 2048 + col0; float sq = 0.f;
; #pragma unroll
;                 for (int bj = 0; bj < 2; ++bj) {
;                     const f32x4 x0 = __builtin_nontemporal_load((const f32x4*)(xin + off + bj * HALF)), x1 = __builtin_nontemporal_load((const f32x4*)(xin + off + bj * HALF + 4));
;                     const f32x4 v0 = x0 + acc[ai][bj][m][0] * alpha, v1 = x1 + acc[ai][bj][m][1] * alpha;
;                     __builtin_nontemporal_store(v0, (f32x4*)(xout + off + bj * HALF)); __builtin_nontemporal_store(v1, (f32x4*)(xout + off + bj * HALF + 4));
;                     if (WRITE_XB) *(u32x4*)(xb + off + bj * HALF) = pack8(v0, v1); sq += dot4(v0) + dot4(v1); }
;                 sq += __shfl_xor(sq, 16); sq += __shfl_xor(sq, 32);
;                 if (fq == 0) ss_add(ssout + row, sq); }
.LBB0_598:
	s_or_b64 exec, exec, s[36:37]
	v_add_u32_e32 v32, 0xa0, v146
	s_waitcnt lgkmcnt(0)
	v_ashrrev_i32_e32 v33, 31, v32
	v_lshlrev_b64 v[34:35], 11, v[32:33]
	v_lshl_add_u64 v[42:43], v[34:35], 0, v[144:145]
	v_lshlrev_b64 v[44:45], 2, v[42:43]
	v_lshl_add_u64 v[46:47], s[52:53], 0, v[44:45]
	global_load_dwordx4 v[34:37], v[46:47], off
	global_load_dwordx4 v[38:41], v[46:47], off offset:16
	global_load_dwordx4 v[176:179], v[46:47], off offset:512
	global_load_dwordx4 v[180:183], v[46:47], off offset:528
	v_lshl_add_u64 v[42:43], v[42:43], 1, s[46:47]
	v_lshl_add_u64 v[44:45], s[28:29], 0, v[44:45]
	s_waitcnt vmcnt(3)
	v_pk_fma_f32 v[30:31], v[30:31], 0.5, v[36:37] op_sel_hi:[1,0,1]
	v_pk_fma_f32 v[28:29], v[28:29], 0.5, v[34:35] op_sel_hi:[1,0,1]
	s_waitcnt vmcnt(2)
	v_pk_fma_f32 v[26:27], v[26:27], 0.5, v[40:41] op_sel_hi:[1,0,1]
	v_pk_fma_f32 v[24:25], v[24:25], 0.5, v[38:39] op_sel_hi:[1,0,1]
	v_cvt_pk_bf16_f32 v34, v28, v29
	v_cvt_pk_bf16_f32 v35, v30, v31
	v_cvt_pk_bf16_f32 v36, v24, v25
	v_cvt_pk_bf16_f32 v37, v26, v27
	global_store_dwordx4 v[44:45], v[28:31], off
	global_store_dwordx4 v[44:45], v[24:27], off offset:16
	global_store_dwordx4 v[42:43], v[34:37], off
	s_nop 1
	v_mul_f32_e32 v29, v29, v29
	v_mul_f32_e32 v31, v31, v31
	v_mul_f32_e32 v25, v25, v25
	v_mul_f32_e32 v27, v27, v27
	v_fmac_f32_e32 v29, v28, v28
	v_fmac_f32_e32 v31, v30, v30
	v_fmac_f32_e32 v25, v24, v24
	v_fmac_f32_e32 v27, v26, v26
	v_add_f32_e32 v24, v29, v31
	v_add_f32_e32 v25, v25, v27
	v_add_f32_e32 v28, v24, v25
	s_waitcnt vmcnt(4)
	v_pk_fma_f32 v[22:23], v[22:23], 0.5, v[178:179] op_sel_hi:[1,0,1]
	v_pk_fma_f32 v[20:21], v[20:21], 0.5, v[176:177] op_sel_hi:[1,0,1]
	s_waitcnt vmcnt(3)
	v_pk_fma_f32 v[26:27], v[18:19], 0.5, v[182:183] op_sel_hi:[1,0,1]
	v_pk_fma_f32 v[24:25], v[16:17], 0.5, v[180:181] op_sel_hi:[1,0,1]
	v_mul_f32_e32 v16, v21, v21
	v_mul_f32_e32 v17, v23, v23
	v_mul_f32_e32 v18, v25, v25
	v_mul_f32_e32 v19, v27, v27
	v_fmac_f32_e32 v16, v20, v20
	v_fmac_f32_e32 v17, v22, v22
	v_fmac_f32_e32 v18, v24, v24
	v_fmac_f32_e32 v19, v26, v26
	v_add_f32_e32 v16, v16, v17
	v_add_f32_e32 v17, v18, v19
	v_add_f32_e32 v16, v16, v17
	v_add_f32_e32 v16, v28, v16
	ds_bpermute_b32 v17, v120, v16
	global_store_dwordx4 v[44:45], v[20:23], off offset:512
	global_store_dwordx4 v[44:45], v[24:27], off offset:528
	v_cvt_pk_bf16_f32 v18, v20, v21
	v_cvt_pk_bf16_f32 v19, v22, v23
	v_cvt_pk_bf16_f32 v20, v24, v25
	s_waitcnt lgkmcnt(0)
	v_add_f32_e32 v16, v16, v17
	ds_bpermute_b32 v17, v114, v16
	v_cvt_pk_bf16_f32 v21, v26, v27
	global_store_dwordx4 v[42:43], v[18:21], off offset:256
	s_and_saveexec_b64 s[36:37], s[2:3]
	s_cbranch_execz .LBB0_600
	s_waitcnt lgkmcnt(0)
	v_add_f32_e32 v16, v16, v17
	v_mul_f32_e32 v16, 0x4b800000, v16
	v_trunc_f32_e32 v16, v16
	v_mul_f32_e32 v17, 0x2f800000, v16
	v_floor_f32_e32 v17, v17
	v_fmac_f32_e32 v16, 0xcf800000, v17
	v_cvt_u32_f32_e32 v16, v16
	v_cvt_u32_f32_e32 v17, v17
	v_lshl_add_u64 v[18:19], v[32:33], 3, s[18:19]
	global_atomic_add_x2 v[18:19], v[16:17], off
.LBB0_600:
	s_or_b64 exec, exec, s[36:37]
	v_add_u32_e32 v16, 0xb0, v146
	s_waitcnt lgkmcnt(0)
	v_ashrrev_i32_e32 v17, 31, v16
	v_lshlrev_b64 v[18:19], 11, v[16:17]
	v_lshl_add_u64 v[26:27], v[18:19], 0, v[144:145]
	v_lshlrev_b64 v[28:29], 2, v[26:27]
	v_lshl_add_u64 v[30:31], s[52:53], 0, v[28:29]
	global_load_dwordx4 v[18:21], v[30:31], off
	global_load_dwordx4 v[22:25], v[30:31], off offset:16
	global_load_dwordx4 v[176:179], v[30:31], off offset:512
	global_load_dwordx4 v[180:183], v[30:31], off offset:528
	v_lshl_add_u64 v[26:27], v[26:27], 1, s[46:47]
	v_lshl_add_u64 v[28:29], s[28:29], 0, v[28:29]
	s_waitcnt vmcnt(3)
	v_pk_fma_f32 v[14:15], v[14:15], 0.5, v[20:21] op_sel_hi:[1,0,1]
	v_pk_fma_f32 v[12:13], v[12:13], 0.5, v[18:19] op_sel_hi:[1,0,1]
	s_waitcnt vmcnt(2)
	v_pk_fma_f32 v[10:11], v[10:11], 0.5, v[24:25] op_sel_hi:[1,0,1]
	v_pk_fma_f32 v[8:9], v[8:9], 0.5, v[22:23] op_sel_hi:[1,0,1]
	v_cvt_pk_bf16_f32 v18, v12, v13
	v_cvt_pk_bf16_f32 v19, v14, v15
	v_cvt_pk_bf16_f32 v20, v8, v9
	v_cvt_pk_bf16_f32 v21, v10, v11
	global_store_dwordx4 v[28:29], v[12:15], off
	global_store_dwordx4 v[28:29], v[8:11], off offset:16
	global_store_dwordx4 v[26:27], v[18:21], off
	s_nop 1
	v_mul_f32_e32 v13, v13, v13
	v_mul_f32_e32 v15, v15, v15
	v_mul_f32_e32 v9, v9, v9
	v_mul_f32_e32 v11, v11, v11
	v_fmac_f32_e32 v13, v12, v12
	v_fmac_f32_e32 v15, v14, v14
	v_fmac_f32_e32 v9, v8, v8
	v_fmac_f32_e32 v11, v10, v10
	v_add_f32_e32 v8, v13, v15
	v_add_f32_e32 v9, v9, v11
	v_add_f32_e32 v12, v8, v9
	s_waitcnt vmcnt(4)
	v_pk_fma_f32 v[6:7], v[6:7], 0.5, v[178:179] op_sel_hi:[1,0,1]
	v_pk_fma_f32 v[4:5], v[4:5], 0.5, v[176:177] op_sel_hi:[1,0,1]
	s_waitcnt vmcnt(3)
	v_pk_fma_f32 v[10:11], v[2:3], 0.5, v[182:183] op_sel_hi:[1,0,1]
	v_pk_fma_f32 v[8:9], v[0:1], 0.5, v[180:181] op_sel_hi:[1,0,1]
	v_mul_f32_e32 v0, v5, v5
	v_mul_f32_e32 v1, v7, v7
	v_mul_f32_e32 v2, v9, v9
	v_mul_f32_e32 v3, v11, v11
	v_fmac_f32_e32 v0, v4, v4
	v_fmac_f32_e32 v1, v6, v6
	v_fmac_f32_e32 v2, v8, v8
	v_fmac_f32_e32 v3, v10, v10
	v_add_f32_e32 v0, v0, v1
	v_add_f32_e32 v1, v2, v3
	v_add_f32_e32 v0, v0, v1
	v_add_f32_e32 v0, v12, v0
	ds_bpermute_b32 v1, v120, v0
	global_store_dwordx4 v[28:29], v[4:7], off offset:512
	global_store_dwordx4 v[28:29], v[8:11], off offset:528
	v_cvt_pk_bf16_f32 v2, v4, v5
	v_cvt_pk_bf16_f32 v3, v6, v7
	v_cvt_pk_bf16_f32 v4, v8, v9
	s_waitcnt lgkmcnt(0)
	v_add_f32_e32 v0, v0, v1
	ds_bpermute_b32 v1, v114, v0
	v_cvt_pk_bf16_f32 v5, v10, v11
	global_store_dwordx4 v[26:27], v[2:5], off offset:256
	s_and_saveexec_b64 s[36:37], s[2:3]
	s_cbranch_execz .LBB0_602
	s_waitcnt lgkmcnt(0)
	v_add_f32_e32 v0, v0, v1
	v_mul_f32_e32 v0, 0x4b800000, v0
	v_trunc_f32_e32 v0, v0
	v_mul_f32_e32 v1, 0x2f800000, v0
	v_floor_f32_e32 v1, v1
	v_fmac_f32_e32 v0, 0xcf800000, v1
	v_cvt_u32_f32_e32 v0, v0
	v_cvt_u32_f32_e32 v1, v1
	v_lshl_add_u64 v[2:3], v[16:17], 3, s[18:19]
	global_atomic_add_x2 v[2:3], v[0:1], off

; __device__ __forceinline__ u32x4 pack8(const f32x4 a, const f32x4 b) { u32x4 w; w.x = cvt_pk_bf16(a[0], a[1]); w.y = cvt_pk_bf16(a[2], a[3]); w.z = cvt_pk_bf16(b[0], b[1]); w.w = cvt_pk_bf16(b[2], b[3]); return w; }
; __device__ __forceinline__ void ss_add(ssq_t* p, float sq) { __hip_atomic_fetch_add(p, (ssq_t)(sq * 16777216.0f), __ATOMIC_RELAXED, __HIP_MEMORY_SCOPE_AGENT); }
; __device__ __forceinline__ float dot4(const f32x4 a) { return (a[0] * a[0] + a[1] * a[1]) + (a[2] * a[2] + a[3] * a[3]); }
;     __device__ __forceinline__ void operator()(const f32x4 (&acc)[2][2][4][2], const Unit& u, int wr, int wc, int fr, int fq) const {
;     ...
;         for (int ai = 0; ai < 2; ++ai)
; #pragma unroll
;             for (int m = 0; m < 4; ++m) { const int row = row0 + ai * HALF + m * 16; const size_t off = (size_t)row * 2048 + col0; float sq = 0.f;
; #pragma unroll
;                 for (int bj = 0; bj < 2; ++bj) {
;                     const f32x4 x0 = __builtin_nontemporal_load((const f32x4*)(xin + off + bj * HALF)), x1 = __builtin_nontemporal_load((const f32x4*)(xin + off + bj * HALF + 4));
;                     const f32x4 v0 = x0 + acc[ai][bj][m][0] * alpha, v1 = x1 + acc[ai][bj][m][1] * alpha;
;                     __builtin_nontemporal_store(v0, (f32x4*)(xout + off + bj * HALF)); __builtin_nontemporal_store(v1, (f32x4*)(xout + off + bj * HALF + 4));
;                     if (WRITE_XB) *(u32x4*)(xb + off + bj * HALF) = pack8(v0, v1); sq += dot4(v0) + dot4(v1); }
;                 sq += __shfl_xor(sq, 16); sq += __shfl_xor(sq, 32);
;                 if (fq == 0) ss_add(ssout + row, sq); }
.LBB0_1306:
	v_lshl_add_u32 v146, s62, 8, v148
	v_lshl_add_u32 v144, s64, 8, v150
	v_ashrrev_i32_e32 v147, 31, v146
	v_ashrrev_i32_e32 v145, 31, v144
	v_lshlrev_b64 v[156:157], 11, v[146:147]
	v_lshl_add_u64 v[164:165], v[156:157], 0, v[144:145]
	v_lshl_add_u64 v[168:169], v[164:165], 2, s[28:29]
	global_load_dwordx4 v[156:159], v[168:169], off
	global_load_dwordx4 v[160:163], v[168:169], off offset:16
	global_load_dwordx4 v[176:179], v[168:169], off offset:512
	global_load_dwordx4 v[180:183], v[168:169], off offset:528
	v_lshl_add_u64 v[170:171], v[164:165], 1, s[46:47]
	s_waitcnt vmcnt(2)
	v_pk_add_f32 v[126:127], v[126:127], v[158:159]
	v_pk_add_f32 v[124:125], v[124:125], v[156:157]
	v_pk_add_f32 v[158:159], v[122:123], v[162:163]
	v_pk_add_f32 v[156:157], v[120:121], v[160:161]
	v_cvt_pk_bf16_f32 v120, v124, v125
	v_cvt_pk_bf16_f32 v121, v126, v127
	v_cvt_pk_bf16_f32 v122, v156, v157
	v_cvt_pk_bf16_f32 v123, v158, v159
	global_store_dwordx4 v[168:169], v[124:127], off
	global_store_dwordx4 v[168:169], v[156:159], off offset:16
	global_store_dwordx4 v[170:171], v[120:123], off
	s_nop 1
	v_and_b32_e32 v121, 64, v154
	v_xor_b32_e32 v120, 16, v154
	v_add_u32_e32 v121, 64, v121
	v_xor_b32_e32 v122, 32, v154
	v_cmp_lt_i32_e32 vcc, v120, v121
	v_mul_f32_e32 v123, v127, v127
	v_mul_f32_e32 v127, v159, v159
	v_cndmask_b32_e32 v120, v154, v120, vcc
	v_cmp_lt_i32_e32 vcc, v122, v121
	v_fmac_f32_e32 v123, v126, v126
	v_fmac_f32_e32 v127, v158, v158
	v_cndmask_b32_e32 v121, v154, v122, vcc
	v_mul_f32_e32 v122, v125, v125
	v_mul_f32_e32 v125, v157, v157
	v_fmac_f32_e32 v122, v124, v124
	v_fmac_f32_e32 v125, v156, v156
	v_add_f32_e32 v122, v122, v123
	v_add_f32_e32 v123, v125, v127
	v_add_f32_e32 v126, v122, v123
	v_lshlrev_b32_e32 v120, 2, v120
	s_waitcnt vmcnt(4)
	v_pk_add_f32 v[118:119], v[118:119], v[178:179]
	v_pk_add_f32 v[116:117], v[116:117], v[176:177]
	s_waitcnt vmcnt(3)
	v_pk_add_f32 v[124:125], v[114:115], v[182:183]
	v_pk_add_f32 v[122:123], v[112:113], v[180:181]
	v_mul_f32_e32 v112, v117, v117
	v_mul_f32_e32 v113, v119, v119
	v_mul_f32_e32 v114, v123, v123
	v_mul_f32_e32 v115, v125, v125
	v_fmac_f32_e32 v112, v116, v116
	v_fmac_f32_e32 v113, v118, v118
	v_fmac_f32_e32 v114, v122, v122
	v_fmac_f32_e32 v115, v124, v124
	v_add_f32_e32 v112, v112, v113
	v_add_f32_e32 v113, v114, v115
	v_add_f32_e32 v112, v112, v113
	v_add_f32_e32 v112, v126, v112
	ds_bpermute_b32 v113, v120, v112
	v_lshlrev_b32_e32 v114, 2, v121
	global_store_dwordx4 v[168:169], v[116:119], off offset:512
	global_store_dwordx4 v[168:169], v[122:125], off offset:528
	s_waitcnt lgkmcnt(0)
	v_add_f32_e32 v112, v112, v113
	ds_bpermute_b32 v113, v114, v112
	v_cvt_pk_bf16_f32 v116, v116, v117
	v_cvt_pk_bf16_f32 v117, v118, v119
	v_cvt_pk_bf16_f32 v118, v122, v123
	v_cvt_pk_bf16_f32 v119, v124, v125
	global_store_dwordx4 v[170:171], v[116:119], off offset:256
	s_and_saveexec_b64 s[48:49], s[2:3]
	s_cbranch_execz .LBB0_1308
	s_waitcnt lgkmcnt(0)
	v_add_f32_e32 v112, v112, v113
	v_mul_f32_e32 v112, 0x4b800000, v112
	v_trunc_f32_e32 v112, v112
	v_mul_f32_e32 v113, 0x2f800000, v112
	v_floor_f32_e32 v113, v113
	v_fmac_f32_e32 v112, 0xcf800000, v113
	v_cvt_u32_f32_e32 v112, v112
	v_cvt_u32_f32_e32 v113, v113
	v_lshl_add_u64 v[116:117], v[146:147], 3, s[6:7]
	global_atomic_add_x2 v[116:117], v[112:113], off
.LBB0_1308:
	s_or_b64 exec, exec, s[48:49]
	v_or_b32_e32 v112, 16, v146
	s_waitcnt lgkmcnt(0)
	v_ashrrev_i32_e32 v113, 31, v112
	v_lshlrev_b64 v[116:117], 11, v[112:113]
	v_lshl_add_u64 v[126:127], v[116:117], 0, v[144:145]
	v_lshl_add_u64 v[156:157], v[126:127], 2, s[28:29]
	global_load_dwordx4 v[116:119], v[156:157], off
	global_load_dwordx4 v[122:125], v[156:157], off offset:16
	global_load_dwordx4 v[176:179], v[156:157], off offset:512
	global_load_dwordx4 v[180:183], v[156:157], off offset:528
	v_lshl_add_u64 v[126:127], v[126:127], 1, s[46:47]
	s_waitcnt vmcnt(3)
	v_pk_add_f32 v[110:111], v[110:111], v[118:119]
	v_pk_add_f32 v[108:109], v[108:109], v[116:117]
	s_waitcnt vmcnt(2)
	v_pk_add_f32 v[106:107], v[106:107], v[124:125]
	v_pk_add_f32 v[104:105], v[104:105], v[122:123]
	v_cvt_pk_bf16_f32 v116, v108, v109
	v_cvt_pk_bf16_f32 v117, v110, v111
	v_cvt_pk_bf16_f32 v118, v104, v105
	v_cvt_pk_bf16_f32 v119, v106, v107
	global_store_dwordx4 v[156:157], v[108:111], off
	global_store_dwordx4 v[156:157], v[104:107], off offset:16
	global_store_dwordx4 v[126:127], v[116:119], off
	s_nop 1
	v_mul_f32_e32 v109, v109, v109
	v_mul_f32_e32 v111, v111, v111
	v_mul_f32_e32 v105, v105, v105
	v_mul_f32_e32 v107, v107, v107
	v_fmac_f32_e32 v109, v108, v108
	v_fmac_f32_e32 v111, v110, v110
	v_fmac_f32_e32 v105, v104, v104
	v_fmac_f32_e32 v107, v106, v106
	v_add_f32_e32 v104, v109, v111
	v_add_f32_e32 v105, v105, v107
	v_add_f32_e32 v108, v104, v105
	s_waitcnt vmcnt(4)
	v_pk_add_f32 v[102:103], v[102:103], v[178:179]
	v_pk_add_f32 v[100:101], v[100:101], v[176:177]
	s_waitcnt vmcnt(3)
	v_pk_add_f32 v[106:107], v[98:99], v[182:183]
	v_pk_add_f32 v[104:105], v[96:97], v[180:181]
	v_mul_f32_e32 v96, v101, v101
	v_mul_f32_e32 v97, v103, v103
	v_mul_f32_e32 v98, v105, v105
	v_mul_f32_e32 v99, v107, v107
	v_fmac_f32_e32 v96, v100, v100
	v_fmac_f32_e32 v97, v102, v102
	v_fmac_f32_e32 v98, v104, v104
	v_fmac_f32_e32 v99, v106, v106
	v_add_f32_e32 v96, v96, v97
	v_add_f32_e32 v97, v98, v99
	v_add_f32_e32 v96, v96, v97
	v_add_f32_e32 v96, v108, v96
	ds_bpermute_b32 v97, v120, v96
	global_store_dwordx4 v[156:157], v[100:103], off offset:512
	global_store_dwordx4 v[156:157], v[104:107], off offset:528
	v_cvt_pk_bf16_f32 v98, v100, v101
	v_cvt_pk_bf16_f32 v99, v102, v103
	v_cvt_pk_bf16_f32 v100, v104, v105
	s_waitcnt lgkmcnt(0)
	v_add_f32_e32 v96, v96, v97
	ds_bpermute_b32 v97, v114, v96
	v_cvt_pk_bf16_f32 v101, v106, v107
	global_store_dwordx4 v[126:127], v[98:101], off offset:256
	s_and_saveexec_b64 s[48:49], s[2:3]
	s_cbranch_execz .LBB0_1310
	s_waitcnt lgkmcnt(0)
	v_add_f32_e32 v96, v96, v97
	v_mul_f32_e32 v96, 0x4b800000, v96
	v_trunc_f32_e32 v96, v96
	v_mul_f32_e32 v97, 0x2f800000, v96
	v_floor_f32_e32 v97, v97
	v_fmac_f32_e32 v96, 0xcf800000, v97
	v_cvt_u32_f32_e32 v96, v96
	v_cvt_u32_f32_e32 v97, v97
	v_lshl_add_u64 v[98:99], v[112:113], 3, s[6:7]
	global_atomic_add_x2 v[98:99], v[96:97], off
; __device__ __forceinline__ u32x4 pack8(const f32x4 a, const f32x4 b) { u32x4 w; w.x = cvt_pk_bf16(a[0], a[1]); w.y = cvt_pk_bf16(a[2], a[3]); w.z = cvt_pk_bf16(b[0], b[1]); w.w = cvt_pk_bf16(b[2], b[3]); return w; }
; __device__ __forceinline__ void ss_add(ssq_t* p, float sq) { __hip_atomic_fetch_add(p, (ssq_t)(sq * 16777216.0f), __ATOMIC_RELAXED, __HIP_MEMORY_SCOPE_AGENT); }
; __device__ __forceinline__ float dot4(const f32x4 a) { return (a[0] * a[0] + a[1] * a[1]) + (a[2] * a[2] + a[3] * a[3]); }
;     __device__ __forceinline__ void operator()(const f32x4 (&acc)[2][2][4][2], const Unit& u, int wr, int wc, int fr, int fq) const {
;     ...
;         for (int ai = 0; ai < 2; ++ai)
; #pragma unroll
;             for (int m = 0; m < 4; ++m) { const int row = row0 + ai * HALF + m * 16; const size_t off = (size_t)row * 2048 + col0; float sq = 0.f;
; #pragma unroll
;                 for (int bj = 0; bj < 2; ++bj) {
;                     const f32x4 x0 = __builtin_nontemporal_load((const f32x4*)(xin + off + bj * HALF)), x1 = __builtin_nontemporal_load((const f32x4*)(xin + off + bj * HALF + 4));
;                     const f32x4 v0 = x0 + acc[ai][bj][m][0] * alpha, v1 = x1 + acc[ai][bj][m][1] * alpha;
;                     __builtin_nontemporal_store(v0, (f32x4*)(xout + off + bj * HALF)); __builtin_nontemporal_store(v1, (f32x4*)(xout + off + bj * HALF + 4));
;                     if (WRITE_XB) *(u32x4*)(xb + off + bj * HALF) = pack8(v0, v1); sq += dot4(v0) + dot4(v1); }
;                 sq += __shfl_xor(sq, 16); sq += __shfl_xor(sq, 32);
;                 if (fq == 0) ss_add(ssout + row, sq); }
.LBB0_1310:
	s_or_b64 exec, exec, s[48:49]
	v_or_b32_e32 v96, 32, v146
	s_waitcnt lgkmcnt(0)
	v_ashrrev_i32_e32 v97, 31, v96
	v_lshlrev_b64 v[98:99], 11, v[96:97]
	v_lshl_add_u64 v[106:107], v[98:99], 0, v[144:145]
	v_lshl_add_u64 v[108:109], v[106:107], 2, s[28:29]
	global_load_dwordx4 v[98:101], v[108:109], off
	global_load_dwordx4 v[102:105], v[108:109], off offset:16
	global_load_dwordx4 v[176:179], v[108:109], off offset:512
	global_load_dwordx4 v[180:183], v[108:109], off offset:528
	v_lshl_add_u64 v[106:107], v[106:107], 1, s[46:47]
	s_waitcnt vmcnt(3)
	v_pk_add_f32 v[94:95], v[94:95], v[100:101]
	v_pk_add_f32 v[92:93], v[92:93], v[98:99]
	s_waitcnt vmcnt(2)
	v_pk_add_f32 v[90:91], v[90:91], v[104:105]
	v_pk_add_f32 v[88:89], v[88:89], v[102:103]
	v_cvt_pk_bf16_f32 v98, v92, v93
	v_cvt_pk_bf16_f32 v99, v94, v95
	v_cvt_pk_bf16_f32 v100, v88, v89
	v_cvt_pk_bf16_f32 v101, v90, v91
	global_store_dwordx4 v[108:109], v[92:95], off
	global_store_dwordx4 v[108:109], v[88:91], off offset:16
	global_store_dwordx4 v[106:107], v[98:101], off
	s_nop 1
	v_mul_f32_e32 v93, v93, v93
	v_mul_f32_e32 v95, v95, v95
	v_mul_f32_e32 v89, v89, v89
	v_mul_f32_e32 v91, v91, v91
	v_fmac_f32_e32 v93, v92, v92
	v_fmac_f32_e32 v95, v94, v94
	v_fmac_f32_e32 v89, v88, v88
	v_fmac_f32_e32 v91, v90, v90
	v_add_f32_e32 v88, v93, v95
	v_add_f32_e32 v89, v89, v91
	v_add_f32_e32 v92, v88, v89
	s_waitcnt vmcnt(4)
	v_pk_add_f32 v[86:87], v[86:87], v[178:179]
	v_pk_add_f32 v[84:85], v[84:85], v[176:177]
	s_waitcnt vmcnt(3)
	v_pk_add_f32 v[90:91], v[82:83], v[182:183]
	v_pk_add_f32 v[88:89], v[80:81], v[180:181]
	v_mul_f32_e32 v80, v85, v85
	v_mul_f32_e32 v81, v87, v87
	v_mul_f32_e32 v82, v89, v89
	v_mul_f32_e32 v83, v91, v91
	v_fmac_f32_e32 v80, v84, v84
	v_fmac_f32_e32 v81, v86, v86
	v_fmac_f32_e32 v82, v88, v88
	v_fmac_f32_e32 v83, v90, v90
	v_add_f32_e32 v80, v80, v81
	v_add_f32_e32 v81, v82, v83
	v_add_f32_e32 v80, v80, v81
	v_add_f32_e32 v80, v92, v80
	ds_bpermute_b32 v81, v120, v80
	global_store_dwordx4 v[108:109], v[84:87], off offset:512
	global_store_dwordx4 v[108:109], v[88:91], off offset:528
	v_cvt_pk_bf16_f32 v82, v84, v85
	v_cvt_pk_bf16_f32 v83, v86, v87
	v_cvt_pk_bf16_f32 v84, v88, v89
	s_waitcnt lgkmcnt(0)
	v_add_f32_e32 v80, v80, v81
	ds_bpermute_b32 v81, v114, v80
	v_cvt_pk_bf16_f32 v85, v90, v91
	global_store_dwordx4 v[106:107], v[82:85], off offset:256
	s_and_saveexec_b64 s[48:49], s[2:3]
	s_cbranch_execz .LBB0_1312
	s_waitcnt lgkmcnt(0)
	v_add_f32_e32 v80, v80, v81
	v_mul_f32_e32 v80, 0x4b800000, v80
	v_trunc_f32_e32 v80, v80
	v_mul_f32_e32 v81, 0x2f800000, v80
	v_floor_f32_e32 v81, v81
	v_fmac_f32_e32 v80, 0xcf800000, v81
	v_cvt_u32_f32_e32 v80, v80
	v_cvt_u32_f32_e32 v81, v81
	v_lshl_add_u64 v[82:83], v[96:97], 3, s[6:7]
	global_atomic_add_x2 v[82:83], v[80:81], off
.LBB0_1312:
	s_or_b64 exec, exec, s[48:49]
	v_or_b32_e32 v80, 48, v146
	s_waitcnt lgkmcnt(0)
	v_ashrrev_i32_e32 v81, 31, v80
	v_lshlrev_b64 v[82:83], 11, v[80:81]
	v_lshl_add_u64 v[90:91], v[82:83], 0, v[144:145]
	v_lshl_add_u64 v[92:93], v[90:91], 2, s[28:29]
	global_load_dwordx4 v[82:85], v[92:93], off
	global_load_dwordx4 v[86:89], v[92:93], off offset:16
	global_load_dwordx4 v[176:179], v[92:93], off offset:512
	global_load_dwordx4 v[180:183], v[92:93], off offset:528
	v_lshl_add_u64 v[90:91], v[90:91], 1, s[46:47]
	s_waitcnt vmcnt(3)
	v_pk_add_f32 v[78:79], v[78:79], v[84:85]
	v_pk_add_f32 v[76:77], v[76:77], v[82:83]
	s_waitcnt vmcnt(2)
	v_pk_add_f32 v[74:75], v[74:75], v[88:89]
	v_pk_add_f32 v[72:73], v[72:73], v[86:87]
	v_cvt_pk_bf16_f32 v82, v76, v77
	v_cvt_pk_bf16_f32 v83, v78, v79
	v_cvt_pk_bf16_f32 v84, v72, v73
	v_cvt_pk_bf16_f32 v85, v74, v75
	global_store_dwordx4 v[92:93], v[76:79], off
	global_store_dwordx4 v[92:93], v[72:75], off offset:16
	global_store_dwordx4 v[90:91], v[82:85], off
	s_nop 1
	v_mul_f32_e32 v77, v77, v77
	v_mul_f32_e32 v79, v79, v79
	v_mul_f32_e32 v73, v73, v73
	v_mul_f32_e32 v75, v75, v75
	v_fmac_f32_e32 v77, v76, v76
	v_fmac_f32_e32 v79, v78, v78
	v_fmac_f32_e32 v73, v72, v72
	v_fmac_f32_e32 v75, v74, v74
	v_add_f32_e32 v72, v77, v79
	v_add_f32_e32 v73, v73, v75
	v_add_f32_e32 v76, v72, v73
	s_waitcnt vmcnt(4)
	v_pk_add_f32 v[70:71], v[70:71], v[178:179]
	v_pk_add_f32 v[68:69], v[68:69], v[176:177]
	s_waitcnt vmcnt(3)
	v_pk_add_f32 v[74:75], v[66:67], v[182:183]
	v_pk_add_f32 v[72:73], v[64:65], v[180:181]
	v_mul_f32_e32 v64, v69, v69
	v_mul_f32_e32 v65, v71, v71
	v_mul_f32_e32 v66, v73, v73
	v_mul_f32_e32 v67, v75, v75
	v_fmac_f32_e32 v64, v68, v68
	v_fmac_f32_e32 v65, v70, v70
	v_fmac_f32_e32 v66, v72, v72
	v_fmac_f32_e32 v67, v74, v74
	v_add_f32_e32 v64, v64, v65
	v_add_f32_e32 v65, v66, v67
	v_add_f32_e32 v64, v64, v65
	v_add_f32_e32 v64, v76, v64
	ds_bpermute_b32 v65, v120, v64
	global_store_dwordx4 v[92:93], v[68:71], off offset:512
	global_store_dwordx4 v[92:93], v[72:75], off offset:528
	v_cvt_pk_bf16_f32 v66, v68, v69
	v_cvt_pk_bf16_f32 v67, v70, v71
	v_cvt_pk_bf16_f32 v68, v72, v73
	s_waitcnt lgkmcnt(0)
	v_add_f32_e32 v64, v64, v65
	ds_bpermute_b32 v65, v114, v64
	v_cvt_pk_bf16_f32 v69, v74, v75
	global_store_dwordx4 v[90:91], v[66:69], off offset:256
	s_and_saveexec_b64 s[48:49], s[2:3]
	s_cbranch_execz .LBB0_1314
	s_waitcnt lgkmcnt(0)
	v_add_f32_e32 v64, v64, v65
	v_mul_f32_e32 v64, 0x4b800000, v64
	v_trunc_f32_e32 v64, v64
	v_mul_f32_e32 v65, 0x2f800000, v64
	v_floor_f32_e32 v65, v65
	v_fmac_f32_e32 v64, 0xcf800000, v65
	v_cvt_u32_f32_e32 v64, v64
	v_cvt_u32_f32_e32 v65, v65
	v_lshl_add_u64 v[66:67], v[80:81], 3, s[6:7]
	global_atomic_add_x2 v[66:67], v[64:65], off
; __device__ __forceinline__ u32x4 pack8(const f32x4 a, const f32x4 b) { u32x4 w; w.x = cvt_pk_bf16(a[0], a[1]); w.y = cvt_pk_bf16(a[2], a[3]); w.z = cvt_pk_bf16(b[0], b[1]); w.w = cvt_pk_bf16(b[2], b[3]); return w; }
; __device__ __forceinline__ void ss_add(ssq_t* p, float sq) { __hip_atomic_fetch_add(p, (ssq_t)(sq * 16777216.0f), __ATOMIC_RELAXED, __HIP_MEMORY_SCOPE_AGENT); }
; __device__ __forceinline__ float dot4(const f32x4 a) { return (a[0] * a[0] + a[1] * a[1]) + (a[2] * a[2] + a[3] * a[3]); }
;     __device__ __forceinline__ void operator()(const f32x4 (&acc)[2][2][4][2], const Unit& u, int wr, int wc, int fr, int fq) const {
;     ...
;         for (int ai = 0; ai < 2; ++ai)
; #pragma unroll
;             for (int m = 0; m < 4; ++m) { const int row = row0 + ai * HALF + m * 16; const size_t off = (size_t)row * 2048 + col0; float sq = 0.f;
; #pragma unroll
;                 for (int bj = 0; bj < 2; ++bj) {
;                     const f32x4 x0 = __builtin_nontemporal_load((const f32x4*)(xin + off + bj * HALF)), x1 = __builtin_nontemporal_load((const f32x4*)(xin + off + bj * HALF + 4));
;                     const f32x4 v0 = x0 + acc[ai][bj][m][0] * alpha, v1 = x1 + acc[ai][bj][m][1] * alpha;
;                     __builtin_nontemporal_store(v0, (f32x4*)(xout + off + bj * HALF)); __builtin_nontemporal_store(v1, (f32x4*)(xout + off + bj * HALF + 4));
;                     if (WRITE_XB) *(u32x4*)(xb + off + bj * HALF) = pack8(v0, v1); sq += dot4(v0) + dot4(v1); }
;                 sq += __shfl_xor(sq, 16); sq += __shfl_xor(sq, 32);
;                 if (fq == 0) ss_add(ssout + row, sq); }
.LBB0_1314:
	s_or_b64 exec, exec, s[48:49]
	v_add_u32_e32 v64, 0x80, v146
	s_waitcnt lgkmcnt(0)
	v_ashrrev_i32_e32 v65, 31, v64
	v_lshlrev_b64 v[66:67], 11, v[64:65]
	v_lshl_add_u64 v[74:75], v[66:67], 0, v[144:145]
	v_lshl_add_u64 v[76:77], v[74:75], 2, s[28:29]
	global_load_dwordx4 v[66:69], v[76:77], off
	global_load_dwordx4 v[70:73], v[76:77], off offset:16
	global_load_dwordx4 v[176:179], v[76:77], off offset:512
	global_load_dwordx4 v[180:183], v[76:77], off offset:528
	v_lshl_add_u64 v[74:75], v[74:75], 1, s[46:47]
	s_waitcnt vmcnt(3)
	v_pk_add_f32 v[62:63], v[62:63], v[68:69]
	v_pk_add_f32 v[60:61], v[60:61], v[66:67]
	s_waitcnt vmcnt(2)
	v_pk_add_f32 v[58:59], v[58:59], v[72:73]
	v_pk_add_f32 v[56:57], v[56:57], v[70:71]
	v_cvt_pk_bf16_f32 v66, v60, v61
	v_cvt_pk_bf16_f32 v67, v62, v63
	v_cvt_pk_bf16_f32 v68, v56, v57
	v_cvt_pk_bf16_f32 v69, v58, v59
	global_store_dwordx4 v[76:77], v[60:63], off
	global_store_dwordx4 v[76:77], v[56:59], off offset:16
	global_store_dwordx4 v[74:75], v[66:69], off
	s_nop 1
	v_mul_f32_e32 v61, v61, v61
	v_mul_f32_e32 v63, v63, v63
	v_mul_f32_e32 v57, v57, v57
	v_mul_f32_e32 v59, v59, v59
	v_fmac_f32_e32 v61, v60, v60
	v_fmac_f32_e32 v63, v62, v62
	v_fmac_f32_e32 v57, v56, v56
	v_fmac_f32_e32 v59, v58, v58
	v_add_f32_e32 v56, v61, v63
	v_add_f32_e32 v57, v57, v59
	v_add_f32_e32 v60, v56, v57
	s_waitcnt vmcnt(4)
	v_pk_add_f32 v[54:55], v[54:55], v[178:179]
	v_pk_add_f32 v[52:53], v[52:53], v[176:177]
	s_waitcnt vmcnt(3)
	v_pk_add_f32 v[58:59], v[50:51], v[182:183]
	v_pk_add_f32 v[56:57], v[48:49], v[180:181]
	v_mul_f32_e32 v48, v53, v53
	v_mul_f32_e32 v49, v55, v55
	v_mul_f32_e32 v50, v57, v57
	v_mul_f32_e32 v51, v59, v59
	v_fmac_f32_e32 v48, v52, v52
	v_fmac_f32_e32 v49, v54, v54
	v_fmac_f32_e32 v50, v56, v56
	v_fmac_f32_e32 v51, v58, v58
	v_add_f32_e32 v48, v48, v49
	v_add_f32_e32 v49, v50, v51
	v_add_f32_e32 v48, v48, v49
	v_add_f32_e32 v48, v60, v48
	ds_bpermute_b32 v49, v120, v48
	global_store_dwordx4 v[76:77], v[52:55], off offset:512
	global_store_dwordx4 v[76:77], v[56:59], off offset:528
	v_cvt_pk_bf16_f32 v50, v52, v53
	v_cvt_pk_bf16_f32 v51, v54, v55
	v_cvt_pk_bf16_f32 v52, v56, v57
	s_waitcnt lgkmcnt(0)
	v_add_f32_e32 v48, v48, v49
	ds_bpermute_b32 v49, v114, v48
	v_cvt_pk_bf16_f32 v53, v58, v59
	global_store_dwordx4 v[74:75], v[50:53], off offset:256
	s_and_saveexec_b64 s[48:49], s[2:3]
	s_cbranch_execz .LBB0_1316
	s_waitcnt lgkmcnt(0)
	v_add_f32_e32 v48, v48, v49
	v_mul_f32_e32 v48, 0x4b800000, v48
	v_trunc_f32_e32 v48, v48
	v_mul_f32_e32 v49, 0x2f800000, v48
	v_floor_f32_e32 v49, v49
	v_fmac_f32_e32 v48, 0xcf800000, v49
	v_cvt_u32_f32_e32 v48, v48
	v_cvt_u32_f32_e32 v49, v49
	v_lshl_add_u64 v[50:51], v[64:65], 3, s[6:7]
	global_atomic_add_x2 v[50:51], v[48:49], off
.LBB0_1316:
	s_or_b64 exec, exec, s[48:49]
	v_add_u32_e32 v48, 0x90, v146
	s_waitcnt lgkmcnt(0)
	v_ashrrev_i32_e32 v49, 31, v48
	v_lshlrev_b64 v[50:51], 11, v[48:49]
	v_lshl_add_u64 v[58:59], v[50:51], 0, v[144:145]
	v_lshl_add_u64 v[60:61], v[58:59], 2, s[28:29]
	global_load_dwordx4 v[50:53], v[60:61], off
	global_load_dwordx4 v[54:57], v[60:61], off offset:16
	global_load_dwordx4 v[176:179], v[60:61], off offset:512
	global_load_dwordx4 v[180:183], v[60:61], off offset:528
	v_lshl_add_u64 v[58:59], v[58:59], 1, s[46:47]
	s_waitcnt vmcnt(3)
	v_pk_add_f32 v[46:47], v[46:47], v[52:53]
	v_pk_add_f32 v[44:45], v[44:45], v[50:51]
	s_waitcnt vmcnt(2)
	v_pk_add_f32 v[42:43], v[42:43], v[56:57]
	v_pk_add_f32 v[40:41], v[40:41], v[54:55]
	v_cvt_pk_bf16_f32 v50, v44, v45
	v_cvt_pk_bf16_f32 v51, v46, v47
	v_cvt_pk_bf16_f32 v52, v40, v41
	v_cvt_pk_bf16_f32 v53, v42, v43
	global_store_dwordx4 v[60:61], v[44:47], off
	global_store_dwordx4 v[60:61], v[40:43], off offset:16
	global_store_dwordx4 v[58:59], v[50:53], off
	s_nop 1
	v_mul_f32_e32 v45, v45, v45
	v_mul_f32_e32 v47, v47, v47
	v_mul_f32_e32 v41, v41, v41
	v_mul_f32_e32 v43, v43, v43
	v_fmac_f32_e32 v45, v44, v44
	v_fmac_f32_e32 v47, v46, v46
	v_fmac_f32_e32 v41, v40, v40
	v_fmac_f32_e32 v43, v42, v42
	v_add_f32_e32 v40, v45, v47
	v_add_f32_e32 v41, v41, v43
	v_add_f32_e32 v44, v40, v41
	s_waitcnt vmcnt(4)
	v_pk_add_f32 v[38:39], v[38:39], v[178:179]
	v_pk_add_f32 v[36:37], v[36:37], v[176:177]
	s_waitcnt vmcnt(3)
	v_pk_add_f32 v[42:43], v[34:35], v[182:183]
	v_pk_add_f32 v[40:41], v[32:33], v[180:181]
	v_mul_f32_e32 v32, v37, v37
	v_mul_f32_e32 v33, v39, v39
	v_mul_f32_e32 v34, v41, v41
	v_mul_f32_e32 v35, v43, v43
	v_fmac_f32_e32 v32, v36, v36
	v_fmac_f32_e32 v33, v38, v38
	v_fmac_f32_e32 v34, v40, v40
	v_fmac_f32_e32 v35, v42, v42
	v_add_f32_e32 v32, v32, v33
	v_add_f32_e32 v33, v34, v35
	v_add_f32_e32 v32, v32, v33
	v_add_f32_e32 v32, v44, v32
	ds_bpermute_b32 v33, v120, v32
	global_store_dwordx4 v[60:61], v[36:39], off offset:512
	global_store_dwordx4 v[60:61], v[40:43], off offset:528
	v_cvt_pk_bf16_f32 v34, v36, v37
	v_cvt_pk_bf16_f32 v35, v38, v39
	v_cvt_pk_bf16_f32 v36, v40, v41
	s_waitcnt lgkmcnt(0)
	v_add_f32_e32 v32, v32, v33
	ds_bpermute_b32 v33, v114, v32
	v_cvt_pk_bf16_f32 v37, v42, v43
	global_store_dwordx4 v[58:59], v[34:37], off offset:256
	s_and_saveexec_b64 s[48:49], s[2:3]
	s_cbranch_execz .LBB0_1318
	s_waitcnt lgkmcnt(0)
	v_add_f32_e32 v32, v32, v33
	v_mul_f32_e32 v32, 0x4b800000, v32
	v_trunc_f32_e32 v32, v32
	v_mul_f32_e32 v33, 0x2f800000, v32
	v_floor_f32_e32 v33, v33
	v_fmac_f32_e32 v32, 0xcf800000, v33
	v_cvt_u32_f32_e32 v32, v32
	v_cvt_u32_f32_e32 v33, v33
	v_lshl_add_u64 v[34:35], v[48:49], 3, s[6:7]
	global_atomic_add_x2 v[34:35], v[32:33], off
; __device__ __forceinline__ u32x4 pack8(const f32x4 a, const f32x4 b) { u32x4 w; w.x = cvt_pk_bf16(a[0], a[1]); w.y = cvt_pk_bf16(a[2], a[3]); w.z = cvt_pk_bf16(b[0], b[1]); w.w = cvt_pk_bf16(b[2], b[3]); return w; }
; __device__ __forceinline__ void ss_add(ssq_t* p, float sq) { __hip_atomic_fetch_add(p, (ssq_t)(sq * 16777216.0f), __ATOMIC_RELAXED, __HIP_MEMORY_SCOPE_AGENT); }
; __device__ __forceinline__ float dot4(const f32x4 a) { return (a[0] * a[0] + a[1] * a[1]) + (a[2] * a[2] + a[3] * a[3]); }
;     __device__ __forceinline__ void operator()(const f32x4 (&acc)[2][2][4][2], const Unit& u, int wr, int wc, int fr, int fq) const {
;     ...
;         for (int ai = 0; ai < 2; ++ai)
; #pragma unroll
;             for (int m = 0; m < 4; ++m) { const int row = row0 + ai * HALF + m * 16; const size_t off = (size_t)row * 2048 + col0; float sq = 0.f;
; #pragma unroll
;                 for (int bj = 0; bj < 2; ++bj) {
;                     const f32x4 x0 = __builtin_nontemporal_load((const f32x4*)(xin + off + bj * HALF)), x1 = __builtin_nontemporal_load((const f32x4*)(xin + off + bj * HALF + 4));
;                     const f32x4 v0 = x0 + acc[ai][bj][m][0] * alpha, v1 = x1 + acc[ai][bj][m][1] * alpha;
;                     __builtin_nontemporal_store(v0, (f32x4*)(xout + off + bj * HALF)); __builtin_nontemporal_store(v1, (f32x4*)(xout + off + bj * HALF + 4));
;                     if (WRITE_XB) *(u32x4*)(xb + off + bj * HALF) = pack8(v0, v1); sq += dot4(v0) + dot4(v1); }
;                 sq += __shfl_xor(sq, 16); sq += __shfl_xor(sq, 32);
;                 if (fq == 0) ss_add(ssout + row, sq); }
.LBB0_1318:
	s_or_b64 exec, exec, s[48:49]
	v_add_u32_e32 v32, 0xa0, v146
	s_waitcnt lgkmcnt(0)
	v_ashrrev_i32_e32 v33, 31, v32
	v_lshlrev_b64 v[34:35], 11, v[32:33]
	v_lshl_add_u64 v[42:43], v[34:35], 0, v[144:145]
	v_lshl_add_u64 v[44:45], v[42:43], 2, s[28:29]
	global_load_dwordx4 v[34:37], v[44:45], off
	global_load_dwordx4 v[38:41], v[44:45], off offset:16
	global_load_dwordx4 v[176:179], v[44:45], off offset:512
	global_load_dwordx4 v[180:183], v[44:45], off offset:528
	v_lshl_add_u64 v[42:43], v[42:43], 1, s[46:47]
	s_waitcnt vmcnt(3)
	v_pk_add_f32 v[30:31], v[30:31], v[36:37]
	v_pk_add_f32 v[28:29], v[28:29], v[34:35]
	s_waitcnt vmcnt(2)
	v_pk_add_f32 v[26:27], v[26:27], v[40:41]
	v_pk_add_f32 v[24:25], v[24:25], v[38:39]
	v_cvt_pk_bf16_f32 v34, v28, v29
	v_cvt_pk_bf16_f32 v35, v30, v31
	v_cvt_pk_bf16_f32 v36, v24, v25
	v_cvt_pk_bf16_f32 v37, v26, v27
	global_store_dwordx4 v[44:45], v[28:31], off
	global_store_dwordx4 v[44:45], v[24:27], off offset:16
	global_store_dwordx4 v[42:43], v[34:37], off
	s_nop 1
	v_mul_f32_e32 v29, v29, v29
	v_mul_f32_e32 v31, v31, v31
	v_mul_f32_e32 v25, v25, v25
	v_mul_f32_e32 v27, v27, v27
	v_fmac_f32_e32 v29, v28, v28
	v_fmac_f32_e32 v31, v30, v30
	v_fmac_f32_e32 v25, v24, v24
	v_fmac_f32_e32 v27, v26, v26
	v_add_f32_e32 v24, v29, v31
	v_add_f32_e32 v25, v25, v27
	v_add_f32_e32 v28, v24, v25
	s_waitcnt vmcnt(4)
	v_pk_add_f32 v[22:23], v[22:23], v[178:179]
	v_pk_add_f32 v[20:21], v[20:21], v[176:177]
	s_waitcnt vmcnt(3)
	v_pk_add_f32 v[26:27], v[18:19], v[182:183]
	v_pk_add_f32 v[24:25], v[16:17], v[180:181]
	v_mul_f32_e32 v16, v21, v21
	v_mul_f32_e32 v17, v23, v23
	v_mul_f32_e32 v18, v25, v25
	v_mul_f32_e32 v19, v27, v27
	v_fmac_f32_e32 v16, v20, v20
	v_fmac_f32_e32 v17, v22, v22
	v_fmac_f32_e32 v18, v24, v24
	v_fmac_f32_e32 v19, v26, v26
	v_add_f32_e32 v16, v16, v17
	v_add_f32_e32 v17, v18, v19
	v_add_f32_e32 v16, v16, v17
	v_add_f32_e32 v16, v28, v16
	ds_bpermute_b32 v17, v120, v16
	global_store_dwordx4 v[44:45], v[20:23], off offset:512
	global_store_dwordx4 v[44:45], v[24:27], off offset:528
	v_cvt_pk_bf16_f32 v18, v20, v21
	v_cvt_pk_bf16_f32 v19, v22, v23
	v_cvt_pk_bf16_f32 v20, v24, v25
	s_waitcnt lgkmcnt(0)
	v_add_f32_e32 v16, v16, v17
	ds_bpermute_b32 v17, v114, v16
	v_cvt_pk_bf16_f32 v21, v26, v27
	global_store_dwordx4 v[42:43], v[18:21], off offset:256
	s_and_saveexec_b64 s[48:49], s[2:3]
	s_cbranch_execz .LBB0_1320
	s_waitcnt lgkmcnt(0)
	v_add_f32_e32 v16, v16, v17
	v_mul_f32_e32 v16, 0x4b800000, v16
	v_trunc_f32_e32 v16, v16
	v_mul_f32_e32 v17, 0x2f800000, v16
	v_floor_f32_e32 v17, v17
	v_fmac_f32_e32 v16, 0xcf800000, v17
	v_cvt_u32_f32_e32 v16, v16
	v_cvt_u32_f32_e32 v17, v17
	v_lshl_add_u64 v[18:19], v[32:33], 3, s[6:7]
	global_atomic_add_x2 v[18:19], v[16:17], off
.LBB0_1320:
	s_or_b64 exec, exec, s[48:49]
	v_add_u32_e32 v16, 0xb0, v146
	s_waitcnt lgkmcnt(0)
	v_ashrrev_i32_e32 v17, 31, v16
	v_lshlrev_b64 v[18:19], 11, v[16:17]
	v_lshl_add_u64 v[26:27], v[18:19], 0, v[144:145]
	v_lshl_add_u64 v[28:29], v[26:27], 2, s[28:29]
	global_load_dwordx4 v[18:21], v[28:29], off
	global_load_dwordx4 v[22:25], v[28:29], off offset:16
	global_load_dwordx4 v[176:179], v[28:29], off offset:512
	global_load_dwordx4 v[180:183], v[28:29], off offset:528
	v_lshl_add_u64 v[26:27], v[26:27], 1, s[46:47]
	s_waitcnt vmcnt(3)
	v_pk_add_f32 v[14:15], v[14:15], v[20:21]
	v_pk_add_f32 v[12:13], v[12:13], v[18:19]
	s_waitcnt vmcnt(2)
	v_pk_add_f32 v[10:11], v[10:11], v[24:25]
	v_pk_add_f32 v[8:9], v[8:9], v[22:23]
	v_cvt_pk_bf16_f32 v18, v12, v13
	v_cvt_pk_bf16_f32 v19, v14, v15
	v_cvt_pk_bf16_f32 v20, v8, v9
	v_cvt_pk_bf16_f32 v21, v10, v11
	global_store_dwordx4 v[28:29], v[12:15], off
	global_store_dwordx4 v[28:29], v[8:11], off offset:16
	global_store_dwordx4 v[26:27], v[18:21], off
	s_nop 1
	v_mul_f32_e32 v13, v13, v13
	v_mul_f32_e32 v15, v15, v15
	v_mul_f32_e32 v9, v9, v9
	v_mul_f32_e32 v11, v11, v11
	v_fmac_f32_e32 v13, v12, v12
	v_fmac_f32_e32 v15, v14, v14
	v_fmac_f32_e32 v9, v8, v8
	v_fmac_f32_e32 v11, v10, v10
	v_add_f32_e32 v8, v13, v15
	v_add_f32_e32 v9, v9, v11
	v_add_f32_e32 v12, v8, v9
	s_waitcnt vmcnt(4)
	v_pk_add_f32 v[6:7], v[6:7], v[178:179]
	v_pk_add_f32 v[4:5], v[4:5], v[176:177]
	s_waitcnt vmcnt(3)
	v_pk_add_f32 v[10:11], v[2:3], v[182:183]
	v_pk_add_f32 v[8:9], v[0:1], v[180:181]
	v_mul_f32_e32 v0, v5, v5
	v_mul_f32_e32 v1, v7, v7
	v_mul_f32_e32 v2, v9, v9
	v_mul_f32_e32 v3, v11, v11
	v_fmac_f32_e32 v0, v4, v4
	v_fmac_f32_e32 v1, v6, v6
	v_fmac_f32_e32 v2, v8, v8
	v_fmac_f32_e32 v3, v10, v10
	v_add_f32_e32 v0, v0, v1
	v_add_f32_e32 v1, v2, v3
	v_add_f32_e32 v0, v0, v1
	v_add_f32_e32 v0, v12, v0
	ds_bpermute_b32 v1, v120, v0
	global_store_dwordx4 v[28:29], v[4:7], off offset:512
	global_store_dwordx4 v[28:29], v[8:11], off offset:528
	v_cvt_pk_bf16_f32 v2, v4, v5
	v_cvt_pk_bf16_f32 v3, v6, v7
	v_cvt_pk_bf16_f32 v4, v8, v9
	s_waitcnt lgkmcnt(0)
	v_add_f32_e32 v0, v0, v1
	ds_bpermute_b32 v1, v114, v0
	v_cvt_pk_bf16_f32 v5, v10, v11
	global_store_dwordx4 v[26:27], v[2:5], off offset:256
	s_and_saveexec_b64 s[48:49], s[2:3]
	s_cbranch_execz .LBB0_1322
	s_waitcnt lgkmcnt(0)
	v_add_f32_e32 v0, v0, v1
	v_mul_f32_e32 v0, 0x4b800000, v0
	v_trunc_f32_e32 v0, v0
	v_mul_f32_e32 v1, 0x2f800000, v0
	v_floor_f32_e32 v1, v1
	v_fmac_f32_e32 v0, 0xcf800000, v1
	v_cvt_u32_f32_e32 v0, v0
	v_cvt_u32_f32_e32 v1, v1
	v_lshl_add_u64 v[2:3], v[16:17], 3, s[6:7]
	global_atomic_add_x2 v[2:3], v[0:1], off

; __device__ __forceinline__ u32x4 pack8(const f32x4 a, const f32x4 b) { u32x4 w; w.x = cvt_pk_bf16(a[0], a[1]); w.y = cvt_pk_bf16(a[2], a[3]); w.z = cvt_pk_bf16(b[0], b[1]); w.w = cvt_pk_bf16(b[2], b[3]); return w; }
; __device__ __forceinline__ void ss_add(ssq_t* p, float sq) { __hip_atomic_fetch_add(p, (ssq_t)(sq * 16777216.0f), __ATOMIC_RELAXED, __HIP_MEMORY_SCOPE_AGENT); }
; __device__ __forceinline__ float dot4(const f32x4 a) { return (a[0] * a[0] + a[1] * a[1]) + (a[2] * a[2] + a[3] * a[3]); }
;     __device__ __forceinline__ void operator()(const f32x4 (&acc)[2][2][4][2], const Unit& u, int wr, int wc, int fr, int fq) const {
;     ...
;             for (int m = 0; m < 4; ++m) { const int row = row0 + ai * HALF + m * 16; const size_t off = (size_t)row * 2048 + col0; float sq = 0.f;
; #pragma unroll
;                 for (int bj = 0; bj < 2; ++bj) {
;                     const f32x4 x0 = __builtin_nontemporal_load((const f32x4*)(xin + off + bj * HALF)), x1 = __builtin_nontemporal_load((const f32x4*)(xin + off + bj * HALF + 4));
;                     const f32x4 v0 = x0 + acc[ai][bj][m][0] * alpha, v1 = x1 + acc[ai][bj][m][1] * alpha;
;                     __builtin_nontemporal_store(v0, (f32x4*)(xout + off + bj * HALF)); __builtin_nontemporal_store(v1, (f32x4*)(xout + off + bj * HALF + 4));
;                     if (WRITE_XB) *(u32x4*)(xb + off + bj * HALF) = pack8(v0, v1); sq += dot4(v0) + dot4(v1); }
;                 sq += __shfl_xor(sq, 16); sq += __shfl_xor(sq, 32);
;                 if (fq == 0) ss_add(ssout + row, sq); }
.LBB0_1478:
	v_lshl_add_u32 v146, s48, 8, v148
	v_lshl_add_u32 v144, s49, 8, v150
	v_ashrrev_i32_e32 v147, 31, v146
	v_ashrrev_i32_e32 v145, 31, v144
	v_lshlrev_b64 v[156:157], 11, v[146:147]
	v_lshl_add_u64 v[164:165], v[156:157], 0, v[144:145]
	v_lshl_add_u64 v[168:169], v[164:165], 2, s[28:29]
	global_load_dwordx4 v[156:159], v[168:169], off
	global_load_dwordx4 v[160:163], v[168:169], off offset:16
	global_load_dwordx4 v[176:179], v[168:169], off offset:512
	global_load_dwordx4 v[180:183], v[168:169], off offset:528
	v_lshl_add_u64 v[170:171], v[164:165], 1, s[46:47]
	s_waitcnt vmcnt(2)
	v_pk_fma_f32 v[126:127], v[126:127], 0.5, v[158:159] op_sel_hi:[1,0,1]
	v_pk_fma_f32 v[124:125], v[124:125], 0.5, v[156:157] op_sel_hi:[1,0,1]
	v_pk_fma_f32 v[158:159], v[122:123], 0.5, v[162:163] op_sel_hi:[1,0,1]
	v_pk_fma_f32 v[156:157], v[120:121], 0.5, v[160:161] op_sel_hi:[1,0,1]
	v_cvt_pk_bf16_f32 v120, v124, v125
	v_cvt_pk_bf16_f32 v121, v126, v127
	v_cvt_pk_bf16_f32 v122, v156, v157
	v_cvt_pk_bf16_f32 v123, v158, v159
	global_store_dwordx4 v[168:169], v[124:127], off
	global_store_dwordx4 v[168:169], v[156:159], off offset:16
	global_store_dwordx4 v[170:171], v[120:123], off
	s_nop 1
	v_and_b32_e32 v121, 64, v154
	v_xor_b32_e32 v120, 16, v154
	v_add_u32_e32 v121, 64, v121
	v_xor_b32_e32 v122, 32, v154
	v_cmp_lt_i32_e32 vcc, v120, v121
	v_mul_f32_e32 v123, v127, v127
	v_mul_f32_e32 v127, v159, v159
	v_cndmask_b32_e32 v120, v154, v120, vcc
	v_cmp_lt_i32_e32 vcc, v122, v121
	v_fmac_f32_e32 v123, v126, v126
	v_fmac_f32_e32 v127, v158, v158
	v_cndmask_b32_e32 v121, v154, v122, vcc
	v_mul_f32_e32 v122, v125, v125
	v_mul_f32_e32 v125, v157, v157
	v_fmac_f32_e32 v122, v124, v124
	v_fmac_f32_e32 v125, v156, v156
	v_add_f32_e32 v122, v122, v123
	v_add_f32_e32 v123, v125, v127
	v_add_f32_e32 v126, v122, v123
	v_lshlrev_b32_e32 v120, 2, v120
	s_waitcnt vmcnt(4)
	v_pk_fma_f32 v[118:119], v[118:119], 0.5, v[178:179] op_sel_hi:[1,0,1]
	v_pk_fma_f32 v[116:117], v[116:117], 0.5, v[176:177] op_sel_hi:[1,0,1]
	s_waitcnt vmcnt(3)
	v_pk_fma_f32 v[124:125], v[114:115], 0.5, v[182:183] op_sel_hi:[1,0,1]
	v_pk_fma_f32 v[122:123], v[112:113], 0.5, v[180:181] op_sel_hi:[1,0,1]
	v_mul_f32_e32 v112, v117, v117
	v_mul_f32_e32 v113, v119, v119
	v_mul_f32_e32 v114, v123, v123
	v_mul_f32_e32 v115, v125, v125
	v_fmac_f32_e32 v112, v116, v116
	v_fmac_f32_e32 v113, v118, v118
	v_fmac_f32_e32 v114, v122, v122
	v_fmac_f32_e32 v115, v124, v124
	v_add_f32_e32 v112, v112, v113
	v_add_f32_e32 v113, v114, v115
	v_add_f32_e32 v112, v112, v113
	v_add_f32_e32 v112, v126, v112
	ds_bpermute_b32 v113, v120, v112
	v_lshlrev_b32_e32 v114, 2, v121
	global_store_dwordx4 v[168:169], v[116:119], off offset:512
	global_store_dwordx4 v[168:169], v[122:125], off offset:528
	s_waitcnt lgkmcnt(0)
	v_add_f32_e32 v112, v112, v113
	ds_bpermute_b32 v113, v114, v112
	v_cvt_pk_bf16_f32 v116, v116, v117
	v_cvt_pk_bf16_f32 v117, v118, v119
	v_cvt_pk_bf16_f32 v118, v122, v123
	v_cvt_pk_bf16_f32 v119, v124, v125
	global_store_dwordx4 v[170:171], v[116:119], off offset:256
	s_and_saveexec_b64 s[48:49], s[2:3]
	s_cbranch_execz .LBB0_1480
	s_waitcnt lgkmcnt(0)
	v_add_f32_e32 v112, v112, v113
	v_mul_f32_e32 v112, 0x4b800000, v112
	v_trunc_f32_e32 v112, v112
	v_mul_f32_e32 v113, 0x2f800000, v112
	v_floor_f32_e32 v113, v113
	v_fmac_f32_e32 v112, 0xcf800000, v113
	v_cvt_u32_f32_e32 v112, v112
	v_cvt_u32_f32_e32 v113, v113
	v_lshl_add_u64 v[116:117], v[146:147], 3, s[18:19]
	global_atomic_add_x2 v[116:117], v[112:113], off
.LBB0_1480:
	s_or_b64 exec, exec, s[48:49]
	v_or_b32_e32 v112, 16, v146
	s_waitcnt lgkmcnt(0)
	v_ashrrev_i32_e32 v113, 31, v112
	v_lshlrev_b64 v[116:117], 11, v[112:113]
	v_lshl_add_u64 v[126:127], v[116:117], 0, v[144:145]
	v_lshl_add_u64 v[156:157], v[126:127], 2, s[28:29]
	global_load_dwordx4 v[116:119], v[156:157], off
	global_load_dwordx4 v[122:125], v[156:157], off offset:16
	global_load_dwordx4 v[176:179], v[156:157], off offset:512
	global_load_dwordx4 v[180:183], v[156:157], off offset:528
	v_lshl_add_u64 v[126:127], v[126:127], 1, s[46:47]
	s_waitcnt vmcnt(3)
	v_pk_fma_f32 v[110:111], v[110:111], 0.5, v[118:119] op_sel_hi:[1,0,1]
	v_pk_fma_f32 v[108:109], v[108:109], 0.5, v[116:117] op_sel_hi:[1,0,1]
	s_waitcnt vmcnt(2)
	v_pk_fma_f32 v[106:107], v[106:107], 0.5, v[124:125] op_sel_hi:[1,0,1]
	v_pk_fma_f32 v[104:105], v[104:105], 0.5, v[122:123] op_sel_hi:[1,0,1]
	v_cvt_pk_bf16_f32 v116, v108, v109
	v_cvt_pk_bf16_f32 v117, v110, v111
	v_cvt_pk_bf16_f32 v118, v104, v105
	v_cvt_pk_bf16_f32 v119, v106, v107
	global_store_dwordx4 v[156:157], v[108:111], off
	global_store_dwordx4 v[156:157], v[104:107], off offset:16
	global_store_dwordx4 v[126:127], v[116:119], off
	s_nop 1
	v_mul_f32_e32 v109, v109, v109
	v_mul_f32_e32 v111, v111, v111
	v_mul_f32_e32 v105, v105, v105
	v_mul_f32_e32 v107, v107, v107
	v_fmac_f32_e32 v109, v108, v108
	v_fmac_f32_e32 v111, v110, v110
	v_fmac_f32_e32 v105, v104, v104
	v_fmac_f32_e32 v107, v106, v106
	v_add_f32_e32 v104, v109, v111
	v_add_f32_e32 v105, v105, v107
	v_add_f32_e32 v108, v104, v105
	s_waitcnt vmcnt(4)
	v_pk_fma_f32 v[102:103], v[102:103], 0.5, v[178:179] op_sel_hi:[1,0,1]
	v_pk_fma_f32 v[100:101], v[100:101], 0.5, v[176:177] op_sel_hi:[1,0,1]
	s_waitcnt vmcnt(3)
	v_pk_fma_f32 v[106:107], v[98:99], 0.5, v[182:183] op_sel_hi:[1,0,1]
	v_pk_fma_f32 v[104:105], v[96:97], 0.5, v[180:181] op_sel_hi:[1,0,1]
	v_mul_f32_e32 v96, v101, v101
	v_mul_f32_e32 v97, v103, v103
	v_mul_f32_e32 v98, v105, v105
	v_mul_f32_e32 v99, v107, v107
	v_fmac_f32_e32 v96, v100, v100
	v_fmac_f32_e32 v97, v102, v102
	v_fmac_f32_e32 v98, v104, v104
	v_fmac_f32_e32 v99, v106, v106
	v_add_f32_e32 v96, v96, v97
	v_add_f32_e32 v97, v98, v99
	v_add_f32_e32 v96, v96, v97
	v_add_f32_e32 v96, v108, v96
	ds_bpermute_b32 v97, v120, v96
	global_store_dwordx4 v[156:157], v[100:103], off offset:512
	global_store_dwordx4 v[156:157], v[104:107], off offset:528
	v_cvt_pk_bf16_f32 v98, v100, v101
	v_cvt_pk_bf16_f32 v99, v102, v103
	v_cvt_pk_bf16_f32 v100, v104, v105
	s_waitcnt lgkmcnt(0)
	v_add_f32_e32 v96, v96, v97
	ds_bpermute_b32 v97, v114, v96
	v_cvt_pk_bf16_f32 v101, v106, v107
	global_store_dwordx4 v[126:127], v[98:101], off offset:256
	s_and_saveexec_b64 s[48:49], s[2:3]
	s_cbranch_execz .LBB0_1482
	s_waitcnt lgkmcnt(0)
	v_add_f32_e32 v96, v96, v97
	v_mul_f32_e32 v96, 0x4b800000, v96
	v_trunc_f32_e32 v96, v96
	v_mul_f32_e32 v97, 0x2f800000, v96
	v_floor_f32_e32 v97, v97
	v_fmac_f32_e32 v96, 0xcf800000, v97
	v_cvt_u32_f32_e32 v96, v96
	v_cvt_u32_f32_e32 v97, v97
	v_lshl_add_u64 v[98:99], v[112:113], 3, s[18:19]
	global_atomic_add_x2 v[98:99], v[96:97], off
; __device__ __forceinline__ u32x4 pack8(const f32x4 a, const f32x4 b) { u32x4 w; w.x = cvt_pk_bf16(a[0], a[1]); w.y = cvt_pk_bf16(a[2], a[3]); w.z = cvt_pk_bf16(b[0], b[1]); w.w = cvt_pk_bf16(b[2], b[3]); return w; }
; __device__ __forceinline__ void ss_add(ssq_t* p, float sq) { __hip_atomic_fetch_add(p, (ssq_t)(sq * 16777216.0f), __ATOMIC_RELAXED, __HIP_MEMORY_SCOPE_AGENT); }
; __device__ __forceinline__ float dot4(const f32x4 a) { return (a[0] * a[0] + a[1] * a[1]) + (a[2] * a[2] + a[3] * a[3]); }
;     __device__ __forceinline__ void operator()(const f32x4 (&acc)[2][2][4][2], const Unit& u, int wr, int wc, int fr, int fq) const {
;     ...
;             for (int m = 0; m < 4; ++m) { const int row = row0 + ai * HALF + m * 16; const size_t off = (size_t)row * 2048 + col0; float sq = 0.f;
; #pragma unroll
;                 for (int bj = 0; bj < 2; ++bj) {
;                     const f32x4 x0 = __builtin_nontemporal_load((const f32x4*)(xin + off + bj * HALF)), x1 = __builtin_nontemporal_load((const f32x4*)(xin + off + bj * HALF + 4));
;                     const f32x4 v0 = x0 + acc[ai][bj][m][0] * alpha, v1 = x1 + acc[ai][bj][m][1] * alpha;
;                     __builtin_nontemporal_store(v0, (f32x4*)(xout + off + bj * HALF)); __builtin_nontemporal_store(v1, (f32x4*)(xout + off + bj * HALF + 4));
;                     if (WRITE_XB) *(u32x4*)(xb + off + bj * HALF) = pack8(v0, v1); sq += dot4(v0) + dot4(v1); }
;                 sq += __shfl_xor(sq, 16); sq += __shfl_xor(sq, 32);
;                 if (fq == 0) ss_add(ssout + row, sq); }
.LBB0_1482:
	s_or_b64 exec, exec, s[48:49]
	v_or_b32_e32 v96, 32, v146
	s_waitcnt lgkmcnt(0)
	v_ashrrev_i32_e32 v97, 31, v96
	v_lshlrev_b64 v[98:99], 11, v[96:97]
	v_lshl_add_u64 v[106:107], v[98:99], 0, v[144:145]
	v_lshl_add_u64 v[108:109], v[106:107], 2, s[28:29]
	global_load_dwordx4 v[98:101], v[108:109], off
	global_load_dwordx4 v[102:105], v[108:109], off offset:16
	global_load_dwordx4 v[176:179], v[108:109], off offset:512
	global_load_dwordx4 v[180:183], v[108:109], off offset:528
	v_lshl_add_u64 v[106:107], v[106:107], 1, s[46:47]
	s_waitcnt vmcnt(3)
	v_pk_fma_f32 v[94:95], v[94:95], 0.5, v[100:101] op_sel_hi:[1,0,1]
	v_pk_fma_f32 v[92:93], v[92:93], 0.5, v[98:99] op_sel_hi:[1,0,1]
	s_waitcnt vmcnt(2)
	v_pk_fma_f32 v[90:91], v[90:91], 0.5, v[104:105] op_sel_hi:[1,0,1]
	v_pk_fma_f32 v[88:89], v[88:89], 0.5, v[102:103] op_sel_hi:[1,0,1]
	v_cvt_pk_bf16_f32 v98, v92, v93
	v_cvt_pk_bf16_f32 v99, v94, v95
	v_cvt_pk_bf16_f32 v100, v88, v89
	v_cvt_pk_bf16_f32 v101, v90, v91
	global_store_dwordx4 v[108:109], v[92:95], off
	global_store_dwordx4 v[108:109], v[88:91], off offset:16
	global_store_dwordx4 v[106:107], v[98:101], off
	s_nop 1
	v_mul_f32_e32 v93, v93, v93
	v_mul_f32_e32 v95, v95, v95
	v_mul_f32_e32 v89, v89, v89
	v_mul_f32_e32 v91, v91, v91
	v_fmac_f32_e32 v93, v92, v92
	v_fmac_f32_e32 v95, v94, v94
	v_fmac_f32_e32 v89, v88, v88
	v_fmac_f32_e32 v91, v90, v90
	v_add_f32_e32 v88, v93, v95
	v_add_f32_e32 v89, v89, v91
	v_add_f32_e32 v92, v88, v89
	s_waitcnt vmcnt(4)
	v_pk_fma_f32 v[86:87], v[86:87], 0.5, v[178:179] op_sel_hi:[1,0,1]
	v_pk_fma_f32 v[84:85], v[84:85], 0.5, v[176:177] op_sel_hi:[1,0,1]
	s_waitcnt vmcnt(3)
	v_pk_fma_f32 v[90:91], v[82:83], 0.5, v[182:183] op_sel_hi:[1,0,1]
	v_pk_fma_f32 v[88:89], v[80:81], 0.5, v[180:181] op_sel_hi:[1,0,1]
	v_mul_f32_e32 v80, v85, v85
	v_mul_f32_e32 v81, v87, v87
	v_mul_f32_e32 v82, v89, v89
	v_mul_f32_e32 v83, v91, v91
	v_fmac_f32_e32 v80, v84, v84
	v_fmac_f32_e32 v81, v86, v86
	v_fmac_f32_e32 v82, v88, v88
	v_fmac_f32_e32 v83, v90, v90
	v_add_f32_e32 v80, v80, v81
	v_add_f32_e32 v81, v82, v83
	v_add_f32_e32 v80, v80, v81
	v_add_f32_e32 v80, v92, v80
	ds_bpermute_b32 v81, v120, v80
	global_store_dwordx4 v[108:109], v[84:87], off offset:512
	global_store_dwordx4 v[108:109], v[88:91], off offset:528
	v_cvt_pk_bf16_f32 v82, v84, v85
	v_cvt_pk_bf16_f32 v83, v86, v87
	v_cvt_pk_bf16_f32 v84, v88, v89
	s_waitcnt lgkmcnt(0)
	v_add_f32_e32 v80, v80, v81
	ds_bpermute_b32 v81, v114, v80
	v_cvt_pk_bf16_f32 v85, v90, v91
	global_store_dwordx4 v[106:107], v[82:85], off offset:256
	s_and_saveexec_b64 s[48:49], s[2:3]
	s_cbranch_execz .LBB0_1484
	s_waitcnt lgkmcnt(0)
	v_add_f32_e32 v80, v80, v81
	v_mul_f32_e32 v80, 0x4b800000, v80
	v_trunc_f32_e32 v80, v80
	v_mul_f32_e32 v81, 0x2f800000, v80
	v_floor_f32_e32 v81, v81
	v_fmac_f32_e32 v80, 0xcf800000, v81
	v_cvt_u32_f32_e32 v80, v80
	v_cvt_u32_f32_e32 v81, v81
	v_lshl_add_u64 v[82:83], v[96:97], 3, s[18:19]
	global_atomic_add_x2 v[82:83], v[80:81], off
.LBB0_1484:
	s_or_b64 exec, exec, s[48:49]
	v_or_b32_e32 v80, 48, v146
	s_waitcnt lgkmcnt(0)
	v_ashrrev_i32_e32 v81, 31, v80
	v_lshlrev_b64 v[82:83], 11, v[80:81]
	v_lshl_add_u64 v[90:91], v[82:83], 0, v[144:145]
	v_lshl_add_u64 v[92:93], v[90:91], 2, s[28:29]
	global_load_dwordx4 v[82:85], v[92:93], off
	global_load_dwordx4 v[86:89], v[92:93], off offset:16
	global_load_dwordx4 v[176:179], v[92:93], off offset:512
	global_load_dwordx4 v[180:183], v[92:93], off offset:528
	v_lshl_add_u64 v[90:91], v[90:91], 1, s[46:47]
	s_waitcnt vmcnt(3)
	v_pk_fma_f32 v[78:79], v[78:79], 0.5, v[84:85] op_sel_hi:[1,0,1]
	v_pk_fma_f32 v[76:77], v[76:77], 0.5, v[82:83] op_sel_hi:[1,0,1]
	s_waitcnt vmcnt(2)
	v_pk_fma_f32 v[74:75], v[74:75], 0.5, v[88:89] op_sel_hi:[1,0,1]
	v_pk_fma_f32 v[72:73], v[72:73], 0.5, v[86:87] op_sel_hi:[1,0,1]
	v_cvt_pk_bf16_f32 v82, v76, v77
	v_cvt_pk_bf16_f32 v83, v78, v79
	v_cvt_pk_bf16_f32 v84, v72, v73
	v_cvt_pk_bf16_f32 v85, v74, v75
	global_store_dwordx4 v[92:93], v[76:79], off
	global_store_dwordx4 v[92:93], v[72:75], off offset:16
	global_store_dwordx4 v[90:91], v[82:85], off
	s_nop 1
	v_mul_f32_e32 v77, v77, v77
	v_mul_f32_e32 v79, v79, v79
	v_mul_f32_e32 v73, v73, v73
	v_mul_f32_e32 v75, v75, v75
	v_fmac_f32_e32 v77, v76, v76
	v_fmac_f32_e32 v79, v78, v78
	v_fmac_f32_e32 v73, v72, v72
	v_fmac_f32_e32 v75, v74, v74
	v_add_f32_e32 v72, v77, v79
	v_add_f32_e32 v73, v73, v75
	v_add_f32_e32 v76, v72, v73
	s_waitcnt vmcnt(4)
	v_pk_fma_f32 v[70:71], v[70:71], 0.5, v[178:179] op_sel_hi:[1,0,1]
	v_pk_fma_f32 v[68:69], v[68:69], 0.5, v[176:177] op_sel_hi:[1,0,1]
	s_waitcnt vmcnt(3)
	v_pk_fma_f32 v[74:75], v[66:67], 0.5, v[182:183] op_sel_hi:[1,0,1]
	v_pk_fma_f32 v[72:73], v[64:65], 0.5, v[180:181] op_sel_hi:[1,0,1]
	v_mul_f32_e32 v64, v69, v69
	v_mul_f32_e32 v65, v71, v71
	v_mul_f32_e32 v66, v73, v73
	v_mul_f32_e32 v67, v75, v75
	v_fmac_f32_e32 v64, v68, v68
	v_fmac_f32_e32 v65, v70, v70
	v_fmac_f32_e32 v66, v72, v72
	v_fmac_f32_e32 v67, v74, v74
	v_add_f32_e32 v64, v64, v65
	v_add_f32_e32 v65, v66, v67
	v_add_f32_e32 v64, v64, v65
	v_add_f32_e32 v64, v76, v64
	ds_bpermute_b32 v65, v120, v64
	global_store_dwordx4 v[92:93], v[68:71], off offset:512
	global_store_dwordx4 v[92:93], v[72:75], off offset:528
	v_cvt_pk_bf16_f32 v66, v68, v69
	v_cvt_pk_bf16_f32 v67, v70, v71
	v_cvt_pk_bf16_f32 v68, v72, v73
	s_waitcnt lgkmcnt(0)
	v_add_f32_e32 v64, v64, v65
	ds_bpermute_b32 v65, v114, v64
	v_cvt_pk_bf16_f32 v69, v74, v75
	global_store_dwordx4 v[90:91], v[66:69], off offset:256
	s_and_saveexec_b64 s[48:49], s[2:3]
	s_cbranch_execz .LBB0_1486
	s_waitcnt lgkmcnt(0)
	v_add_f32_e32 v64, v64, v65
	v_mul_f32_e32 v64, 0x4b800000, v64
	v_trunc_f32_e32 v64, v64
	v_mul_f32_e32 v65, 0x2f800000, v64
	v_floor_f32_e32 v65, v65
	v_fmac_f32_e32 v64, 0xcf800000, v65
	v_cvt_u32_f32_e32 v64, v64
	v_cvt_u32_f32_e32 v65, v65
	v_lshl_add_u64 v[66:67], v[80:81], 3, s[18:19]
	global_atomic_add_x2 v[66:67], v[64:65], off
; __device__ __forceinline__ u32x4 pack8(const f32x4 a, const f32x4 b) { u32x4 w; w.x = cvt_pk_bf16(a[0], a[1]); w.y = cvt_pk_bf16(a[2], a[3]); w.z = cvt_pk_bf16(b[0], b[1]); w.w = cvt_pk_bf16(b[2], b[3]); return w; }
; __device__ __forceinline__ void ss_add(ssq_t* p, float sq) { __hip_atomic_fetch_add(p, (ssq_t)(sq * 16777216.0f), __ATOMIC_RELAXED, __HIP_MEMORY_SCOPE_AGENT); }
; __device__ __forceinline__ float dot4(const f32x4 a) { return (a[0] * a[0] + a[1] * a[1]) + (a[2] * a[2] + a[3] * a[3]); }
;     __device__ __forceinline__ void operator()(const f32x4 (&acc)[2][2][4][2], const Unit& u, int wr, int wc, int fr, int fq) const {
;     ...
;             for (int m = 0; m < 4; ++m) { const int row = row0 + ai * HALF + m * 16; const size_t off = (size_t)row * 2048 + col0; float sq = 0.f;
; #pragma unroll
;                 for (int bj = 0; bj < 2; ++bj) {
;                     const f32x4 x0 = __builtin_nontemporal_load((const f32x4*)(xin + off + bj * HALF)), x1 = __builtin_nontemporal_load((const f32x4*)(xin + off + bj * HALF + 4));
;                     const f32x4 v0 = x0 + acc[ai][bj][m][0] * alpha, v1 = x1 + acc[ai][bj][m][1] * alpha;
;                     __builtin_nontemporal_store(v0, (f32x4*)(xout + off + bj * HALF)); __builtin_nontemporal_store(v1, (f32x4*)(xout + off + bj * HALF + 4));
;                     if (WRITE_XB) *(u32x4*)(xb + off + bj * HALF) = pack8(v0, v1); sq += dot4(v0) + dot4(v1); }
;                 sq += __shfl_xor(sq, 16); sq += __shfl_xor(sq, 32);
;                 if (fq == 0) ss_add(ssout + row, sq); }
.LBB0_1486:
	s_or_b64 exec, exec, s[48:49]
	v_add_u32_e32 v64, 0x80, v146
	s_waitcnt lgkmcnt(0)
	v_ashrrev_i32_e32 v65, 31, v64
	v_lshlrev_b64 v[66:67], 11, v[64:65]
	v_lshl_add_u64 v[74:75], v[66:67], 0, v[144:145]
	v_lshl_add_u64 v[76:77], v[74:75], 2, s[28:29]
	global_load_dwordx4 v[66:69], v[76:77], off
	global_load_dwordx4 v[70:73], v[76:77], off offset:16
	global_load_dwordx4 v[176:179], v[76:77], off offset:512
	global_load_dwordx4 v[180:183], v[76:77], off offset:528
	v_lshl_add_u64 v[74:75], v[74:75], 1, s[46:47]
	s_waitcnt vmcnt(3)
	v_pk_fma_f32 v[62:63], v[62:63], 0.5, v[68:69] op_sel_hi:[1,0,1]
	v_pk_fma_f32 v[60:61], v[60:61], 0.5, v[66:67] op_sel_hi:[1,0,1]
	s_waitcnt vmcnt(2)
	v_pk_fma_f32 v[58:59], v[58:59], 0.5, v[72:73] op_sel_hi:[1,0,1]
	v_pk_fma_f32 v[56:57], v[56:57], 0.5, v[70:71] op_sel_hi:[1,0,1]
	v_cvt_pk_bf16_f32 v66, v60, v61
	v_cvt_pk_bf16_f32 v67, v62, v63
	v_cvt_pk_bf16_f32 v68, v56, v57
	v_cvt_pk_bf16_f32 v69, v58, v59
	global_store_dwordx4 v[76:77], v[60:63], off
	global_store_dwordx4 v[76:77], v[56:59], off offset:16
	global_store_dwordx4 v[74:75], v[66:69], off
	s_nop 1
	v_mul_f32_e32 v61, v61, v61
	v_mul_f32_e32 v63, v63, v63
	v_mul_f32_e32 v57, v57, v57
	v_mul_f32_e32 v59, v59, v59
	v_fmac_f32_e32 v61, v60, v60
	v_fmac_f32_e32 v63, v62, v62
	v_fmac_f32_e32 v57, v56, v56
	v_fmac_f32_e32 v59, v58, v58
	v_add_f32_e32 v56, v61, v63
	v_add_f32_e32 v57, v57, v59
	v_add_f32_e32 v60, v56, v57
	s_waitcnt vmcnt(4)
	v_pk_fma_f32 v[54:55], v[54:55], 0.5, v[178:179] op_sel_hi:[1,0,1]
	v_pk_fma_f32 v[52:53], v[52:53], 0.5, v[176:177] op_sel_hi:[1,0,1]
	s_waitcnt vmcnt(3)
	v_pk_fma_f32 v[58:59], v[50:51], 0.5, v[182:183] op_sel_hi:[1,0,1]
	v_pk_fma_f32 v[56:57], v[48:49], 0.5, v[180:181] op_sel_hi:[1,0,1]
	v_mul_f32_e32 v48, v53, v53
	v_mul_f32_e32 v49, v55, v55
	v_mul_f32_e32 v50, v57, v57
	v_mul_f32_e32 v51, v59, v59
	v_fmac_f32_e32 v48, v52, v52
	v_fmac_f32_e32 v49, v54, v54
	v_fmac_f32_e32 v50, v56, v56
	v_fmac_f32_e32 v51, v58, v58
	v_add_f32_e32 v48, v48, v49
	v_add_f32_e32 v49, v50, v51
	v_add_f32_e32 v48, v48, v49
	v_add_f32_e32 v48, v60, v48
	ds_bpermute_b32 v49, v120, v48
	global_store_dwordx4 v[76:77], v[52:55], off offset:512
	global_store_dwordx4 v[76:77], v[56:59], off offset:528
	v_cvt_pk_bf16_f32 v50, v52, v53
	v_cvt_pk_bf16_f32 v51, v54, v55
	v_cvt_pk_bf16_f32 v52, v56, v57
	s_waitcnt lgkmcnt(0)
	v_add_f32_e32 v48, v48, v49
	ds_bpermute_b32 v49, v114, v48
	v_cvt_pk_bf16_f32 v53, v58, v59
	global_store_dwordx4 v[74:75], v[50:53], off offset:256
	s_and_saveexec_b64 s[48:49], s[2:3]
	s_cbranch_execz .LBB0_1488
	s_waitcnt lgkmcnt(0)
	v_add_f32_e32 v48, v48, v49
	v_mul_f32_e32 v48, 0x4b800000, v48
	v_trunc_f32_e32 v48, v48
	v_mul_f32_e32 v49, 0x2f800000, v48
	v_floor_f32_e32 v49, v49
	v_fmac_f32_e32 v48, 0xcf800000, v49
	v_cvt_u32_f32_e32 v48, v48
	v_cvt_u32_f32_e32 v49, v49
	v_lshl_add_u64 v[50:51], v[64:65], 3, s[18:19]
	global_atomic_add_x2 v[50:51], v[48:49], off
.LBB0_1488:
	s_or_b64 exec, exec, s[48:49]
	v_add_u32_e32 v48, 0x90, v146
	s_waitcnt lgkmcnt(0)
	v_ashrrev_i32_e32 v49, 31, v48
	v_lshlrev_b64 v[50:51], 11, v[48:49]
	v_lshl_add_u64 v[58:59], v[50:51], 0, v[144:145]
	v_lshl_add_u64 v[60:61], v[58:59], 2, s[28:29]
	global_load_dwordx4 v[50:53], v[60:61], off
	global_load_dwordx4 v[54:57], v[60:61], off offset:16
	global_load_dwordx4 v[176:179], v[60:61], off offset:512
	global_load_dwordx4 v[180:183], v[60:61], off offset:528
	v_lshl_add_u64 v[58:59], v[58:59], 1, s[46:47]
	s_waitcnt vmcnt(3)
	v_pk_fma_f32 v[46:47], v[46:47], 0.5, v[52:53] op_sel_hi:[1,0,1]
	v_pk_fma_f32 v[44:45], v[44:45], 0.5, v[50:51] op_sel_hi:[1,0,1]
	s_waitcnt vmcnt(2)
	v_pk_fma_f32 v[42:43], v[42:43], 0.5, v[56:57] op_sel_hi:[1,0,1]
	v_pk_fma_f32 v[40:41], v[40:41], 0.5, v[54:55] op_sel_hi:[1,0,1]
	v_cvt_pk_bf16_f32 v50, v44, v45
	v_cvt_pk_bf16_f32 v51, v46, v47
	v_cvt_pk_bf16_f32 v52, v40, v41
	v_cvt_pk_bf16_f32 v53, v42, v43
	global_store_dwordx4 v[60:61], v[44:47], off
	global_store_dwordx4 v[60:61], v[40:43], off offset:16
	global_store_dwordx4 v[58:59], v[50:53], off
	s_nop 1
	v_mul_f32_e32 v45, v45, v45
	v_mul_f32_e32 v47, v47, v47
	v_mul_f32_e32 v41, v41, v41
	v_mul_f32_e32 v43, v43, v43
	v_fmac_f32_e32 v45, v44, v44
	v_fmac_f32_e32 v47, v46, v46
	v_fmac_f32_e32 v41, v40, v40
	v_fmac_f32_e32 v43, v42, v42
	v_add_f32_e32 v40, v45, v47
	v_add_f32_e32 v41, v41, v43
	v_add_f32_e32 v44, v40, v41
	s_waitcnt vmcnt(4)
	v_pk_fma_f32 v[38:39], v[38:39], 0.5, v[178:179] op_sel_hi:[1,0,1]
	v_pk_fma_f32 v[36:37], v[36:37], 0.5, v[176:177] op_sel_hi:[1,0,1]
	s_waitcnt vmcnt(3)
	v_pk_fma_f32 v[42:43], v[34:35], 0.5, v[182:183] op_sel_hi:[1,0,1]
	v_pk_fma_f32 v[40:41], v[32:33], 0.5, v[180:181] op_sel_hi:[1,0,1]
	v_mul_f32_e32 v32, v37, v37
	v_mul_f32_e32 v33, v39, v39
	v_mul_f32_e32 v34, v41, v41
	v_mul_f32_e32 v35, v43, v43
	v_fmac_f32_e32 v32, v36, v36
	v_fmac_f32_e32 v33, v38, v38
	v_fmac_f32_e32 v34, v40, v40
	v_fmac_f32_e32 v35, v42, v42
	v_add_f32_e32 v32, v32, v33
	v_add_f32_e32 v33, v34, v35
	v_add_f32_e32 v32, v32, v33
	v_add_f32_e32 v32, v44, v32
	ds_bpermute_b32 v33, v120, v32
	global_store_dwordx4 v[60:61], v[36:39], off offset:512
	global_store_dwordx4 v[60:61], v[40:43], off offset:528
	v_cvt_pk_bf16_f32 v34, v36, v37
	v_cvt_pk_bf16_f32 v35, v38, v39
	v_cvt_pk_bf16_f32 v36, v40, v41
	s_waitcnt lgkmcnt(0)
	v_add_f32_e32 v32, v32, v33
	ds_bpermute_b32 v33, v114, v32
	v_cvt_pk_bf16_f32 v37, v42, v43
	global_store_dwordx4 v[58:59], v[34:37], off offset:256
	s_and_saveexec_b64 s[48:49], s[2:3]
	s_cbranch_execz .LBB0_1490
	s_waitcnt lgkmcnt(0)
	v_add_f32_e32 v32, v32, v33
	v_mul_f32_e32 v32, 0x4b800000, v32
	v_trunc_f32_e32 v32, v32
	v_mul_f32_e32 v33, 0x2f800000, v32
	v_floor_f32_e32 v33, v33
	v_fmac_f32_e32 v32, 0xcf800000, v33
	v_cvt_u32_f32_e32 v32, v32
	v_cvt_u32_f32_e32 v33, v33
	v_lshl_add_u64 v[34:35], v[48:49], 3, s[18:19]
	global_atomic_add_x2 v[34:35], v[32:33], off
; __device__ __forceinline__ u32x4 pack8(const f32x4 a, const f32x4 b) { u32x4 w; w.x = cvt_pk_bf16(a[0], a[1]); w.y = cvt_pk_bf16(a[2], a[3]); w.z = cvt_pk_bf16(b[0], b[1]); w.w = cvt_pk_bf16(b[2], b[3]); return w; }
; __device__ __forceinline__ void ss_add(ssq_t* p, float sq) { __hip_atomic_fetch_add(p, (ssq_t)(sq * 16777216.0f), __ATOMIC_RELAXED, __HIP_MEMORY_SCOPE_AGENT); }
; __device__ __forceinline__ float dot4(const f32x4 a) { return (a[0] * a[0] + a[1] * a[1]) + (a[2] * a[2] + a[3] * a[3]); }
;     __device__ __forceinline__ void operator()(const f32x4 (&acc)[2][2][4][2], const Unit& u, int wr, int wc, int fr, int fq) const {
;     ...
;             for (int m = 0; m < 4; ++m) { const int row = row0 + ai * HALF + m * 16; const size_t off = (size_t)row * 2048 + col0; float sq = 0.f;
; #pragma unroll
;                 for (int bj = 0; bj < 2; ++bj) {
;                     const f32x4 x0 = __builtin_nontemporal_load((const f32x4*)(xin + off + bj * HALF)), x1 = __builtin_nontemporal_load((const f32x4*)(xin + off + bj * HALF + 4));
;                     const f32x4 v0 = x0 + acc[ai][bj][m][0] * alpha, v1 = x1 + acc[ai][bj][m][1] * alpha;
;                     __builtin_nontemporal_store(v0, (f32x4*)(xout + off + bj * HALF)); __builtin_nontemporal_store(v1, (f32x4*)(xout + off + bj * HALF + 4));
;                     if (WRITE_XB) *(u32x4*)(xb + off + bj * HALF) = pack8(v0, v1); sq += dot4(v0) + dot4(v1); }
;                 sq += __shfl_xor(sq, 16); sq += __shfl_xor(sq, 32);
;                 if (fq == 0) ss_add(ssout + row, sq); }
.LBB0_1490:
	s_or_b64 exec, exec, s[48:49]
	v_add_u32_e32 v32, 0xa0, v146
	s_waitcnt lgkmcnt(0)
	v_ashrrev_i32_e32 v33, 31, v32
	v_lshlrev_b64 v[34:35], 11, v[32:33]
	v_lshl_add_u64 v[42:43], v[34:35], 0, v[144:145]
	v_lshl_add_u64 v[44:45], v[42:43], 2, s[28:29]
	global_load_dwordx4 v[34:37], v[44:45], off
	global_load_dwordx4 v[38:41], v[44:45], off offset:16
	global_load_dwordx4 v[176:179], v[44:45], off offset:512
	global_load_dwordx4 v[180:183], v[44:45], off offset:528
	v_lshl_add_u64 v[42:43], v[42:43], 1, s[46:47]
	s_waitcnt vmcnt(3)
	v_pk_fma_f32 v[30:31], v[30:31], 0.5, v[36:37] op_sel_hi:[1,0,1]
	v_pk_fma_f32 v[28:29], v[28:29], 0.5, v[34:35] op_sel_hi:[1,0,1]
	s_waitcnt vmcnt(2)
	v_pk_fma_f32 v[26:27], v[26:27], 0.5, v[40:41] op_sel_hi:[1,0,1]
	v_pk_fma_f32 v[24:25], v[24:25], 0.5, v[38:39] op_sel_hi:[1,0,1]
	v_cvt_pk_bf16_f32 v34, v28, v29
	v_cvt_pk_bf16_f32 v35, v30, v31
	v_cvt_pk_bf16_f32 v36, v24, v25
	v_cvt_pk_bf16_f32 v37, v26, v27
	global_store_dwordx4 v[44:45], v[28:31], off
	global_store_dwordx4 v[44:45], v[24:27], off offset:16
	global_store_dwordx4 v[42:43], v[34:37], off
	s_nop 1
	v_mul_f32_e32 v29, v29, v29
	v_mul_f32_e32 v31, v31, v31
	v_mul_f32_e32 v25, v25, v25
	v_mul_f32_e32 v27, v27, v27
	v_fmac_f32_e32 v29, v28, v28
	v_fmac_f32_e32 v31, v30, v30
	v_fmac_f32_e32 v25, v24, v24
	v_fmac_f32_e32 v27, v26, v26
	v_add_f32_e32 v24, v29, v31
	v_add_f32_e32 v25, v25, v27
	v_add_f32_e32 v28, v24, v25
	s_waitcnt vmcnt(4)
	v_pk_fma_f32 v[22:23], v[22:23], 0.5, v[178:179] op_sel_hi:[1,0,1]
	v_pk_fma_f32 v[20:21], v[20:21], 0.5, v[176:177] op_sel_hi:[1,0,1]
	s_waitcnt vmcnt(3)
	v_pk_fma_f32 v[26:27], v[18:19], 0.5, v[182:183] op_sel_hi:[1,0,1]
	v_pk_fma_f32 v[24:25], v[16:17], 0.5, v[180:181] op_sel_hi:[1,0,1]
	v_mul_f32_e32 v16, v21, v21
	v_mul_f32_e32 v17, v23, v23
	v_mul_f32_e32 v18, v25, v25
	v_mul_f32_e32 v19, v27, v27
	v_fmac_f32_e32 v16, v20, v20
	v_fmac_f32_e32 v17, v22, v22
	v_fmac_f32_e32 v18, v24, v24
	v_fmac_f32_e32 v19, v26, v26
	v_add_f32_e32 v16, v16, v17
	v_add_f32_e32 v17, v18, v19
	v_add_f32_e32 v16, v16, v17
	v_add_f32_e32 v16, v28, v16
	ds_bpermute_b32 v17, v120, v16
	global_store_dwordx4 v[44:45], v[20:23], off offset:512
	global_store_dwordx4 v[44:45], v[24:27], off offset:528
	v_cvt_pk_bf16_f32 v18, v20, v21
	v_cvt_pk_bf16_f32 v19, v22, v23
	v_cvt_pk_bf16_f32 v20, v24, v25
	s_waitcnt lgkmcnt(0)
	v_add_f32_e32 v16, v16, v17
	ds_bpermute_b32 v17, v114, v16
	v_cvt_pk_bf16_f32 v21, v26, v27
	global_store_dwordx4 v[42:43], v[18:21], off offset:256
	s_and_saveexec_b64 s[48:49], s[2:3]
	s_cbranch_execz .LBB0_1492
	s_waitcnt lgkmcnt(0)
	v_add_f32_e32 v16, v16, v17
	v_mul_f32_e32 v16, 0x4b800000, v16
	v_trunc_f32_e32 v16, v16
	v_mul_f32_e32 v17, 0x2f800000, v16
	v_floor_f32_e32 v17, v17
	v_fmac_f32_e32 v16, 0xcf800000, v17
	v_cvt_u32_f32_e32 v16, v16
	v_cvt_u32_f32_e32 v17, v17
	v_lshl_add_u64 v[18:19], v[32:33], 3, s[18:19]
	global_atomic_add_x2 v[18:19], v[16:17], off
.LBB0_1492:
	s_or_b64 exec, exec, s[48:49]
	v_add_u32_e32 v16, 0xb0, v146
	s_waitcnt lgkmcnt(0)
	v_ashrrev_i32_e32 v17, 31, v16
	v_lshlrev_b64 v[18:19], 11, v[16:17]
	v_lshl_add_u64 v[26:27], v[18:19], 0, v[144:145]
	v_lshl_add_u64 v[28:29], v[26:27], 2, s[28:29]
	global_load_dwordx4 v[18:21], v[28:29], off
	global_load_dwordx4 v[22:25], v[28:29], off offset:16
	global_load_dwordx4 v[176:179], v[28:29], off offset:512
	global_load_dwordx4 v[180:183], v[28:29], off offset:528
	v_lshl_add_u64 v[26:27], v[26:27], 1, s[46:47]
	s_waitcnt vmcnt(3)
	v_pk_fma_f32 v[14:15], v[14:15], 0.5, v[20:21] op_sel_hi:[1,0,1]
	v_pk_fma_f32 v[12:13], v[12:13], 0.5, v[18:19] op_sel_hi:[1,0,1]
	s_waitcnt vmcnt(2)
	v_pk_fma_f32 v[10:11], v[10:11], 0.5, v[24:25] op_sel_hi:[1,0,1]
	v_pk_fma_f32 v[8:9], v[8:9], 0.5, v[22:23] op_sel_hi:[1,0,1]
	v_cvt_pk_bf16_f32 v18, v12, v13
	v_cvt_pk_bf16_f32 v19, v14, v15
	v_cvt_pk_bf16_f32 v20, v8, v9
	v_cvt_pk_bf16_f32 v21, v10, v11
	global_store_dwordx4 v[28:29], v[12:15], off
	global_store_dwordx4 v[28:29], v[8:11], off offset:16
	global_store_dwordx4 v[26:27], v[18:21], off
	s_nop 1
	v_mul_f32_e32 v13, v13, v13
	v_mul_f32_e32 v15, v15, v15
	v_mul_f32_e32 v9, v9, v9
	v_mul_f32_e32 v11, v11, v11
	v_fmac_f32_e32 v13, v12, v12
	v_fmac_f32_e32 v15, v14, v14
	v_fmac_f32_e32 v9, v8, v8
	v_fmac_f32_e32 v11, v10, v10
	v_add_f32_e32 v8, v13, v15
	v_add_f32_e32 v9, v9, v11
	v_add_f32_e32 v12, v8, v9
	s_waitcnt vmcnt(4)
	v_pk_fma_f32 v[6:7], v[6:7], 0.5, v[178:179] op_sel_hi:[1,0,1]
	v_pk_fma_f32 v[4:5], v[4:5], 0.5, v[176:177] op_sel_hi:[1,0,1]
	s_waitcnt vmcnt(3)
	v_pk_fma_f32 v[10:11], v[2:3], 0.5, v[182:183] op_sel_hi:[1,0,1]
	v_pk_fma_f32 v[8:9], v[0:1], 0.5, v[180:181] op_sel_hi:[1,0,1]
	v_mul_f32_e32 v0, v5, v5
	v_mul_f32_e32 v1, v7, v7
	v_mul_f32_e32 v2, v9, v9
	v_mul_f32_e32 v3, v11, v11
	v_fmac_f32_e32 v0, v4, v4
	v_fmac_f32_e32 v1, v6, v6
	v_fmac_f32_e32 v2, v8, v8
	v_fmac_f32_e32 v3, v10, v10
	v_add_f32_e32 v0, v0, v1
	v_add_f32_e32 v1, v2, v3
	v_add_f32_e32 v0, v0, v1
	v_add_f32_e32 v0, v12, v0
	ds_bpermute_b32 v1, v120, v0
	global_store_dwordx4 v[28:29], v[4:7], off offset:512
	global_store_dwordx4 v[28:29], v[8:11], off offset:528
	v_cvt_pk_bf16_f32 v2, v4, v5
	v_cvt_pk_bf16_f32 v3, v6, v7
	v_cvt_pk_bf16_f32 v4, v8, v9
	s_waitcnt lgkmcnt(0)
	v_add_f32_e32 v0, v0, v1
	ds_bpermute_b32 v1, v114, v0
	v_cvt_pk_bf16_f32 v5, v10, v11
	global_store_dwordx4 v[26:27], v[2:5], off offset:256
	s_and_saveexec_b64 s[48:49], s[2:3]
	s_cbranch_execz .LBB0_1494
	s_waitcnt lgkmcnt(0)
	v_add_f32_e32 v0, v0, v1
	v_mul_f32_e32 v0, 0x4b800000, v0
	v_trunc_f32_e32 v0, v0
	v_mul_f32_e32 v1, 0x2f800000, v0
	v_floor_f32_e32 v1, v1
	v_fmac_f32_e32 v0, 0xcf800000, v1
	v_cvt_u32_f32_e32 v0, v0
	v_cvt_u32_f32_e32 v1, v1
	v_lshl_add_u64 v[2:3], v[16:17], 3, s[18:19]
	global_atomic_add_x2 v[2:3], v[0:1], off

; __device__ __forceinline__ u32x4 pack8(const f32x4 a, const f32x4 b) { u32x4 w; w.x = cvt_pk_bf16(a[0], a[1]); w.y = cvt_pk_bf16(a[2], a[3]); w.z = cvt_pk_bf16(b[0], b[1]); w.w = cvt_pk_bf16(b[2], b[3]); return w; }
; __device__ __forceinline__ void ss_add(ssq_t* p, float sq) { __hip_atomic_fetch_add(p, (ssq_t)(sq * 16777216.0f), __ATOMIC_RELAXED, __HIP_MEMORY_SCOPE_AGENT); }
; __device__ __forceinline__ float dot4(const f32x4 a) { return (a[0] * a[0] + a[1] * a[1]) + (a[2] * a[2] + a[3] * a[3]); }
;     __device__ __forceinline__ void operator()(const f32x4 (&acc)[2][2][4][2], const Unit& u, int wr, int wc, int fr, int fq) const {
;     ...
;             for (int m = 0; m < 4; ++m) { const int row = row0 + ai * HALF + m * 16; const size_t off = (size_t)row * 2048 + col0; float sq = 0.f;
; #pragma unroll
;                 for (int bj = 0; bj < 2; ++bj) {
;                     const f32x4 x0 = __builtin_nontemporal_load((const f32x4*)(xin + off + bj * HALF)), x1 = __builtin_nontemporal_load((const f32x4*)(xin + off + bj * HALF + 4));
;                     const f32x4 v0 = x0 + acc[ai][bj][m][0] * alpha, v1 = x1 + acc[ai][bj][m][1] * alpha;
;                     __builtin_nontemporal_store(v0, (f32x4*)(xout + off + bj * HALF)); __builtin_nontemporal_store(v1, (f32x4*)(xout + off + bj * HALF + 4));
;                     if (WRITE_XB) *(u32x4*)(xb + off + bj * HALF) = pack8(v0, v1); sq += dot4(v0) + dot4(v1); }
;                 sq += __shfl_xor(sq, 16); sq += __shfl_xor(sq, 32);
;                 if (fq == 0) ss_add(ssout + row, sq); }
.LBB0_2085:
	v_lshl_add_u32 v146, s24, 8, v148
	v_lshl_add_u32 v144, s36, 8, v150
	v_ashrrev_i32_e32 v147, 31, v146
	v_ashrrev_i32_e32 v145, 31, v144
	v_lshlrev_b64 v[156:157], 11, v[146:147]
	v_lshl_add_u64 v[164:165], v[156:157], 0, v[144:145]
	v_lshl_add_u64 v[168:169], v[164:165], 2, s[28:29]
	global_load_dwordx4 v[156:159], v[168:169], off
	global_load_dwordx4 v[160:163], v[168:169], off offset:16
	global_load_dwordx4 v[176:179], v[168:169], off offset:512
	global_load_dwordx4 v[180:183], v[168:169], off offset:528
	v_lshl_add_u64 v[170:171], v[164:165], 1, s[46:47]
	s_waitcnt vmcnt(2)
	v_pk_add_f32 v[126:127], v[126:127], v[158:159]
	v_pk_add_f32 v[124:125], v[124:125], v[156:157]
	v_pk_add_f32 v[158:159], v[122:123], v[162:163]
	v_pk_add_f32 v[156:157], v[120:121], v[160:161]
	v_cvt_pk_bf16_f32 v120, v124, v125
	v_cvt_pk_bf16_f32 v121, v126, v127
	v_cvt_pk_bf16_f32 v122, v156, v157
	v_cvt_pk_bf16_f32 v123, v158, v159
	global_store_dwordx4 v[168:169], v[124:127], off
	global_store_dwordx4 v[168:169], v[156:159], off offset:16
	global_store_dwordx4 v[170:171], v[120:123], off
	s_nop 1
	v_and_b32_e32 v121, 64, v154
	v_xor_b32_e32 v120, 16, v154
	v_add_u32_e32 v121, 64, v121
	v_xor_b32_e32 v122, 32, v154
	v_cmp_lt_i32_e32 vcc, v120, v121
	v_mul_f32_e32 v123, v127, v127
	v_mul_f32_e32 v127, v159, v159
	v_cndmask_b32_e32 v120, v154, v120, vcc
	v_cmp_lt_i32_e32 vcc, v122, v121
	v_fmac_f32_e32 v123, v126, v126
	v_fmac_f32_e32 v127, v158, v158
	v_cndmask_b32_e32 v121, v154, v122, vcc
	v_mul_f32_e32 v122, v125, v125
	v_mul_f32_e32 v125, v157, v157
	v_fmac_f32_e32 v122, v124, v124
	v_fmac_f32_e32 v125, v156, v156
	v_add_f32_e32 v122, v122, v123
	v_add_f32_e32 v123, v125, v127
	v_add_f32_e32 v126, v122, v123
	v_lshlrev_b32_e32 v120, 2, v120
	s_waitcnt vmcnt(4)
	v_pk_add_f32 v[118:119], v[118:119], v[178:179]
	v_pk_add_f32 v[116:117], v[116:117], v[176:177]
	s_waitcnt vmcnt(3)
	v_pk_add_f32 v[124:125], v[114:115], v[182:183]
	v_pk_add_f32 v[122:123], v[112:113], v[180:181]
	v_mul_f32_e32 v112, v117, v117
	v_mul_f32_e32 v113, v119, v119
	v_mul_f32_e32 v114, v123, v123
	v_mul_f32_e32 v115, v125, v125
	v_fmac_f32_e32 v112, v116, v116
	v_fmac_f32_e32 v113, v118, v118
	v_fmac_f32_e32 v114, v122, v122
	v_fmac_f32_e32 v115, v124, v124
	v_add_f32_e32 v112, v112, v113
	v_add_f32_e32 v113, v114, v115
	v_add_f32_e32 v112, v112, v113
	v_add_f32_e32 v112, v126, v112
	ds_bpermute_b32 v113, v120, v112
	v_lshlrev_b32_e32 v114, 2, v121
	global_store_dwordx4 v[168:169], v[116:119], off offset:512
	global_store_dwordx4 v[168:169], v[122:125], off offset:528
	s_waitcnt lgkmcnt(0)
	v_add_f32_e32 v112, v112, v113
	ds_bpermute_b32 v113, v114, v112
	v_cvt_pk_bf16_f32 v116, v116, v117
	v_cvt_pk_bf16_f32 v117, v118, v119
	v_cvt_pk_bf16_f32 v118, v122, v123
	v_cvt_pk_bf16_f32 v119, v124, v125
	global_store_dwordx4 v[170:171], v[116:119], off offset:256
	s_and_saveexec_b64 s[24:25], s[2:3]
	s_cbranch_execz .LBB0_2087
	s_waitcnt lgkmcnt(0)
	v_add_f32_e32 v112, v112, v113
	v_mul_f32_e32 v112, 0x4b800000, v112
	v_trunc_f32_e32 v112, v112
	v_mul_f32_e32 v113, 0x2f800000, v112
	v_floor_f32_e32 v113, v113
	v_fmac_f32_e32 v112, 0xcf800000, v113
	v_cvt_u32_f32_e32 v112, v112
	v_cvt_u32_f32_e32 v113, v113
	v_lshl_add_u64 v[116:117], v[146:147], 3, s[6:7]
	global_atomic_add_x2 v[116:117], v[112:113], off
.LBB0_2087:
	s_or_b64 exec, exec, s[24:25]
	v_or_b32_e32 v112, 16, v146
	s_waitcnt lgkmcnt(0)
	v_ashrrev_i32_e32 v113, 31, v112
	v_lshlrev_b64 v[116:117], 11, v[112:113]
	v_lshl_add_u64 v[126:127], v[116:117], 0, v[144:145]
	v_lshl_add_u64 v[156:157], v[126:127], 2, s[28:29]
	global_load_dwordx4 v[116:119], v[156:157], off
	global_load_dwordx4 v[122:125], v[156:157], off offset:16
	global_load_dwordx4 v[176:179], v[156:157], off offset:512
	global_load_dwordx4 v[180:183], v[156:157], off offset:528
	v_lshl_add_u64 v[126:127], v[126:127], 1, s[46:47]
	s_waitcnt vmcnt(3)
	v_pk_add_f32 v[110:111], v[110:111], v[118:119]
	v_pk_add_f32 v[108:109], v[108:109], v[116:117]
	s_waitcnt vmcnt(2)
	v_pk_add_f32 v[106:107], v[106:107], v[124:125]
	v_pk_add_f32 v[104:105], v[104:105], v[122:123]
	v_cvt_pk_bf16_f32 v116, v108, v109
	v_cvt_pk_bf16_f32 v117, v110, v111
	v_cvt_pk_bf16_f32 v118, v104, v105
	v_cvt_pk_bf16_f32 v119, v106, v107
	global_store_dwordx4 v[156:157], v[108:111], off
	global_store_dwordx4 v[156:157], v[104:107], off offset:16
	global_store_dwordx4 v[126:127], v[116:119], off
	s_nop 1
	v_mul_f32_e32 v109, v109, v109
	v_mul_f32_e32 v111, v111, v111
	v_mul_f32_e32 v105, v105, v105
	v_mul_f32_e32 v107, v107, v107
	v_fmac_f32_e32 v109, v108, v108
	v_fmac_f32_e32 v111, v110, v110
	v_fmac_f32_e32 v105, v104, v104
	v_fmac_f32_e32 v107, v106, v106
	v_add_f32_e32 v104, v109, v111
	v_add_f32_e32 v105, v105, v107
	v_add_f32_e32 v108, v104, v105
	s_waitcnt vmcnt(4)
	v_pk_add_f32 v[102:103], v[102:103], v[178:179]
	v_pk_add_f32 v[100:101], v[100:101], v[176:177]
	s_waitcnt vmcnt(3)
	v_pk_add_f32 v[106:107], v[98:99], v[182:183]
	v_pk_add_f32 v[104:105], v[96:97], v[180:181]
	v_mul_f32_e32 v96, v101, v101
	v_mul_f32_e32 v97, v103, v103
	v_mul_f32_e32 v98, v105, v105
	v_mul_f32_e32 v99, v107, v107
	v_fmac_f32_e32 v96, v100, v100
	v_fmac_f32_e32 v97, v102, v102
	v_fmac_f32_e32 v98, v104, v104
	v_fmac_f32_e32 v99, v106, v106
	v_add_f32_e32 v96, v96, v97
	v_add_f32_e32 v97, v98, v99
	v_add_f32_e32 v96, v96, v97
	v_add_f32_e32 v96, v108, v96
	ds_bpermute_b32 v97, v120, v96
	global_store_dwordx4 v[156:157], v[100:103], off offset:512
	global_store_dwordx4 v[156:157], v[104:107], off offset:528
	v_cvt_pk_bf16_f32 v98, v100, v101
	v_cvt_pk_bf16_f32 v99, v102, v103
	v_cvt_pk_bf16_f32 v100, v104, v105
	s_waitcnt lgkmcnt(0)
	v_add_f32_e32 v96, v96, v97
	ds_bpermute_b32 v97, v114, v96
	v_cvt_pk_bf16_f32 v101, v106, v107
	global_store_dwordx4 v[126:127], v[98:101], off offset:256
	s_and_saveexec_b64 s[24:25], s[2:3]
	s_cbranch_execz .LBB0_2089
	s_waitcnt lgkmcnt(0)
	v_add_f32_e32 v96, v96, v97
	v_mul_f32_e32 v96, 0x4b800000, v96
	v_trunc_f32_e32 v96, v96
	v_mul_f32_e32 v97, 0x2f800000, v96
	v_floor_f32_e32 v97, v97
	v_fmac_f32_e32 v96, 0xcf800000, v97
	v_cvt_u32_f32_e32 v96, v96
	v_cvt_u32_f32_e32 v97, v97
	v_lshl_add_u64 v[98:99], v[112:113], 3, s[6:7]
	global_atomic_add_x2 v[98:99], v[96:97], off
; __device__ __forceinline__ u32x4 pack8(const f32x4 a, const f32x4 b) { u32x4 w; w.x = cvt_pk_bf16(a[0], a[1]); w.y = cvt_pk_bf16(a[2], a[3]); w.z = cvt_pk_bf16(b[0], b[1]); w.w = cvt_pk_bf16(b[2], b[3]); return w; }
; __device__ __forceinline__ void ss_add(ssq_t* p, float sq) { __hip_atomic_fetch_add(p, (ssq_t)(sq * 16777216.0f), __ATOMIC_RELAXED, __HIP_MEMORY_SCOPE_AGENT); }
; __device__ __forceinline__ float dot4(const f32x4 a) { return (a[0] * a[0] + a[1] * a[1]) + (a[2] * a[2] + a[3] * a[3]); }
;     __device__ __forceinline__ void operator()(const f32x4 (&acc)[2][2][4][2], const Unit& u, int wr, int wc, int fr, int fq) const {
;     ...
;             for (int m = 0; m < 4; ++m) { const int row = row0 + ai * HALF + m * 16; const size_t off = (size_t)row * 2048 + col0; float sq = 0.f;
; #pragma unroll
;                 for (int bj = 0; bj < 2; ++bj) {
;                     const f32x4 x0 = __builtin_nontemporal_load((const f32x4*)(xin + off + bj * HALF)), x1 = __builtin_nontemporal_load((const f32x4*)(xin + off + bj * HALF + 4));
;                     const f32x4 v0 = x0 + acc[ai][bj][m][0] * alpha, v1 = x1 + acc[ai][bj][m][1] * alpha;
;                     __builtin_nontemporal_store(v0, (f32x4*)(xout + off + bj * HALF)); __builtin_nontemporal_store(v1, (f32x4*)(xout + off + bj * HALF + 4));
;                     if (WRITE_XB) *(u32x4*)(xb + off + bj * HALF) = pack8(v0, v1); sq += dot4(v0) + dot4(v1); }
;                 sq += __shfl_xor(sq, 16); sq += __shfl_xor(sq, 32);
;                 if (fq == 0) ss_add(ssout + row, sq); }
.LBB0_2089:
	s_or_b64 exec, exec, s[24:25]
	v_or_b32_e32 v96, 32, v146
	s_waitcnt lgkmcnt(0)
	v_ashrrev_i32_e32 v97, 31, v96
	v_lshlrev_b64 v[98:99], 11, v[96:97]
	v_lshl_add_u64 v[106:107], v[98:99], 0, v[144:145]
	v_lshl_add_u64 v[108:109], v[106:107], 2, s[28:29]
	global_load_dwordx4 v[98:101], v[108:109], off
	global_load_dwordx4 v[102:105], v[108:109], off offset:16
	global_load_dwordx4 v[176:179], v[108:109], off offset:512
	global_load_dwordx4 v[180:183], v[108:109], off offset:528
	v_lshl_add_u64 v[106:107], v[106:107], 1, s[46:47]
	s_waitcnt vmcnt(3)
	v_pk_add_f32 v[94:95], v[94:95], v[100:101]
	v_pk_add_f32 v[92:93], v[92:93], v[98:99]
	s_waitcnt vmcnt(2)
	v_pk_add_f32 v[90:91], v[90:91], v[104:105]
	v_pk_add_f32 v[88:89], v[88:89], v[102:103]
	v_cvt_pk_bf16_f32 v98, v92, v93
	v_cvt_pk_bf16_f32 v99, v94, v95
	v_cvt_pk_bf16_f32 v100, v88, v89
	v_cvt_pk_bf16_f32 v101, v90, v91
	global_store_dwordx4 v[108:109], v[92:95], off
	global_store_dwordx4 v[108:109], v[88:91], off offset:16
	global_store_dwordx4 v[106:107], v[98:101], off
	s_nop 1
	v_mul_f32_e32 v93, v93, v93
	v_mul_f32_e32 v95, v95, v95
	v_mul_f32_e32 v89, v89, v89
	v_mul_f32_e32 v91, v91, v91
	v_fmac_f32_e32 v93, v92, v92
	v_fmac_f32_e32 v95, v94, v94
	v_fmac_f32_e32 v89, v88, v88
	v_fmac_f32_e32 v91, v90, v90
	v_add_f32_e32 v88, v93, v95
	v_add_f32_e32 v89, v89, v91
	v_add_f32_e32 v92, v88, v89
	s_waitcnt vmcnt(4)
	v_pk_add_f32 v[86:87], v[86:87], v[178:179]
	v_pk_add_f32 v[84:85], v[84:85], v[176:177]
	s_waitcnt vmcnt(3)
	v_pk_add_f32 v[90:91], v[82:83], v[182:183]
	v_pk_add_f32 v[88:89], v[80:81], v[180:181]
	v_mul_f32_e32 v80, v85, v85
	v_mul_f32_e32 v81, v87, v87
	v_mul_f32_e32 v82, v89, v89
	v_mul_f32_e32 v83, v91, v91
	v_fmac_f32_e32 v80, v84, v84
	v_fmac_f32_e32 v81, v86, v86
	v_fmac_f32_e32 v82, v88, v88
	v_fmac_f32_e32 v83, v90, v90
	v_add_f32_e32 v80, v80, v81
	v_add_f32_e32 v81, v82, v83
	v_add_f32_e32 v80, v80, v81
	v_add_f32_e32 v80, v92, v80
	ds_bpermute_b32 v81, v120, v80
	global_store_dwordx4 v[108:109], v[84:87], off offset:512
	global_store_dwordx4 v[108:109], v[88:91], off offset:528
	v_cvt_pk_bf16_f32 v82, v84, v85
	v_cvt_pk_bf16_f32 v83, v86, v87
	v_cvt_pk_bf16_f32 v84, v88, v89
	s_waitcnt lgkmcnt(0)
	v_add_f32_e32 v80, v80, v81
	ds_bpermute_b32 v81, v114, v80
	v_cvt_pk_bf16_f32 v85, v90, v91
	global_store_dwordx4 v[106:107], v[82:85], off offset:256
	s_and_saveexec_b64 s[24:25], s[2:3]
	s_cbranch_execz .LBB0_2091
	s_waitcnt lgkmcnt(0)
	v_add_f32_e32 v80, v80, v81
	v_mul_f32_e32 v80, 0x4b800000, v80
	v_trunc_f32_e32 v80, v80
	v_mul_f32_e32 v81, 0x2f800000, v80
	v_floor_f32_e32 v81, v81
	v_fmac_f32_e32 v80, 0xcf800000, v81
	v_cvt_u32_f32_e32 v80, v80
	v_cvt_u32_f32_e32 v81, v81
	v_lshl_add_u64 v[82:83], v[96:97], 3, s[6:7]
	global_atomic_add_x2 v[82:83], v[80:81], off
.LBB0_2091:
	s_or_b64 exec, exec, s[24:25]
	v_or_b32_e32 v80, 48, v146
	s_waitcnt lgkmcnt(0)
	v_ashrrev_i32_e32 v81, 31, v80
	v_lshlrev_b64 v[82:83], 11, v[80:81]
	v_lshl_add_u64 v[90:91], v[82:83], 0, v[144:145]
	v_lshl_add_u64 v[92:93], v[90:91], 2, s[28:29]
	global_load_dwordx4 v[82:85], v[92:93], off
	global_load_dwordx4 v[86:89], v[92:93], off offset:16
	global_load_dwordx4 v[176:179], v[92:93], off offset:512
	global_load_dwordx4 v[180:183], v[92:93], off offset:528
	v_lshl_add_u64 v[90:91], v[90:91], 1, s[46:47]
	s_waitcnt vmcnt(3)
	v_pk_add_f32 v[78:79], v[78:79], v[84:85]
	v_pk_add_f32 v[76:77], v[76:77], v[82:83]
	s_waitcnt vmcnt(2)
	v_pk_add_f32 v[74:75], v[74:75], v[88:89]
	v_pk_add_f32 v[72:73], v[72:73], v[86:87]
	v_cvt_pk_bf16_f32 v82, v76, v77
	v_cvt_pk_bf16_f32 v83, v78, v79
	v_cvt_pk_bf16_f32 v84, v72, v73
	v_cvt_pk_bf16_f32 v85, v74, v75
	global_store_dwordx4 v[92:93], v[76:79], off
	global_store_dwordx4 v[92:93], v[72:75], off offset:16
	global_store_dwordx4 v[90:91], v[82:85], off
	s_nop 1
	v_mul_f32_e32 v77, v77, v77
	v_mul_f32_e32 v79, v79, v79
	v_mul_f32_e32 v73, v73, v73
	v_mul_f32_e32 v75, v75, v75
	v_fmac_f32_e32 v77, v76, v76
	v_fmac_f32_e32 v79, v78, v78
	v_fmac_f32_e32 v73, v72, v72
	v_fmac_f32_e32 v75, v74, v74
	v_add_f32_e32 v72, v77, v79
	v_add_f32_e32 v73, v73, v75
	v_add_f32_e32 v76, v72, v73
	s_waitcnt vmcnt(4)
	v_pk_add_f32 v[70:71], v[70:71], v[178:179]
	v_pk_add_f32 v[68:69], v[68:69], v[176:177]
	s_waitcnt vmcnt(3)
	v_pk_add_f32 v[74:75], v[66:67], v[182:183]
	v_pk_add_f32 v[72:73], v[64:65], v[180:181]
	v_mul_f32_e32 v64, v69, v69
	v_mul_f32_e32 v65, v71, v71
	v_mul_f32_e32 v66, v73, v73
	v_mul_f32_e32 v67, v75, v75
	v_fmac_f32_e32 v64, v68, v68
	v_fmac_f32_e32 v65, v70, v70
	v_fmac_f32_e32 v66, v72, v72
	v_fmac_f32_e32 v67, v74, v74
	v_add_f32_e32 v64, v64, v65
	v_add_f32_e32 v65, v66, v67
	v_add_f32_e32 v64, v64, v65
	v_add_f32_e32 v64, v76, v64
	ds_bpermute_b32 v65, v120, v64
	global_store_dwordx4 v[92:93], v[68:71], off offset:512
	global_store_dwordx4 v[92:93], v[72:75], off offset:528
	v_cvt_pk_bf16_f32 v66, v68, v69
	v_cvt_pk_bf16_f32 v67, v70, v71
	v_cvt_pk_bf16_f32 v68, v72, v73
	s_waitcnt lgkmcnt(0)
	v_add_f32_e32 v64, v64, v65
	ds_bpermute_b32 v65, v114, v64
	v_cvt_pk_bf16_f32 v69, v74, v75
	global_store_dwordx4 v[90:91], v[66:69], off offset:256
	s_and_saveexec_b64 s[24:25], s[2:3]
	s_cbranch_execz .LBB0_2093
	s_waitcnt lgkmcnt(0)
	v_add_f32_e32 v64, v64, v65
	v_mul_f32_e32 v64, 0x4b800000, v64
	v_trunc_f32_e32 v64, v64
	v_mul_f32_e32 v65, 0x2f800000, v64
	v_floor_f32_e32 v65, v65
	v_fmac_f32_e32 v64, 0xcf800000, v65
	v_cvt_u32_f32_e32 v64, v64
	v_cvt_u32_f32_e32 v65, v65
	v_lshl_add_u64 v[66:67], v[80:81], 3, s[6:7]
	global_atomic_add_x2 v[66:67], v[64:65], off
; __device__ __forceinline__ u32x4 pack8(const f32x4 a, const f32x4 b) { u32x4 w; w.x = cvt_pk_bf16(a[0], a[1]); w.y = cvt_pk_bf16(a[2], a[3]); w.z = cvt_pk_bf16(b[0], b[1]); w.w = cvt_pk_bf16(b[2], b[3]); return w; }
; __device__ __forceinline__ void ss_add(ssq_t* p, float sq) { __hip_atomic_fetch_add(p, (ssq_t)(sq * 16777216.0f), __ATOMIC_RELAXED, __HIP_MEMORY_SCOPE_AGENT); }
; __device__ __forceinline__ float dot4(const f32x4 a) { return (a[0] * a[0] + a[1] * a[1]) + (a[2] * a[2] + a[3] * a[3]); }
;     __device__ __forceinline__ void operator()(const f32x4 (&acc)[2][2][4][2], const Unit& u, int wr, int wc, int fr, int fq) const {
;     ...
;             for (int m = 0; m < 4; ++m) { const int row = row0 + ai * HALF + m * 16; const size_t off = (size_t)row * 2048 + col0; float sq = 0.f;
; #pragma unroll
;                 for (int bj = 0; bj < 2; ++bj) {
;                     const f32x4 x0 = __builtin_nontemporal_load((const f32x4*)(xin + off + bj * HALF)), x1 = __builtin_nontemporal_load((const f32x4*)(xin + off + bj * HALF + 4));
;                     const f32x4 v0 = x0 + acc[ai][bj][m][0] * alpha, v1 = x1 + acc[ai][bj][m][1] * alpha;
;                     __builtin_nontemporal_store(v0, (f32x4*)(xout + off + bj * HALF)); __builtin_nontemporal_store(v1, (f32x4*)(xout + off + bj * HALF + 4));
;                     if (WRITE_XB) *(u32x4*)(xb + off + bj * HALF) = pack8(v0, v1); sq += dot4(v0) + dot4(v1); }
;                 sq += __shfl_xor(sq, 16); sq += __shfl_xor(sq, 32);
;                 if (fq == 0) ss_add(ssout + row, sq); }
.LBB0_2093:
	s_or_b64 exec, exec, s[24:25]
	v_add_u32_e32 v64, 0x80, v146
	s_waitcnt lgkmcnt(0)
	v_ashrrev_i32_e32 v65, 31, v64
	v_lshlrev_b64 v[66:67], 11, v[64:65]
	v_lshl_add_u64 v[74:75], v[66:67], 0, v[144:145]
	v_lshl_add_u64 v[76:77], v[74:75], 2, s[28:29]
	global_load_dwordx4 v[66:69], v[76:77], off
	global_load_dwordx4 v[70:73], v[76:77], off offset:16
	global_load_dwordx4 v[176:179], v[76:77], off offset:512
	global_load_dwordx4 v[180:183], v[76:77], off offset:528
	v_lshl_add_u64 v[74:75], v[74:75], 1, s[46:47]
	s_waitcnt vmcnt(3)
	v_pk_add_f32 v[62:63], v[62:63], v[68:69]
	v_pk_add_f32 v[60:61], v[60:61], v[66:67]
	s_waitcnt vmcnt(2)
	v_pk_add_f32 v[58:59], v[58:59], v[72:73]
	v_pk_add_f32 v[56:57], v[56:57], v[70:71]
	v_cvt_pk_bf16_f32 v66, v60, v61
	v_cvt_pk_bf16_f32 v67, v62, v63
	v_cvt_pk_bf16_f32 v68, v56, v57
	v_cvt_pk_bf16_f32 v69, v58, v59
	global_store_dwordx4 v[76:77], v[60:63], off
	global_store_dwordx4 v[76:77], v[56:59], off offset:16
	global_store_dwordx4 v[74:75], v[66:69], off
	s_nop 1
	v_mul_f32_e32 v61, v61, v61
	v_mul_f32_e32 v63, v63, v63
	v_mul_f32_e32 v57, v57, v57
	v_mul_f32_e32 v59, v59, v59
	v_fmac_f32_e32 v61, v60, v60
	v_fmac_f32_e32 v63, v62, v62
	v_fmac_f32_e32 v57, v56, v56
	v_fmac_f32_e32 v59, v58, v58
	v_add_f32_e32 v56, v61, v63
	v_add_f32_e32 v57, v57, v59
	v_add_f32_e32 v60, v56, v57
	s_waitcnt vmcnt(4)
	v_pk_add_f32 v[54:55], v[54:55], v[178:179]
	v_pk_add_f32 v[52:53], v[52:53], v[176:177]
	s_waitcnt vmcnt(3)
	v_pk_add_f32 v[58:59], v[50:51], v[182:183]
	v_pk_add_f32 v[56:57], v[48:49], v[180:181]
	v_mul_f32_e32 v48, v53, v53
	v_mul_f32_e32 v49, v55, v55
	v_mul_f32_e32 v50, v57, v57
	v_mul_f32_e32 v51, v59, v59
	v_fmac_f32_e32 v48, v52, v52
	v_fmac_f32_e32 v49, v54, v54
	v_fmac_f32_e32 v50, v56, v56
	v_fmac_f32_e32 v51, v58, v58
	v_add_f32_e32 v48, v48, v49
	v_add_f32_e32 v49, v50, v51
	v_add_f32_e32 v48, v48, v49
	v_add_f32_e32 v48, v60, v48
	ds_bpermute_b32 v49, v120, v48
	global_store_dwordx4 v[76:77], v[52:55], off offset:512
	global_store_dwordx4 v[76:77], v[56:59], off offset:528
	v_cvt_pk_bf16_f32 v50, v52, v53
	v_cvt_pk_bf16_f32 v51, v54, v55
	v_cvt_pk_bf16_f32 v52, v56, v57
	s_waitcnt lgkmcnt(0)
	v_add_f32_e32 v48, v48, v49
	ds_bpermute_b32 v49, v114, v48
	v_cvt_pk_bf16_f32 v53, v58, v59
	global_store_dwordx4 v[74:75], v[50:53], off offset:256
	s_and_saveexec_b64 s[24:25], s[2:3]
	s_cbranch_execz .LBB0_2095
	s_waitcnt lgkmcnt(0)
	v_add_f32_e32 v48, v48, v49
	v_mul_f32_e32 v48, 0x4b800000, v48
	v_trunc_f32_e32 v48, v48
	v_mul_f32_e32 v49, 0x2f800000, v48
	v_floor_f32_e32 v49, v49
	v_fmac_f32_e32 v48, 0xcf800000, v49
	v_cvt_u32_f32_e32 v48, v48
	v_cvt_u32_f32_e32 v49, v49
	v_lshl_add_u64 v[50:51], v[64:65], 3, s[6:7]
	global_atomic_add_x2 v[50:51], v[48:49], off
.LBB0_2095:
	s_or_b64 exec, exec, s[24:25]
	v_add_u32_e32 v48, 0x90, v146
	s_waitcnt lgkmcnt(0)
	v_ashrrev_i32_e32 v49, 31, v48
	v_lshlrev_b64 v[50:51], 11, v[48:49]
	v_lshl_add_u64 v[58:59], v[50:51], 0, v[144:145]
	v_lshl_add_u64 v[60:61], v[58:59], 2, s[28:29]
	global_load_dwordx4 v[50:53], v[60:61], off
	global_load_dwordx4 v[54:57], v[60:61], off offset:16
	global_load_dwordx4 v[176:179], v[60:61], off offset:512
	global_load_dwordx4 v[180:183], v[60:61], off offset:528
	v_lshl_add_u64 v[58:59], v[58:59], 1, s[46:47]
	s_waitcnt vmcnt(3)
	v_pk_add_f32 v[46:47], v[46:47], v[52:53]
	v_pk_add_f32 v[44:45], v[44:45], v[50:51]
	s_waitcnt vmcnt(2)
	v_pk_add_f32 v[42:43], v[42:43], v[56:57]
	v_pk_add_f32 v[40:41], v[40:41], v[54:55]
	v_cvt_pk_bf16_f32 v50, v44, v45
	v_cvt_pk_bf16_f32 v51, v46, v47
	v_cvt_pk_bf16_f32 v52, v40, v41
	v_cvt_pk_bf16_f32 v53, v42, v43
	global_store_dwordx4 v[60:61], v[44:47], off
	global_store_dwordx4 v[60:61], v[40:43], off offset:16
	global_store_dwordx4 v[58:59], v[50:53], off
	s_nop 1
	v_mul_f32_e32 v45, v45, v45
	v_mul_f32_e32 v47, v47, v47
	v_mul_f32_e32 v41, v41, v41
	v_mul_f32_e32 v43, v43, v43
	v_fmac_f32_e32 v45, v44, v44
	v_fmac_f32_e32 v47, v46, v46
	v_fmac_f32_e32 v41, v40, v40
	v_fmac_f32_e32 v43, v42, v42
	v_add_f32_e32 v40, v45, v47
	v_add_f32_e32 v41, v41, v43
	v_add_f32_e32 v44, v40, v41
	s_waitcnt vmcnt(4)
	v_pk_add_f32 v[38:39], v[38:39], v[178:179]
	v_pk_add_f32 v[36:37], v[36:37], v[176:177]
	s_waitcnt vmcnt(3)
	v_pk_add_f32 v[42:43], v[34:35], v[182:183]
	v_pk_add_f32 v[40:41], v[32:33], v[180:181]
	v_mul_f32_e32 v32, v37, v37
	v_mul_f32_e32 v33, v39, v39
	v_mul_f32_e32 v34, v41, v41
	v_mul_f32_e32 v35, v43, v43
	v_fmac_f32_e32 v32, v36, v36
	v_fmac_f32_e32 v33, v38, v38
	v_fmac_f32_e32 v34, v40, v40
	v_fmac_f32_e32 v35, v42, v42
	v_add_f32_e32 v32, v32, v33
	v_add_f32_e32 v33, v34, v35
	v_add_f32_e32 v32, v32, v33
	v_add_f32_e32 v32, v44, v32
	ds_bpermute_b32 v33, v120, v32
	global_store_dwordx4 v[60:61], v[36:39], off offset:512
	global_store_dwordx4 v[60:61], v[40:43], off offset:528
	v_cvt_pk_bf16_f32 v34, v36, v37
	v_cvt_pk_bf16_f32 v35, v38, v39
	v_cvt_pk_bf16_f32 v36, v40, v41
	s_waitcnt lgkmcnt(0)
	v_add_f32_e32 v32, v32, v33
	ds_bpermute_b32 v33, v114, v32
	v_cvt_pk_bf16_f32 v37, v42, v43
	global_store_dwordx4 v[58:59], v[34:37], off offset:256
	s_and_saveexec_b64 s[24:25], s[2:3]
	s_cbranch_execz .LBB0_2097
	s_waitcnt lgkmcnt(0)
	v_add_f32_e32 v32, v32, v33
	v_mul_f32_e32 v32, 0x4b800000, v32
	v_trunc_f32_e32 v32, v32
	v_mul_f32_e32 v33, 0x2f800000, v32
	v_floor_f32_e32 v33, v33
	v_fmac_f32_e32 v32, 0xcf800000, v33
	v_cvt_u32_f32_e32 v32, v32
	v_cvt_u32_f32_e32 v33, v33
	v_lshl_add_u64 v[34:35], v[48:49], 3, s[6:7]
	global_atomic_add_x2 v[34:35], v[32:33], off
; __device__ __forceinline__ u32x4 pack8(const f32x4 a, const f32x4 b) { u32x4 w; w.x = cvt_pk_bf16(a[0], a[1]); w.y = cvt_pk_bf16(a[2], a[3]); w.z = cvt_pk_bf16(b[0], b[1]); w.w = cvt_pk_bf16(b[2], b[3]); return w; }
; __device__ __forceinline__ void ss_add(ssq_t* p, float sq) { __hip_atomic_fetch_add(p, (ssq_t)(sq * 16777216.0f), __ATOMIC_RELAXED, __HIP_MEMORY_SCOPE_AGENT); }
; __device__ __forceinline__ float dot4(const f32x4 a) { return (a[0] * a[0] + a[1] * a[1]) + (a[2] * a[2] + a[3] * a[3]); }
;     __device__ __forceinline__ void operator()(const f32x4 (&acc)[2][2][4][2], const Unit& u, int wr, int wc, int fr, int fq) const {
;     ...
;             for (int m = 0; m < 4; ++m) { const int row = row0 + ai * HALF + m * 16; const size_t off = (size_t)row * 2048 + col0; float sq = 0.f;
; #pragma unroll
;                 for (int bj = 0; bj < 2; ++bj) {
;                     const f32x4 x0 = __builtin_nontemporal_load((const f32x4*)(xin + off + bj * HALF)), x1 = __builtin_nontemporal_load((const f32x4*)(xin + off + bj * HALF + 4));
;                     const f32x4 v0 = x0 + acc[ai][bj][m][0] * alpha, v1 = x1 + acc[ai][bj][m][1] * alpha;
;                     __builtin_nontemporal_store(v0, (f32x4*)(xout + off + bj * HALF)); __builtin_nontemporal_store(v1, (f32x4*)(xout + off + bj * HALF + 4));
;                     if (WRITE_XB) *(u32x4*)(xb + off + bj * HALF) = pack8(v0, v1); sq += dot4(v0) + dot4(v1); }
;                 sq += __shfl_xor(sq, 16); sq += __shfl_xor(sq, 32);
;                 if (fq == 0) ss_add(ssout + row, sq); }
.LBB0_2097:
	s_or_b64 exec, exec, s[24:25]
	v_add_u32_e32 v32, 0xa0, v146
	s_waitcnt lgkmcnt(0)
	v_ashrrev_i32_e32 v33, 31, v32
	v_lshlrev_b64 v[34:35], 11, v[32:33]
	v_lshl_add_u64 v[42:43], v[34:35], 0, v[144:145]
	v_lshl_add_u64 v[44:45], v[42:43], 2, s[28:29]
	global_load_dwordx4 v[34:37], v[44:45], off
	global_load_dwordx4 v[38:41], v[44:45], off offset:16
	global_load_dwordx4 v[176:179], v[44:45], off offset:512
	global_load_dwordx4 v[180:183], v[44:45], off offset:528
	v_lshl_add_u64 v[42:43], v[42:43], 1, s[46:47]
	s_waitcnt vmcnt(3)
	v_pk_add_f32 v[30:31], v[30:31], v[36:37]
	v_pk_add_f32 v[28:29], v[28:29], v[34:35]
	s_waitcnt vmcnt(2)
	v_pk_add_f32 v[26:27], v[26:27], v[40:41]
	v_pk_add_f32 v[24:25], v[24:25], v[38:39]
	v_cvt_pk_bf16_f32 v34, v28, v29
	v_cvt_pk_bf16_f32 v35, v30, v31
	v_cvt_pk_bf16_f32 v36, v24, v25
	v_cvt_pk_bf16_f32 v37, v26, v27
	global_store_dwordx4 v[44:45], v[28:31], off
	global_store_dwordx4 v[44:45], v[24:27], off offset:16
	global_store_dwordx4 v[42:43], v[34:37], off
	s_nop 1
	v_mul_f32_e32 v29, v29, v29
	v_mul_f32_e32 v31, v31, v31
	v_mul_f32_e32 v25, v25, v25
	v_mul_f32_e32 v27, v27, v27
	v_fmac_f32_e32 v29, v28, v28
	v_fmac_f32_e32 v31, v30, v30
	v_fmac_f32_e32 v25, v24, v24
	v_fmac_f32_e32 v27, v26, v26
	v_add_f32_e32 v24, v29, v31
	v_add_f32_e32 v25, v25, v27
	v_add_f32_e32 v28, v24, v25
	s_waitcnt vmcnt(4)
	v_pk_add_f32 v[22:23], v[22:23], v[178:179]
	v_pk_add_f32 v[20:21], v[20:21], v[176:177]
	s_waitcnt vmcnt(3)
	v_pk_add_f32 v[26:27], v[18:19], v[182:183]
	v_pk_add_f32 v[24:25], v[16:17], v[180:181]
	v_mul_f32_e32 v16, v21, v21
	v_mul_f32_e32 v17, v23, v23
	v_mul_f32_e32 v18, v25, v25
	v_mul_f32_e32 v19, v27, v27
	v_fmac_f32_e32 v16, v20, v20
	v_fmac_f32_e32 v17, v22, v22
	v_fmac_f32_e32 v18, v24, v24
	v_fmac_f32_e32 v19, v26, v26
	v_add_f32_e32 v16, v16, v17
	v_add_f32_e32 v17, v18, v19
	v_add_f32_e32 v16, v16, v17
	v_add_f32_e32 v16, v28, v16
	ds_bpermute_b32 v17, v120, v16
	global_store_dwordx4 v[44:45], v[20:23], off offset:512
	global_store_dwordx4 v[44:45], v[24:27], off offset:528
	v_cvt_pk_bf16_f32 v18, v20, v21
	v_cvt_pk_bf16_f32 v19, v22, v23
	v_cvt_pk_bf16_f32 v20, v24, v25
	s_waitcnt lgkmcnt(0)
	v_add_f32_e32 v16, v16, v17
	ds_bpermute_b32 v17, v114, v16
	v_cvt_pk_bf16_f32 v21, v26, v27
	global_store_dwordx4 v[42:43], v[18:21], off offset:256
	s_and_saveexec_b64 s[24:25], s[2:3]
	s_cbranch_execz .LBB0_2099
	s_waitcnt lgkmcnt(0)
	v_add_f32_e32 v16, v16, v17
	v_mul_f32_e32 v16, 0x4b800000, v16
	v_trunc_f32_e32 v16, v16
	v_mul_f32_e32 v17, 0x2f800000, v16
	v_floor_f32_e32 v17, v17
	v_fmac_f32_e32 v16, 0xcf800000, v17
	v_cvt_u32_f32_e32 v16, v16
	v_cvt_u32_f32_e32 v17, v17
	v_lshl_add_u64 v[18:19], v[32:33], 3, s[6:7]
	global_atomic_add_x2 v[18:19], v[16:17], off
.LBB0_2099:
	s_or_b64 exec, exec, s[24:25]
	v_add_u32_e32 v16, 0xb0, v146
	s_waitcnt lgkmcnt(0)
	v_ashrrev_i32_e32 v17, 31, v16
	v_lshlrev_b64 v[18:19], 11, v[16:17]
	v_lshl_add_u64 v[26:27], v[18:19], 0, v[144:145]
	v_lshl_add_u64 v[28:29], v[26:27], 2, s[28:29]
	global_load_dwordx4 v[18:21], v[28:29], off
	global_load_dwordx4 v[22:25], v[28:29], off offset:16
	global_load_dwordx4 v[176:179], v[28:29], off offset:512
	global_load_dwordx4 v[180:183], v[28:29], off offset:528
	v_lshl_add_u64 v[26:27], v[26:27], 1, s[46:47]
	s_waitcnt vmcnt(3)
	v_pk_add_f32 v[14:15], v[14:15], v[20:21]
	v_pk_add_f32 v[12:13], v[12:13], v[18:19]
	s_waitcnt vmcnt(2)
	v_pk_add_f32 v[10:11], v[10:11], v[24:25]
	v_pk_add_f32 v[8:9], v[8:9], v[22:23]
	v_cvt_pk_bf16_f32 v18, v12, v13
	v_cvt_pk_bf16_f32 v19, v14, v15
	v_cvt_pk_bf16_f32 v20, v8, v9
	v_cvt_pk_bf16_f32 v21, v10, v11
	global_store_dwordx4 v[28:29], v[12:15], off
	global_store_dwordx4 v[28:29], v[8:11], off offset:16
	global_store_dwordx4 v[26:27], v[18:21], off
	s_nop 1
	v_mul_f32_e32 v13, v13, v13
	v_mul_f32_e32 v15, v15, v15
	v_mul_f32_e32 v9, v9, v9
	v_mul_f32_e32 v11, v11, v11
	v_fmac_f32_e32 v13, v12, v12
	v_fmac_f32_e32 v15, v14, v14
	v_fmac_f32_e32 v9, v8, v8
	v_fmac_f32_e32 v11, v10, v10
	v_add_f32_e32 v8, v13, v15
	v_add_f32_e32 v9, v9, v11
	v_add_f32_e32 v12, v8, v9
	s_waitcnt vmcnt(4)
	v_pk_add_f32 v[6:7], v[6:7], v[178:179]
	v_pk_add_f32 v[4:5], v[4:5], v[176:177]
	s_waitcnt vmcnt(3)
	v_pk_add_f32 v[10:11], v[2:3], v[182:183]
	v_pk_add_f32 v[8:9], v[0:1], v[180:181]
	v_mul_f32_e32 v0, v5, v5
	v_mul_f32_e32 v1, v7, v7
	v_mul_f32_e32 v2, v9, v9
	v_mul_f32_e32 v3, v11, v11
	v_fmac_f32_e32 v0, v4, v4
	v_fmac_f32_e32 v1, v6, v6
	v_fmac_f32_e32 v2, v8, v8
	v_fmac_f32_e32 v3, v10, v10
	v_add_f32_e32 v0, v0, v1
	v_add_f32_e32 v1, v2, v3
	v_add_f32_e32 v0, v0, v1
	v_add_f32_e32 v0, v12, v0
	ds_bpermute_b32 v1, v120, v0
	global_store_dwordx4 v[28:29], v[4:7], off offset:512
	global_store_dwordx4 v[28:29], v[8:11], off offset:528
	v_cvt_pk_bf16_f32 v2, v4, v5
	v_cvt_pk_bf16_f32 v3, v6, v7
	v_cvt_pk_bf16_f32 v4, v8, v9
	s_waitcnt lgkmcnt(0)
	v_add_f32_e32 v0, v0, v1
	ds_bpermute_b32 v1, v114, v0
	v_cvt_pk_bf16_f32 v5, v10, v11
	global_store_dwordx4 v[26:27], v[2:5], off offset:256
	s_and_saveexec_b64 s[24:25], s[2:3]
	s_cbranch_execz .LBB0_2101
	s_waitcnt lgkmcnt(0)
	v_add_f32_e32 v0, v0, v1
	v_mul_f32_e32 v0, 0x4b800000, v0
	v_trunc_f32_e32 v0, v0
	v_mul_f32_e32 v1, 0x2f800000, v0
	v_floor_f32_e32 v1, v1
	v_fmac_f32_e32 v0, 0xcf800000, v1
	v_cvt_u32_f32_e32 v0, v0
	v_cvt_u32_f32_e32 v1, v1
	v_lshl_add_u64 v[2:3], v[16:17], 3, s[6:7]
	global_atomic_add_x2 v[2:3], v[0:1], off

; __device__ __forceinline__ u32x4 pack8(const f32x4 a, const f32x4 b) { u32x4 w; w.x = cvt_pk_bf16(a[0], a[1]); w.y = cvt_pk_bf16(a[2], a[3]); w.z = cvt_pk_bf16(b[0], b[1]); w.w = cvt_pk_bf16(b[2], b[3]); return w; }
; __device__ __forceinline__ void ss_add(ssq_t* p, float sq) { __hip_atomic_fetch_add(p, (ssq_t)(sq * 16777216.0f), __ATOMIC_RELAXED, __HIP_MEMORY_SCOPE_AGENT); }
; __device__ __forceinline__ float dot4(const f32x4 a) { return (a[0] * a[0] + a[1] * a[1]) + (a[2] * a[2] + a[3] * a[3]); }
;     __device__ __forceinline__ void operator()(const f32x4 (&acc)[2][2][4][2], const Unit& u, int wr, int wc, int fr, int fq) const {
;     ...
;             for (int m = 0; m < 4; ++m) { const int row = row0 + ai * HALF + m * 16; const size_t off = (size_t)row * 2048 + col0; float sq = 0.f;
; #pragma unroll
;                 for (int bj = 0; bj < 2; ++bj) {
;                     const f32x4 x0 = __builtin_nontemporal_load((const f32x4*)(xin + off + bj * HALF)), x1 = __builtin_nontemporal_load((const f32x4*)(xin + off + bj * HALF + 4));
;                     const f32x4 v0 = x0 + acc[ai][bj][m][0] * alpha, v1 = x1 + acc[ai][bj][m][1] * alpha;
;                     __builtin_nontemporal_store(v0, (f32x4*)(xout + off + bj * HALF)); __builtin_nontemporal_store(v1, (f32x4*)(xout + off + bj * HALF + 4));
;                     if (WRITE_XB) *(u32x4*)(xb + off + bj * HALF) = pack8(v0, v1); sq += dot4(v0) + dot4(v1); }
;                 sq += __shfl_xor(sq, 16); sq += __shfl_xor(sq, 32);
;                 if (fq == 0) ss_add(ssout + row, sq); }
.LBB0_2257:
	v_lshl_add_u32 v146, s49, 8, v148
	v_ashrrev_i32_e32 v147, 31, v146
	v_lshl_add_u32 v144, s50, 8, v150
	v_lshlrev_b64 v[156:157], 13, v[146:147]
	v_ashrrev_i32_e32 v145, 31, v144
	v_lshl_add_u64 v[156:157], s[28:29], 0, v[156:157]
	v_lshl_add_u64 v[172:173], v[144:145], 2, v[156:157]
	global_load_dwordx4 v[156:159], v[172:173], off
	global_load_dwordx4 v[160:163], v[172:173], off offset:16
	global_load_dwordx4 v[164:167], v[172:173], off offset:512
	global_load_dwordx4 v[168:171], v[172:173], off offset:528
	v_and_b32_e32 v174, 64, v154
	v_xor_b32_e32 v155, 16, v154
	v_add_u32_e32 v174, 64, v174
	v_cmp_lt_i32_e32 vcc, v155, v174
	s_waitcnt vmcnt(0)
	v_pk_fma_f32 v[126:127], v[126:127], 0.5, v[158:159] op_sel_hi:[1,0,1]
	v_pk_fma_f32 v[124:125], v[124:125], 0.5, v[156:157] op_sel_hi:[1,0,1]
	v_pk_fma_f32 v[122:123], v[122:123], 0.5, v[162:163] op_sel_hi:[1,0,1]
	v_pk_fma_f32 v[120:121], v[120:121], 0.5, v[160:161] op_sel_hi:[1,0,1]
	v_pk_fma_f32 v[118:119], v[118:119], 0.5, v[166:167] op_sel_hi:[1,0,1]
	v_pk_fma_f32 v[116:117], v[116:117], 0.5, v[164:165] op_sel_hi:[1,0,1]
	v_pk_fma_f32 v[158:159], v[114:115], 0.5, v[170:171] op_sel_hi:[1,0,1]
	v_pk_fma_f32 v[156:157], v[112:113], 0.5, v[168:169] op_sel_hi:[1,0,1]
	v_mul_f32_e32 v112, v125, v125
	v_mul_f32_e32 v113, v127, v127
	v_mul_f32_e32 v114, v121, v121
	v_mul_f32_e32 v115, v123, v123
	v_mul_f32_e32 v160, v117, v117
	v_mul_f32_e32 v161, v119, v119
	v_mul_f32_e32 v162, v157, v157
	v_mul_f32_e32 v163, v159, v159
	v_fmac_f32_e32 v112, v124, v124
	v_fmac_f32_e32 v113, v126, v126
	v_fmac_f32_e32 v114, v120, v120
	v_fmac_f32_e32 v115, v122, v122
	v_fmac_f32_e32 v160, v116, v116
	v_fmac_f32_e32 v161, v118, v118
	v_fmac_f32_e32 v162, v156, v156
	v_fmac_f32_e32 v163, v158, v158
	v_add_f32_e32 v112, v112, v113
	v_add_f32_e32 v113, v114, v115
	v_add_f32_e32 v114, v160, v161
	v_add_f32_e32 v115, v162, v163
	v_cndmask_b32_e32 v155, v154, v155, vcc
	v_add_f32_e32 v112, v112, v113
	v_add_f32_e32 v113, v114, v115
	v_lshlrev_b32_e32 v155, 2, v155
	v_add_f32_e32 v112, v112, v113
	ds_bpermute_b32 v113, v155, v112
	v_xor_b32_e32 v114, 32, v154
	v_cmp_lt_i32_e32 vcc, v114, v174
	global_store_dwordx4 v[172:173], v[124:127], off
	global_store_dwordx4 v[172:173], v[120:123], off offset:16
	global_store_dwordx4 v[172:173], v[116:119], off offset:512
	global_store_dwordx4 v[172:173], v[156:159], off offset:528
	v_cndmask_b32_e32 v114, v154, v114, vcc
	v_lshlrev_b32_e32 v114, 2, v114
	s_waitcnt lgkmcnt(0)
	v_add_f32_e32 v112, v112, v113
	ds_bpermute_b32 v113, v114, v112
	s_and_saveexec_b64 s[20:21], s[2:3]
	s_cbranch_execz .LBB0_2259
	s_waitcnt lgkmcnt(0)
	v_add_f32_e32 v112, v112, v113
	v_mul_f32_e32 v112, 0x4b800000, v112
	v_trunc_f32_e32 v112, v112
	v_mul_f32_e32 v113, 0x2f800000, v112
	v_floor_f32_e32 v113, v113
	v_fmac_f32_e32 v112, 0xcf800000, v113
	v_cvt_u32_f32_e32 v112, v112
	v_cvt_u32_f32_e32 v113, v113
	v_lshl_add_u64 v[116:117], v[146:147], 3, s[12:13]
	global_atomic_add_x2 v[116:117], v[112:113], off
.LBB0_2259:
	s_or_b64 exec, exec, s[20:21]
	v_or_b32_e32 v112, 16, v146
	s_waitcnt lgkmcnt(0)
	v_ashrrev_i32_e32 v113, 31, v112
	v_lshlrev_b64 v[116:117], 13, v[112:113]
	v_lshl_add_u64 v[116:117], s[28:29], 0, v[116:117]
	v_lshl_add_u64 v[160:161], v[144:145], 2, v[116:117]
	global_load_dwordx4 v[116:119], v[160:161], off
	global_load_dwordx4 v[120:123], v[160:161], off offset:16
	global_load_dwordx4 v[124:127], v[160:161], off offset:512
	global_load_dwordx4 v[156:159], v[160:161], off offset:528
	s_waitcnt vmcnt(3)
	v_pk_fma_f32 v[110:111], v[110:111], 0.5, v[118:119] op_sel_hi:[1,0,1]
	v_pk_fma_f32 v[108:109], v[108:109], 0.5, v[116:117] op_sel_hi:[1,0,1]
	s_waitcnt vmcnt(2)
	v_pk_fma_f32 v[106:107], v[106:107], 0.5, v[122:123] op_sel_hi:[1,0,1]
	v_pk_fma_f32 v[104:105], v[104:105], 0.5, v[120:121] op_sel_hi:[1,0,1]
	s_waitcnt vmcnt(1)
	v_pk_fma_f32 v[102:103], v[102:103], 0.5, v[126:127] op_sel_hi:[1,0,1]
	v_pk_fma_f32 v[100:101], v[100:101], 0.5, v[124:125] op_sel_hi:[1,0,1]
	s_waitcnt vmcnt(0)
	v_pk_fma_f32 v[118:119], v[98:99], 0.5, v[158:159] op_sel_hi:[1,0,1]
	v_pk_fma_f32 v[116:117], v[96:97], 0.5, v[156:157] op_sel_hi:[1,0,1]
	v_mul_f32_e32 v96, v109, v109
	v_mul_f32_e32 v97, v111, v111
	v_mul_f32_e32 v98, v105, v105
	v_mul_f32_e32 v99, v107, v107
	v_mul_f32_e32 v115, v101, v101
	v_mul_f32_e32 v120, v103, v103
	v_mul_f32_e32 v121, v117, v117
	v_mul_f32_e32 v122, v119, v119
	v_fmac_f32_e32 v96, v108, v108
	v_fmac_f32_e32 v97, v110, v110
	v_fmac_f32_e32 v98, v104, v104
	v_fmac_f32_e32 v99, v106, v106
	v_fmac_f32_e32 v115, v100, v100
	v_fmac_f32_e32 v120, v102, v102
	v_fmac_f32_e32 v121, v116, v116
	v_fmac_f32_e32 v122, v118, v118
	v_add_f32_e32 v96, v96, v97
	v_add_f32_e32 v97, v98, v99
	v_add_f32_e32 v98, v115, v120
	v_add_f32_e32 v99, v121, v122
	v_add_f32_e32 v96, v96, v97
	v_add_f32_e32 v97, v98, v99
	v_add_f32_e32 v96, v96, v97
	ds_bpermute_b32 v97, v155, v96
	global_store_dwordx4 v[160:161], v[108:111], off
	global_store_dwordx4 v[160:161], v[104:107], off offset:16
	global_store_dwordx4 v[160:161], v[100:103], off offset:512
	global_store_dwordx4 v[160:161], v[116:119], off offset:528
	s_waitcnt lgkmcnt(0)
	v_add_f32_e32 v96, v96, v97
	ds_bpermute_b32 v97, v114, v96
	s_and_saveexec_b64 s[20:21], s[2:3]
	s_cbranch_execz .LBB0_2261
	s_waitcnt lgkmcnt(0)
	v_add_f32_e32 v96, v96, v97
	v_mul_f32_e32 v96, 0x4b800000, v96
	v_trunc_f32_e32 v96, v96
	v_mul_f32_e32 v97, 0x2f800000, v96
	v_floor_f32_e32 v97, v97
	v_fmac_f32_e32 v96, 0xcf800000, v97
	v_cvt_u32_f32_e32 v96, v96
	v_cvt_u32_f32_e32 v97, v97
	v_lshl_add_u64 v[98:99], v[112:113], 3, s[12:13]
	global_atomic_add_x2 v[98:99], v[96:97], off
; __device__ __forceinline__ u32x4 pack8(const f32x4 a, const f32x4 b) { u32x4 w; w.x = cvt_pk_bf16(a[0], a[1]); w.y = cvt_pk_bf16(a[2], a[3]); w.z = cvt_pk_bf16(b[0], b[1]); w.w = cvt_pk_bf16(b[2], b[3]); return w; }
; __device__ __forceinline__ void ss_add(ssq_t* p, float sq) { __hip_atomic_fetch_add(p, (ssq_t)(sq * 16777216.0f), __ATOMIC_RELAXED, __HIP_MEMORY_SCOPE_AGENT); }
; __device__ __forceinline__ float dot4(const f32x4 a) { return (a[0] * a[0] + a[1] * a[1]) + (a[2] * a[2] + a[3] * a[3]); }
;     __device__ __forceinline__ void operator()(const f32x4 (&acc)[2][2][4][2], const Unit& u, int wr, int wc, int fr, int fq) const {
;     ...
;             for (int m = 0; m < 4; ++m) { const int row = row0 + ai * HALF + m * 16; const size_t off = (size_t)row * 2048 + col0; float sq = 0.f;
; #pragma unroll
;                 for (int bj = 0; bj < 2; ++bj) {
;                     const f32x4 x0 = __builtin_nontemporal_load((const f32x4*)(xin + off + bj * HALF)), x1 = __builtin_nontemporal_load((const f32x4*)(xin + off + bj * HALF + 4));
;                     const f32x4 v0 = x0 + acc[ai][bj][m][0] * alpha, v1 = x1 + acc[ai][bj][m][1] * alpha;
;                     __builtin_nontemporal_store(v0, (f32x4*)(xout + off + bj * HALF)); __builtin_nontemporal_store(v1, (f32x4*)(xout + off + bj * HALF + 4));
;                     if (WRITE_XB) *(u32x4*)(xb + off + bj * HALF) = pack8(v0, v1); sq += dot4(v0) + dot4(v1); }
;                 sq += __shfl_xor(sq, 16); sq += __shfl_xor(sq, 32);
;                 if (fq == 0) ss_add(ssout + row, sq); }
.LBB0_2261:
	s_or_b64 exec, exec, s[20:21]
	v_or_b32_e32 v96, 32, v146
	s_waitcnt lgkmcnt(0)
	v_ashrrev_i32_e32 v97, 31, v96
	v_lshlrev_b64 v[98:99], 13, v[96:97]
	v_lshl_add_u64 v[98:99], s[28:29], 0, v[98:99]
	v_lshl_add_u64 v[116:117], v[144:145], 2, v[98:99]
	global_load_dwordx4 v[98:101], v[116:117], off
	global_load_dwordx4 v[102:105], v[116:117], off offset:16
	global_load_dwordx4 v[106:109], v[116:117], off offset:512
	global_load_dwordx4 v[110:113], v[116:117], off offset:528
	s_waitcnt vmcnt(3)
	v_pk_fma_f32 v[94:95], v[94:95], 0.5, v[100:101] op_sel_hi:[1,0,1]
	v_pk_fma_f32 v[92:93], v[92:93], 0.5, v[98:99] op_sel_hi:[1,0,1]
	s_waitcnt vmcnt(2)
	v_pk_fma_f32 v[90:91], v[90:91], 0.5, v[104:105] op_sel_hi:[1,0,1]
	v_pk_fma_f32 v[88:89], v[88:89], 0.5, v[102:103] op_sel_hi:[1,0,1]
	s_waitcnt vmcnt(1)
	v_pk_fma_f32 v[86:87], v[86:87], 0.5, v[108:109] op_sel_hi:[1,0,1]
	v_pk_fma_f32 v[84:85], v[84:85], 0.5, v[106:107] op_sel_hi:[1,0,1]
	s_waitcnt vmcnt(0)
	v_pk_fma_f32 v[100:101], v[82:83], 0.5, v[112:113] op_sel_hi:[1,0,1]
	v_pk_fma_f32 v[98:99], v[80:81], 0.5, v[110:111] op_sel_hi:[1,0,1]
	v_mul_f32_e32 v80, v93, v93
	v_mul_f32_e32 v81, v95, v95
	v_mul_f32_e32 v82, v89, v89
	v_mul_f32_e32 v83, v91, v91
	v_mul_f32_e32 v102, v85, v85
	v_mul_f32_e32 v103, v87, v87
	v_mul_f32_e32 v104, v99, v99
	v_mul_f32_e32 v105, v101, v101
	v_fmac_f32_e32 v80, v92, v92
	v_fmac_f32_e32 v81, v94, v94
	v_fmac_f32_e32 v82, v88, v88
	v_fmac_f32_e32 v83, v90, v90
	v_fmac_f32_e32 v102, v84, v84
	v_fmac_f32_e32 v103, v86, v86
	v_fmac_f32_e32 v104, v98, v98
	v_fmac_f32_e32 v105, v100, v100
	v_add_f32_e32 v80, v80, v81
	v_add_f32_e32 v81, v82, v83
	v_add_f32_e32 v82, v102, v103
	v_add_f32_e32 v83, v104, v105
	v_add_f32_e32 v80, v80, v81
	v_add_f32_e32 v81, v82, v83
	v_add_f32_e32 v80, v80, v81
	ds_bpermute_b32 v81, v155, v80
	global_store_dwordx4 v[116:117], v[92:95], off
	global_store_dwordx4 v[116:117], v[88:91], off offset:16
	global_store_dwordx4 v[116:117], v[84:87], off offset:512
	global_store_dwordx4 v[116:117], v[98:101], off offset:528
	s_waitcnt lgkmcnt(0)
	v_add_f32_e32 v80, v80, v81
	ds_bpermute_b32 v81, v114, v80
	s_and_saveexec_b64 s[20:21], s[2:3]
	s_cbranch_execz .LBB0_2263
	s_waitcnt lgkmcnt(0)
	v_add_f32_e32 v80, v80, v81
	v_mul_f32_e32 v80, 0x4b800000, v80
	v_trunc_f32_e32 v80, v80
	v_mul_f32_e32 v81, 0x2f800000, v80
	v_floor_f32_e32 v81, v81
	v_fmac_f32_e32 v80, 0xcf800000, v81
	v_cvt_u32_f32_e32 v80, v80
	v_cvt_u32_f32_e32 v81, v81
	v_lshl_add_u64 v[82:83], v[96:97], 3, s[12:13]
	global_atomic_add_x2 v[82:83], v[80:81], off
.LBB0_2263:
	s_or_b64 exec, exec, s[20:21]
	v_or_b32_e32 v80, 48, v146
	s_waitcnt lgkmcnt(0)
	v_ashrrev_i32_e32 v81, 31, v80
	v_lshlrev_b64 v[82:83], 13, v[80:81]
	v_lshl_add_u64 v[82:83], s[28:29], 0, v[82:83]
	v_lshl_add_u64 v[98:99], v[144:145], 2, v[82:83]
	global_load_dwordx4 v[82:85], v[98:99], off
	global_load_dwordx4 v[86:89], v[98:99], off offset:16
	global_load_dwordx4 v[90:93], v[98:99], off offset:512
	global_load_dwordx4 v[94:97], v[98:99], off offset:528
	s_waitcnt vmcnt(3)
	v_pk_fma_f32 v[78:79], v[78:79], 0.5, v[84:85] op_sel_hi:[1,0,1]
	v_pk_fma_f32 v[76:77], v[76:77], 0.5, v[82:83] op_sel_hi:[1,0,1]
	s_waitcnt vmcnt(2)
	v_pk_fma_f32 v[74:75], v[74:75], 0.5, v[88:89] op_sel_hi:[1,0,1]
	v_pk_fma_f32 v[72:73], v[72:73], 0.5, v[86:87] op_sel_hi:[1,0,1]
	s_waitcnt vmcnt(1)
	v_pk_fma_f32 v[70:71], v[70:71], 0.5, v[92:93] op_sel_hi:[1,0,1]
	v_pk_fma_f32 v[68:69], v[68:69], 0.5, v[90:91] op_sel_hi:[1,0,1]
	s_waitcnt vmcnt(0)
	v_pk_fma_f32 v[84:85], v[66:67], 0.5, v[96:97] op_sel_hi:[1,0,1]
	v_pk_fma_f32 v[82:83], v[64:65], 0.5, v[94:95] op_sel_hi:[1,0,1]
	v_mul_f32_e32 v64, v77, v77
	v_mul_f32_e32 v65, v79, v79
	v_mul_f32_e32 v66, v73, v73
	v_mul_f32_e32 v67, v75, v75
	v_mul_f32_e32 v86, v69, v69
	v_mul_f32_e32 v87, v71, v71
	v_mul_f32_e32 v88, v83, v83
	v_mul_f32_e32 v89, v85, v85
	v_fmac_f32_e32 v64, v76, v76
	v_fmac_f32_e32 v65, v78, v78
	v_fmac_f32_e32 v66, v72, v72
	v_fmac_f32_e32 v67, v74, v74
	v_fmac_f32_e32 v86, v68, v68
	v_fmac_f32_e32 v87, v70, v70
	v_fmac_f32_e32 v88, v82, v82
	v_fmac_f32_e32 v89, v84, v84
	v_add_f32_e32 v64, v64, v65
	v_add_f32_e32 v65, v66, v67
	v_add_f32_e32 v66, v86, v87
	v_add_f32_e32 v67, v88, v89
	v_add_f32_e32 v64, v64, v65
	v_add_f32_e32 v65, v66, v67
	v_add_f32_e32 v64, v64, v65
	ds_bpermute_b32 v65, v155, v64
	global_store_dwordx4 v[98:99], v[76:79], off
	global_store_dwordx4 v[98:99], v[72:75], off offset:16
	global_store_dwordx4 v[98:99], v[68:71], off offset:512
	global_store_dwordx4 v[98:99], v[82:85], off offset:528
	s_waitcnt lgkmcnt(0)
	v_add_f32_e32 v64, v64, v65
	ds_bpermute_b32 v65, v114, v64
	s_and_saveexec_b64 s[20:21], s[2:3]
	s_cbranch_execz .LBB0_2265
	s_waitcnt lgkmcnt(0)
	v_add_f32_e32 v64, v64, v65
	v_mul_f32_e32 v64, 0x4b800000, v64
	v_trunc_f32_e32 v64, v64
	v_mul_f32_e32 v65, 0x2f800000, v64
	v_floor_f32_e32 v65, v65
	v_fmac_f32_e32 v64, 0xcf800000, v65
	v_cvt_u32_f32_e32 v64, v64
	v_cvt_u32_f32_e32 v65, v65
	v_lshl_add_u64 v[66:67], v[80:81], 3, s[12:13]
	global_atomic_add_x2 v[66:67], v[64:65], off
; __device__ __forceinline__ u32x4 pack8(const f32x4 a, const f32x4 b) { u32x4 w; w.x = cvt_pk_bf16(a[0], a[1]); w.y = cvt_pk_bf16(a[2], a[3]); w.z = cvt_pk_bf16(b[0], b[1]); w.w = cvt_pk_bf16(b[2], b[3]); return w; }
; __device__ __forceinline__ void ss_add(ssq_t* p, float sq) { __hip_atomic_fetch_add(p, (ssq_t)(sq * 16777216.0f), __ATOMIC_RELAXED, __HIP_MEMORY_SCOPE_AGENT); }
; __device__ __forceinline__ float dot4(const f32x4 a) { return (a[0] * a[0] + a[1] * a[1]) + (a[2] * a[2] + a[3] * a[3]); }
;     __device__ __forceinline__ void operator()(const f32x4 (&acc)[2][2][4][2], const Unit& u, int wr, int wc, int fr, int fq) const {
;     ...
;             for (int m = 0; m < 4; ++m) { const int row = row0 + ai * HALF + m * 16; const size_t off = (size_t)row * 2048 + col0; float sq = 0.f;
; #pragma unroll
;                 for (int bj = 0; bj < 2; ++bj) {
;                     const f32x4 x0 = __builtin_nontemporal_load((const f32x4*)(xin + off + bj * HALF)), x1 = __builtin_nontemporal_load((const f32x4*)(xin + off + bj * HALF + 4));
;                     const f32x4 v0 = x0 + acc[ai][bj][m][0] * alpha, v1 = x1 + acc[ai][bj][m][1] * alpha;
;                     __builtin_nontemporal_store(v0, (f32x4*)(xout + off + bj * HALF)); __builtin_nontemporal_store(v1, (f32x4*)(xout + off + bj * HALF + 4));
;                     if (WRITE_XB) *(u32x4*)(xb + off + bj * HALF) = pack8(v0, v1); sq += dot4(v0) + dot4(v1); }
;                 sq += __shfl_xor(sq, 16); sq += __shfl_xor(sq, 32);
;                 if (fq == 0) ss_add(ssout + row, sq); }
.LBB0_2265:
	s_or_b64 exec, exec, s[20:21]
	v_add_u32_e32 v64, 0x80, v146
	s_waitcnt lgkmcnt(0)
	v_ashrrev_i32_e32 v65, 31, v64
	v_lshlrev_b64 v[66:67], 13, v[64:65]
	v_lshl_add_u64 v[66:67], s[28:29], 0, v[66:67]
	v_lshl_add_u64 v[82:83], v[144:145], 2, v[66:67]
	global_load_dwordx4 v[66:69], v[82:83], off
	global_load_dwordx4 v[70:73], v[82:83], off offset:16
	global_load_dwordx4 v[74:77], v[82:83], off offset:512
	global_load_dwordx4 v[78:81], v[82:83], off offset:528
	s_waitcnt vmcnt(3)
	v_pk_fma_f32 v[62:63], v[62:63], 0.5, v[68:69] op_sel_hi:[1,0,1]
	v_pk_fma_f32 v[60:61], v[60:61], 0.5, v[66:67] op_sel_hi:[1,0,1]
	s_waitcnt vmcnt(2)
	v_pk_fma_f32 v[58:59], v[58:59], 0.5, v[72:73] op_sel_hi:[1,0,1]
	v_pk_fma_f32 v[56:57], v[56:57], 0.5, v[70:71] op_sel_hi:[1,0,1]
	s_waitcnt vmcnt(1)
	v_pk_fma_f32 v[54:55], v[54:55], 0.5, v[76:77] op_sel_hi:[1,0,1]
	v_pk_fma_f32 v[52:53], v[52:53], 0.5, v[74:75] op_sel_hi:[1,0,1]
	s_waitcnt vmcnt(0)
	v_pk_fma_f32 v[68:69], v[50:51], 0.5, v[80:81] op_sel_hi:[1,0,1]
	v_pk_fma_f32 v[66:67], v[48:49], 0.5, v[78:79] op_sel_hi:[1,0,1]
	v_mul_f32_e32 v48, v61, v61
	v_mul_f32_e32 v49, v63, v63
	v_mul_f32_e32 v50, v57, v57
	v_mul_f32_e32 v51, v59, v59
	v_mul_f32_e32 v70, v53, v53
	v_mul_f32_e32 v71, v55, v55
	v_mul_f32_e32 v72, v67, v67
	v_mul_f32_e32 v73, v69, v69
	v_fmac_f32_e32 v48, v60, v60
	v_fmac_f32_e32 v49, v62, v62
	v_fmac_f32_e32 v50, v56, v56
	v_fmac_f32_e32 v51, v58, v58
	v_fmac_f32_e32 v70, v52, v52
	v_fmac_f32_e32 v71, v54, v54
	v_fmac_f32_e32 v72, v66, v66
	v_fmac_f32_e32 v73, v68, v68
	v_add_f32_e32 v48, v48, v49
	v_add_f32_e32 v49, v50, v51
	v_add_f32_e32 v50, v70, v71
	v_add_f32_e32 v51, v72, v73
	v_add_f32_e32 v48, v48, v49
	v_add_f32_e32 v49, v50, v51
	v_add_f32_e32 v48, v48, v49
	ds_bpermute_b32 v49, v155, v48
	global_store_dwordx4 v[82:83], v[60:63], off
	global_store_dwordx4 v[82:83], v[56:59], off offset:16
	global_store_dwordx4 v[82:83], v[52:55], off offset:512
	global_store_dwordx4 v[82:83], v[66:69], off offset:528
	s_waitcnt lgkmcnt(0)
	v_add_f32_e32 v48, v48, v49
	ds_bpermute_b32 v49, v114, v48
	s_and_saveexec_b64 s[20:21], s[2:3]
	s_cbranch_execz .LBB0_2267
	s_waitcnt lgkmcnt(0)
	v_add_f32_e32 v48, v48, v49
	v_mul_f32_e32 v48, 0x4b800000, v48
	v_trunc_f32_e32 v48, v48
	v_mul_f32_e32 v49, 0x2f800000, v48
	v_floor_f32_e32 v49, v49
	v_fmac_f32_e32 v48, 0xcf800000, v49
	v_cvt_u32_f32_e32 v48, v48
	v_cvt_u32_f32_e32 v49, v49
	v_lshl_add_u64 v[50:51], v[64:65], 3, s[12:13]
	global_atomic_add_x2 v[50:51], v[48:49], off
.LBB0_2267:
	s_or_b64 exec, exec, s[20:21]
	v_add_u32_e32 v48, 0x90, v146
	s_waitcnt lgkmcnt(0)
	v_ashrrev_i32_e32 v49, 31, v48
	v_lshlrev_b64 v[50:51], 13, v[48:49]
	v_lshl_add_u64 v[50:51], s[28:29], 0, v[50:51]
	v_lshl_add_u64 v[66:67], v[144:145], 2, v[50:51]
	global_load_dwordx4 v[50:53], v[66:67], off
	global_load_dwordx4 v[54:57], v[66:67], off offset:16
	global_load_dwordx4 v[58:61], v[66:67], off offset:512
	global_load_dwordx4 v[62:65], v[66:67], off offset:528
	s_waitcnt vmcnt(3)
	v_pk_fma_f32 v[46:47], v[46:47], 0.5, v[52:53] op_sel_hi:[1,0,1]
	v_pk_fma_f32 v[44:45], v[44:45], 0.5, v[50:51] op_sel_hi:[1,0,1]
	s_waitcnt vmcnt(2)
	v_pk_fma_f32 v[42:43], v[42:43], 0.5, v[56:57] op_sel_hi:[1,0,1]
	v_pk_fma_f32 v[40:41], v[40:41], 0.5, v[54:55] op_sel_hi:[1,0,1]
	s_waitcnt vmcnt(1)
	v_pk_fma_f32 v[38:39], v[38:39], 0.5, v[60:61] op_sel_hi:[1,0,1]
	v_pk_fma_f32 v[36:37], v[36:37], 0.5, v[58:59] op_sel_hi:[1,0,1]
	s_waitcnt vmcnt(0)
	v_pk_fma_f32 v[52:53], v[34:35], 0.5, v[64:65] op_sel_hi:[1,0,1]
	v_pk_fma_f32 v[50:51], v[32:33], 0.5, v[62:63] op_sel_hi:[1,0,1]
	v_mul_f32_e32 v32, v45, v45
	v_mul_f32_e32 v33, v47, v47
	v_mul_f32_e32 v34, v41, v41
	v_mul_f32_e32 v35, v43, v43
	v_mul_f32_e32 v54, v37, v37
	v_mul_f32_e32 v55, v39, v39
	v_mul_f32_e32 v56, v51, v51
	v_mul_f32_e32 v57, v53, v53
	v_fmac_f32_e32 v32, v44, v44
	v_fmac_f32_e32 v33, v46, v46
	v_fmac_f32_e32 v34, v40, v40
	v_fmac_f32_e32 v35, v42, v42
	v_fmac_f32_e32 v54, v36, v36
	v_fmac_f32_e32 v55, v38, v38
	v_fmac_f32_e32 v56, v50, v50
	v_fmac_f32_e32 v57, v52, v52
	v_add_f32_e32 v32, v32, v33
	v_add_f32_e32 v33, v34, v35
	v_add_f32_e32 v34, v54, v55
	v_add_f32_e32 v35, v56, v57
	v_add_f32_e32 v32, v32, v33
	v_add_f32_e32 v33, v34, v35
	v_add_f32_e32 v32, v32, v33
	ds_bpermute_b32 v33, v155, v32
	global_store_dwordx4 v[66:67], v[44:47], off
	global_store_dwordx4 v[66:67], v[40:43], off offset:16
	global_store_dwordx4 v[66:67], v[36:39], off offset:512
	global_store_dwordx4 v[66:67], v[50:53], off offset:528
	s_waitcnt lgkmcnt(0)
	v_add_f32_e32 v32, v32, v33
	ds_bpermute_b32 v33, v114, v32
	s_and_saveexec_b64 s[20:21], s[2:3]
	s_cbranch_execz .LBB0_2269
	s_waitcnt lgkmcnt(0)
	v_add_f32_e32 v32, v32, v33
	v_mul_f32_e32 v32, 0x4b800000, v32
	v_trunc_f32_e32 v32, v32
	v_mul_f32_e32 v33, 0x2f800000, v32
	v_floor_f32_e32 v33, v33
	v_fmac_f32_e32 v32, 0xcf800000, v33
	v_cvt_u32_f32_e32 v32, v32
	v_cvt_u32_f32_e32 v33, v33
	v_lshl_add_u64 v[34:35], v[48:49], 3, s[12:13]
	global_atomic_add_x2 v[34:35], v[32:33], off
; __device__ __forceinline__ u32x4 pack8(const f32x4 a, const f32x4 b) { u32x4 w; w.x = cvt_pk_bf16(a[0], a[1]); w.y = cvt_pk_bf16(a[2], a[3]); w.z = cvt_pk_bf16(b[0], b[1]); w.w = cvt_pk_bf16(b[2], b[3]); return w; }
; __device__ __forceinline__ void ss_add(ssq_t* p, float sq) { __hip_atomic_fetch_add(p, (ssq_t)(sq * 16777216.0f), __ATOMIC_RELAXED, __HIP_MEMORY_SCOPE_AGENT); }
; __device__ __forceinline__ float dot4(const f32x4 a) { return (a[0] * a[0] + a[1] * a[1]) + (a[2] * a[2] + a[3] * a[3]); }
;     __device__ __forceinline__ void operator()(const f32x4 (&acc)[2][2][4][2], const Unit& u, int wr, int wc, int fr, int fq) const {
;     ...
;             for (int m = 0; m < 4; ++m) { const int row = row0 + ai * HALF + m * 16; const size_t off = (size_t)row * 2048 + col0; float sq = 0.f;
; #pragma unroll
;                 for (int bj = 0; bj < 2; ++bj) {
;                     const f32x4 x0 = __builtin_nontemporal_load((const f32x4*)(xin + off + bj * HALF)), x1 = __builtin_nontemporal_load((const f32x4*)(xin + off + bj * HALF + 4));
;                     const f32x4 v0 = x0 + acc[ai][bj][m][0] * alpha, v1 = x1 + acc[ai][bj][m][1] * alpha;
;                     __builtin_nontemporal_store(v0, (f32x4*)(xout + off + bj * HALF)); __builtin_nontemporal_store(v1, (f32x4*)(xout + off + bj * HALF + 4));
;                     if (WRITE_XB) *(u32x4*)(xb + off + bj * HALF) = pack8(v0, v1); sq += dot4(v0) + dot4(v1); }
;                 sq += __shfl_xor(sq, 16); sq += __shfl_xor(sq, 32);
;                 if (fq == 0) ss_add(ssout + row, sq); }
.LBB0_2269:
	s_or_b64 exec, exec, s[20:21]
	v_add_u32_e32 v32, 0xa0, v146
	s_waitcnt lgkmcnt(0)
	v_ashrrev_i32_e32 v33, 31, v32
	v_lshlrev_b64 v[34:35], 13, v[32:33]
	v_lshl_add_u64 v[34:35], s[28:29], 0, v[34:35]
	v_lshl_add_u64 v[50:51], v[144:145], 2, v[34:35]
	global_load_dwordx4 v[34:37], v[50:51], off
	global_load_dwordx4 v[38:41], v[50:51], off offset:16
	global_load_dwordx4 v[42:45], v[50:51], off offset:512
	global_load_dwordx4 v[46:49], v[50:51], off offset:528
	s_waitcnt vmcnt(3)
	v_pk_fma_f32 v[30:31], v[30:31], 0.5, v[36:37] op_sel_hi:[1,0,1]
	v_pk_fma_f32 v[28:29], v[28:29], 0.5, v[34:35] op_sel_hi:[1,0,1]
	s_waitcnt vmcnt(2)
	v_pk_fma_f32 v[26:27], v[26:27], 0.5, v[40:41] op_sel_hi:[1,0,1]
	v_pk_fma_f32 v[24:25], v[24:25], 0.5, v[38:39] op_sel_hi:[1,0,1]
	s_waitcnt vmcnt(1)
	v_pk_fma_f32 v[22:23], v[22:23], 0.5, v[44:45] op_sel_hi:[1,0,1]
	v_pk_fma_f32 v[20:21], v[20:21], 0.5, v[42:43] op_sel_hi:[1,0,1]
	s_waitcnt vmcnt(0)
	v_pk_fma_f32 v[36:37], v[18:19], 0.5, v[48:49] op_sel_hi:[1,0,1]
	v_pk_fma_f32 v[34:35], v[16:17], 0.5, v[46:47] op_sel_hi:[1,0,1]
	v_mul_f32_e32 v16, v29, v29
	v_mul_f32_e32 v17, v31, v31
	v_mul_f32_e32 v18, v25, v25
	v_mul_f32_e32 v19, v27, v27
	v_mul_f32_e32 v38, v21, v21
	v_mul_f32_e32 v39, v23, v23
	v_mul_f32_e32 v40, v35, v35
	v_mul_f32_e32 v41, v37, v37
	v_fmac_f32_e32 v16, v28, v28
	v_fmac_f32_e32 v17, v30, v30
	v_fmac_f32_e32 v18, v24, v24
	v_fmac_f32_e32 v19, v26, v26
	v_fmac_f32_e32 v38, v20, v20
	v_fmac_f32_e32 v39, v22, v22
	v_fmac_f32_e32 v40, v34, v34
	v_fmac_f32_e32 v41, v36, v36
	v_add_f32_e32 v16, v16, v17
	v_add_f32_e32 v17, v18, v19
	v_add_f32_e32 v18, v38, v39
	v_add_f32_e32 v19, v40, v41
	v_add_f32_e32 v16, v16, v17
	v_add_f32_e32 v17, v18, v19
	v_add_f32_e32 v16, v16, v17
	ds_bpermute_b32 v17, v155, v16
	global_store_dwordx4 v[50:51], v[28:31], off
	global_store_dwordx4 v[50:51], v[24:27], off offset:16
	global_store_dwordx4 v[50:51], v[20:23], off offset:512
	global_store_dwordx4 v[50:51], v[34:37], off offset:528
	s_waitcnt lgkmcnt(0)
	v_add_f32_e32 v16, v16, v17
	ds_bpermute_b32 v17, v114, v16
	s_and_saveexec_b64 s[20:21], s[2:3]
	s_cbranch_execz .LBB0_2271
	s_waitcnt lgkmcnt(0)
	v_add_f32_e32 v16, v16, v17
	v_mul_f32_e32 v16, 0x4b800000, v16
	v_trunc_f32_e32 v16, v16
	v_mul_f32_e32 v17, 0x2f800000, v16
	v_floor_f32_e32 v17, v17
	v_fmac_f32_e32 v16, 0xcf800000, v17
	v_cvt_u32_f32_e32 v16, v16
	v_cvt_u32_f32_e32 v17, v17
	v_lshl_add_u64 v[18:19], v[32:33], 3, s[12:13]
	global_atomic_add_x2 v[18:19], v[16:17], off
.LBB0_2271:
	s_or_b64 exec, exec, s[20:21]
	v_add_u32_e32 v16, 0xb0, v146
	s_waitcnt lgkmcnt(0)
	v_ashrrev_i32_e32 v17, 31, v16
	v_lshlrev_b64 v[18:19], 13, v[16:17]
	v_lshl_add_u64 v[18:19], s[28:29], 0, v[18:19]
	v_lshl_add_u64 v[34:35], v[144:145], 2, v[18:19]
	global_load_dwordx4 v[18:21], v[34:35], off
	global_load_dwordx4 v[22:25], v[34:35], off offset:16
	global_load_dwordx4 v[26:29], v[34:35], off offset:512
	global_load_dwordx4 v[30:33], v[34:35], off offset:528
	s_waitcnt vmcnt(3)
	v_pk_fma_f32 v[14:15], v[14:15], 0.5, v[20:21] op_sel_hi:[1,0,1]
	v_pk_fma_f32 v[12:13], v[12:13], 0.5, v[18:19] op_sel_hi:[1,0,1]
	s_waitcnt vmcnt(2)
	v_pk_fma_f32 v[10:11], v[10:11], 0.5, v[24:25] op_sel_hi:[1,0,1]
	v_pk_fma_f32 v[8:9], v[8:9], 0.5, v[22:23] op_sel_hi:[1,0,1]
	s_waitcnt vmcnt(1)
	v_pk_fma_f32 v[6:7], v[6:7], 0.5, v[28:29] op_sel_hi:[1,0,1]
	v_pk_fma_f32 v[4:5], v[4:5], 0.5, v[26:27] op_sel_hi:[1,0,1]
	s_waitcnt vmcnt(0)
	v_pk_fma_f32 v[20:21], v[2:3], 0.5, v[32:33] op_sel_hi:[1,0,1]
	v_pk_fma_f32 v[18:19], v[0:1], 0.5, v[30:31] op_sel_hi:[1,0,1]
	v_mul_f32_e32 v0, v13, v13
	v_mul_f32_e32 v1, v15, v15
	v_mul_f32_e32 v2, v9, v9
	v_mul_f32_e32 v3, v11, v11
	v_mul_f32_e32 v22, v5, v5
	v_mul_f32_e32 v23, v7, v7
	v_mul_f32_e32 v24, v19, v19
	v_mul_f32_e32 v25, v21, v21
	v_fmac_f32_e32 v0, v12, v12
	v_fmac_f32_e32 v1, v14, v14
	v_fmac_f32_e32 v2, v8, v8
	v_fmac_f32_e32 v3, v10, v10
	v_fmac_f32_e32 v22, v4, v4
	v_fmac_f32_e32 v23, v6, v6
	v_fmac_f32_e32 v24, v18, v18
	v_fmac_f32_e32 v25, v20, v20
	v_add_f32_e32 v0, v0, v1
	v_add_f32_e32 v1, v2, v3
	v_add_f32_e32 v2, v22, v23
	v_add_f32_e32 v3, v24, v25
	v_add_f32_e32 v0, v0, v1
	v_add_f32_e32 v1, v2, v3
	v_add_f32_e32 v0, v0, v1
	ds_bpermute_b32 v1, v155, v0
	global_store_dwordx4 v[34:35], v[12:15], off
	global_store_dwordx4 v[34:35], v[8:11], off offset:16
	global_store_dwordx4 v[34:35], v[4:7], off offset:512
	global_store_dwordx4 v[34:35], v[18:21], off offset:528
	s_waitcnt lgkmcnt(0)
	v_add_f32_e32 v0, v0, v1
	ds_bpermute_b32 v1, v114, v0
	s_and_saveexec_b64 s[20:21], s[2:3]
	s_cbranch_execz .LBB0_2273
	s_waitcnt lgkmcnt(0)
	v_add_f32_e32 v0, v0, v1
	v_mul_f32_e32 v0, 0x4b800000, v0
	v_trunc_f32_e32 v0, v0
	v_mul_f32_e32 v1, 0x2f800000, v0
	v_floor_f32_e32 v1, v1
	v_fmac_f32_e32 v0, 0xcf800000, v1
	v_cvt_u32_f32_e32 v0, v0
	v_cvt_u32_f32_e32 v1, v1
	v_lshl_add_u64 v[2:3], v[16:17], 3, s[12:13]
	global_atomic_add_x2 v[2:3], v[0:1], off
